# fp8 attention steps: QK^T as two v_mfma_16x16x128_f8f6f4 (fp8 e4m3, K = head dim 128) instead of eight 16x16x32 fp8 MFMAs, with the 12 wait states their results need
# baseline (speedup 1.0000x reference)
; template <bool SLC, bool NOMASK> ...
;     ...
;     load_frag8(nxt, KF, VF, SLC ? (dnext & 0xfffff) : dnext, lane);
;     f32x4 sa[2] = {(f32x4){0.f, 0.f, 0.f, 0.f}, (f32x4){0.f, 0.f, 0.f, 0.f}};
; #pragma unroll
;     for (int T = 0; T < 2; ++T)
; #pragma unroll
;         for (int s2 = 0; s2 < 4; ++s2) sa[T] = __builtin_amdgcn_mfma_f32_16x16x32_fp8_fp8(cur.k[T][s2], qf[s2], sa[T], 0, 0, 0);
;     float sc[8]; bool vd[8]; float mx = -1e30f;
;     const bool act = lo == 0 || !SLC;
;     if (NOMASK) {
; #pragma unroll
;         for (int j = 0; j < 8; ++j) { sc[j] = sa[j >> 2][j & 3]; vd[j] = act; }
;         mx = fmaxf(fmaxf(fmaxf(sc[0], sc[1]), fmaxf(sc[2], sc[3])), fmaxf(fmaxf(sc[4], sc[5]), fmaxf(sc[6], sc[7])));
;         mx = act ? mx : -1e30f;
;     } else {
; #pragma unroll
;         for (int T = 0; T < 2; ++T)
; #pragma unroll
;             for (int r = 0; r < 4; ++r) { const int p = pos0 + 16 * T + 4 * kq + r; const bool v = (p >= lo) & (p <= hi); const float x = sa[T][r];
;                 sc[4 * T + r] = x; vd[4 * T + r] = v; mx = v ? fmaxf(mx, x) : mx; }
;     }
;     if (__builtin_amdgcn_ballot_w64(mx > st.m + 4.f) != 0ull) {
;         mx = fmaxf(mx, __shfl_xor(mx, 16)); mx = fmaxf(mx, __shfl_xor(mx, 32));
;         const float mn = fmaxf(st.m, mx), alpha = __builtin_amdgcn_exp2f(st.m - mn); st.m = mn; st.l *= alpha;
; #pragma unroll
;         for (int j = 0; j < 8; ++j) st.o[j] = st.o[j] * alpha;
;     }
.LBB0_704:
	v_lshl_add_u64 v[244:245], v[198:199], 0, v[98:99]
	global_load_dwordx4 v[180:183], v[244:245], off
	global_load_dwordx4 v[184:187], v[244:245], off offset:1024
	global_load_dwordx4 v[188:191], v[244:245], off offset:2048
	global_load_dwordx4 v[192:195], v[244:245], off offset:3072
	v_lshl_add_u64 v[246:247], v[196:197], 0, v[98:99]
	global_load_dwordx4 v[164:167], v[246:247], off
	global_load_dwordx4 v[168:171], v[246:247], off offset:1024
	global_load_dwordx4 v[172:175], v[246:247], off offset:2048
	global_load_dwordx4 v[176:179], v[246:247], off offset:3072
	s_waitcnt vmcnt(20)
	v_mfma_f32_16x16x128_f8f6f4 v[2:5], v[132:139], v[74:81], 0
	v_mfma_f32_16x16x128_f8f6f4 v[6:9], v[140:147], v[74:81], 0
	v_mov_b32_e32 v207, v210
	v_mov_b32_e32 v208, v209
	s_nop 8
	v_max_f32_e32 v0, v3, v3
	v_max_f32_e32 v10, v2, v2
	v_max_f32_e32 v0, v10, v0
	v_max_f32_e32 v10, v5, v5
	v_max_f32_e32 v11, v4, v4
	v_max_f32_e32 v10, v11, v10
	v_max_f32_e32 v11, v9, v9
	v_max_f32_e32 v12, v8, v8
	v_max_f32_e32 v11, v12, v11
	v_max3_f32 v11, v6, v7, v11
	v_max3_f32 v0, v0, v10, v11
	v_cmp_gt_f32_e32 vcc, v0, v211
	s_cbranch_vccz .LBB0_706
	v_and_b32_e32 v11, 64, v204
	v_xor_b32_e32 v10, 16, v204
	v_add_u32_e32 v11, 64, v11
	v_cmp_lt_i32_e32 vcc, v10, v11
	v_xor_b32_e32 v12, 32, v204
	s_nop 0
	v_cndmask_b32_e32 v10, v204, v10, vcc
	v_lshlrev_b32_e32 v10, 2, v10
	ds_bpermute_b32 v10, v10, v0
	v_max_f32_e32 v0, v0, v0
	v_cmp_lt_i32_e32 vcc, v12, v11
	s_waitcnt lgkmcnt(0)
	v_max_f32_e32 v10, v10, v10
	v_max_f32_e32 v0, v0, v10
	v_cndmask_b32_e32 v10, v204, v12, vcc
	v_lshlrev_b32_e32 v10, 2, v10
	ds_bpermute_b32 v10, v10, v0
	s_waitcnt lgkmcnt(0)
	v_max3_f32 v207, v210, v0, v10
	v_sub_f32_e32 v0, v210, v207
	v_exp_f32_e32 v0, v0
	s_nop 0
	v_mul_f32_e32 v208, v209, v0
	v_pk_mul_f32 v[36:37], v[36:37], v[0:1] op_sel_hi:[1,0]
	v_pk_mul_f32 v[34:35], v[34:35], v[0:1] op_sel_hi:[1,0]
	v_pk_mul_f32 v[40:41], v[40:41], v[0:1] op_sel_hi:[1,0]
	v_pk_mul_f32 v[38:39], v[38:39], v[0:1] op_sel_hi:[1,0]
	v_pk_mul_f32 v[44:45], v[44:45], v[0:1] op_sel_hi:[1,0]
	v_pk_mul_f32 v[42:43], v[42:43], v[0:1] op_sel_hi:[1,0]
	v_pk_mul_f32 v[56:57], v[56:57], v[0:1] op_sel_hi:[1,0]
	v_pk_mul_f32 v[54:55], v[54:55], v[0:1] op_sel_hi:[1,0]
	v_pk_mul_f32 v[64:65], v[64:65], v[0:1] op_sel_hi:[1,0]
	v_pk_mul_f32 v[62:63], v[62:63], v[0:1] op_sel_hi:[1,0]
	v_pk_mul_f32 v[60:61], v[60:61], v[0:1] op_sel_hi:[1,0]
	v_pk_mul_f32 v[58:59], v[58:59], v[0:1] op_sel_hi:[1,0]
	v_pk_mul_f32 v[52:53], v[52:53], v[0:1] op_sel_hi:[1,0]
	v_pk_mul_f32 v[50:51], v[50:51], v[0:1] op_sel_hi:[1,0]
	v_pk_mul_f32 v[48:49], v[48:49], v[0:1] op_sel_hi:[1,0]
	v_pk_mul_f32 v[46:47], v[46:47], v[0:1] op_sel_hi:[1,0]

; template <bool SLC, bool NOMASK> ...
;     ...
;     load_frag8(nxt, KF, VF, SLC ? (dnext & 0xfffff) : dnext, lane);
;     f32x4 sa[2] = {(f32x4){0.f, 0.f, 0.f, 0.f}, (f32x4){0.f, 0.f, 0.f, 0.f}};
; #pragma unroll
;     for (int T = 0; T < 2; ++T)
; #pragma unroll
;         for (int s2 = 0; s2 < 4; ++s2) sa[T] = __builtin_amdgcn_mfma_f32_16x16x32_fp8_fp8(cur.k[T][s2], qf[s2], sa[T], 0, 0, 0);
;     float sc[8]; bool vd[8]; float mx = -1e30f;
;     const bool act = lo == 0 || !SLC;
;     if (NOMASK) {
; #pragma unroll
;         for (int j = 0; j < 8; ++j) { sc[j] = sa[j >> 2][j & 3]; vd[j] = act; }
;         mx = fmaxf(fmaxf(fmaxf(sc[0], sc[1]), fmaxf(sc[2], sc[3])), fmaxf(fmaxf(sc[4], sc[5]), fmaxf(sc[6], sc[7])));
;         mx = act ? mx : -1e30f;
;     } else {
; #pragma unroll
;         for (int T = 0; T < 2; ++T)
; #pragma unroll
;             for (int r = 0; r < 4; ++r) { const int p = pos0 + 16 * T + 4 * kq + r; const bool v = (p >= lo) & (p <= hi); const float x = sa[T][r];
;                 sc[4 * T + r] = x; vd[4 * T + r] = v; mx = v ? fmaxf(mx, x) : mx; }
;     }
.LBB0_707:
	v_lshl_add_u64 v[244:245], v[198:199], 0, v[98:99]
	global_load_dwordx4 v[180:183], v[244:245], off
	global_load_dwordx4 v[184:187], v[244:245], off offset:1024
	global_load_dwordx4 v[188:191], v[244:245], off offset:2048
	global_load_dwordx4 v[192:195], v[244:245], off offset:3072
	v_lshl_add_u64 v[246:247], v[196:197], 0, v[98:99]
	global_load_dwordx4 v[164:167], v[246:247], off
	global_load_dwordx4 v[168:171], v[246:247], off offset:1024
	global_load_dwordx4 v[172:175], v[246:247], off offset:2048
	global_load_dwordx4 v[176:179], v[246:247], off offset:3072
	s_waitcnt vmcnt(20)
	v_mfma_f32_16x16x128_f8f6f4 v[2:5], v[132:139], v[74:81], 0
	v_or_b32_e32 v0, s75, v203
	v_cmp_ge_i32_e32 vcc, v0, v105
	v_cmp_le_i32_e64 s[4:5], v0, v206
	v_mfma_f32_16x16x128_f8f6f4 v[6:9], v[140:147], v[74:81], 0
	s_and_b64 s[10:11], vcc, s[4:5]
	v_or_b32_e32 v11, 1, v0
	v_cmp_ge_i32_e32 vcc, v11, v105
	v_cmp_lt_i32_e64 s[4:5], v0, v206
	s_and_b64 s[6:7], s[4:5], vcc
	s_nop 5
	v_max_f32_e32 v10, v2, v2
	v_max_f32_e32 v10, 0xf149f2ca, v10
	v_cndmask_b32_e64 v10, v205, v10, s[10:11]
	v_max_f32_e32 v11, v3, v3
	v_max_f32_e32 v11, v10, v11
	v_cndmask_b32_e64 v10, v10, v11, s[6:7]
	v_or_b32_e32 v11, 2, v0
	v_cmp_ge_i32_e32 vcc, v11, v105
	v_cmp_le_i32_e64 s[4:5], v11, v206
	v_max_f32_e32 v11, v4, v4
	v_max_f32_e32 v11, v10, v11
	s_and_b64 s[8:9], vcc, s[4:5]
	v_cndmask_b32_e64 v10, v10, v11, s[8:9]
	v_or_b32_e32 v11, 3, v0
	v_cmp_ge_i32_e32 vcc, v11, v105
	v_cmp_le_i32_e64 s[4:5], v11, v206
	v_max_f32_e32 v11, v5, v5
	v_max_f32_e32 v11, v10, v11
	s_and_b64 s[4:5], vcc, s[4:5]
	v_cndmask_b32_e64 v10, v10, v11, s[4:5]
	v_or_b32_e32 v11, 16, v0
	v_cmp_ge_i32_e32 vcc, v11, v105
	v_cmp_le_i32_e64 s[12:13], v11, v206
	v_max_f32_e32 v11, v6, v6
	v_max_f32_e32 v11, v10, v11
	s_and_b64 s[18:19], vcc, s[12:13]
	v_cndmask_b32_e64 v10, v10, v11, s[18:19]
	v_or_b32_e32 v11, 17, v0
	v_cmp_ge_i32_e32 vcc, v11, v105
	v_cmp_le_i32_e64 s[12:13], v11, v206
	v_max_f32_e32 v11, v10, v10
	v_max_f32_e32 v12, v7, v7
	v_max_f32_e32 v11, v11, v12
	s_and_b64 s[14:15], vcc, s[12:13]
	v_cndmask_b32_e64 v10, v10, v11, s[14:15]
	v_or_b32_e32 v11, 18, v0
	v_cmp_ge_i32_e32 vcc, v11, v105
	v_cmp_le_i32_e64 s[12:13], v11, v206
	v_max_f32_e32 v11, v10, v10
	v_max_f32_e32 v12, v8, v8
	v_max_f32_e32 v11, v11, v12
	s_and_b64 s[16:17], vcc, s[12:13]
	v_cndmask_b32_e64 v10, v10, v11, s[16:17]
	v_or_b32_e32 v0, 19, v0
	v_cmp_ge_i32_e32 vcc, v0, v105
	v_cmp_le_i32_e64 s[12:13], v0, v206
	v_max_f32_e32 v0, v10, v10
	v_max_f32_e32 v11, v9, v9
	v_max_f32_e32 v0, v0, v11
	s_and_b64 s[12:13], vcc, s[12:13]
	v_cndmask_b32_e64 v0, v10, v0, s[12:13]
	v_cmp_gt_f32_e32 vcc, v0, v211
	s_cbranch_vccz .LBB0_709
	v_and_b32_e32 v11, 64, v204
	v_xor_b32_e32 v10, 16, v204
	v_add_u32_e32 v11, 64, v11
	v_cmp_lt_i32_e32 vcc, v10, v11
	v_xor_b32_e32 v12, 32, v204
	s_nop 0
	v_cndmask_b32_e32 v10, v204, v10, vcc
	v_lshlrev_b32_e32 v10, 2, v10
	ds_bpermute_b32 v10, v10, v0
	v_max_f32_e32 v0, v0, v0
	v_cmp_lt_i32_e32 vcc, v12, v11
	s_waitcnt lgkmcnt(0)
	v_max_f32_e32 v10, v10, v10
	v_max_f32_e32 v0, v0, v10
	v_cndmask_b32_e32 v10, v204, v12, vcc
	v_lshlrev_b32_e32 v10, 2, v10
	ds_bpermute_b32 v10, v10, v0
	s_waitcnt lgkmcnt(0)
	v_max3_f32 v10, v210, v0, v10
	v_sub_f32_e32 v0, v210, v10
	v_exp_f32_e32 v0, v0
	v_mov_b32_e32 v210, v10
	v_mul_f32_e32 v209, v209, v0
	v_pk_mul_f32 v[36:37], v[36:37], v[0:1] op_sel_hi:[1,0]
	v_pk_mul_f32 v[34:35], v[34:35], v[0:1] op_sel_hi:[1,0]
	v_pk_mul_f32 v[40:41], v[40:41], v[0:1] op_sel_hi:[1,0]
	v_pk_mul_f32 v[38:39], v[38:39], v[0:1] op_sel_hi:[1,0]
	v_pk_mul_f32 v[44:45], v[44:45], v[0:1] op_sel_hi:[1,0]
	v_pk_mul_f32 v[42:43], v[42:43], v[0:1] op_sel_hi:[1,0]
	v_pk_mul_f32 v[56:57], v[56:57], v[0:1] op_sel_hi:[1,0]
	v_pk_mul_f32 v[54:55], v[54:55], v[0:1] op_sel_hi:[1,0]
	v_pk_mul_f32 v[64:65], v[64:65], v[0:1] op_sel_hi:[1,0]
	v_pk_mul_f32 v[62:63], v[62:63], v[0:1] op_sel_hi:[1,0]
	v_pk_mul_f32 v[60:61], v[60:61], v[0:1] op_sel_hi:[1,0]
	v_pk_mul_f32 v[58:59], v[58:59], v[0:1] op_sel_hi:[1,0]
	v_pk_mul_f32 v[52:53], v[52:53], v[0:1] op_sel_hi:[1,0]
	v_pk_mul_f32 v[50:51], v[50:51], v[0:1] op_sel_hi:[1,0]
	v_pk_mul_f32 v[48:49], v[48:49], v[0:1] op_sel_hi:[1,0]
	v_pk_mul_f32 v[46:47], v[46:47], v[0:1] op_sel_hi:[1,0]

; template <bool SLC, bool NOMASK> ...
;     ...
;     load_frag8(nxt, KF, VF, SLC ? (dnext & 0xfffff) : dnext, lane);
;     f32x4 sa[2] = {(f32x4){0.f, 0.f, 0.f, 0.f}, (f32x4){0.f, 0.f, 0.f, 0.f}};
; #pragma unroll
;     for (int T = 0; T < 2; ++T)
; #pragma unroll
;         for (int s2 = 0; s2 < 4; ++s2) sa[T] = __builtin_amdgcn_mfma_f32_16x16x32_fp8_fp8(cur.k[T][s2], qf[s2], sa[T], 0, 0, 0);
;     float sc[8]; bool vd[8]; float mx = -1e30f;
;     const bool act = lo == 0 || !SLC;
;     if (NOMASK) {
; #pragma unroll
;         for (int j = 0; j < 8; ++j) { sc[j] = sa[j >> 2][j & 3]; vd[j] = act; }
;         mx = fmaxf(fmaxf(fmaxf(sc[0], sc[1]), fmaxf(sc[2], sc[3])), fmaxf(fmaxf(sc[4], sc[5]), fmaxf(sc[6], sc[7])));
;         mx = act ? mx : -1e30f;
;     } else {
; #pragma unroll
;         for (int T = 0; T < 2; ++T)
; #pragma unroll
;             for (int r = 0; r < 4; ++r) { const int p = pos0 + 16 * T + 4 * kq + r; const bool v = (p >= lo) & (p <= hi); const float x = sa[T][r];
;                 sc[4 * T + r] = x; vd[4 * T + r] = v; mx = v ? fmaxf(mx, x) : mx; }
;     }
;     if (__builtin_amdgcn_ballot_w64(mx > st.m + 4.f) != 0ull) {
;         mx = fmaxf(mx, __shfl_xor(mx, 16)); mx = fmaxf(mx, __shfl_xor(mx, 32));
;         const float mn = fmaxf(st.m, mx), alpha = __builtin_amdgcn_exp2f(st.m - mn); st.m = mn; st.l *= alpha;
; #pragma unroll
;         for (int j = 0; j < 8; ++j) st.o[j] = st.o[j] * alpha;
;     }
.LBB0_711:
	v_lshl_add_u64 v[244:245], v[198:199], 0, v[98:99]
	global_load_dwordx4 v[132:135], v[244:245], off
	global_load_dwordx4 v[136:139], v[244:245], off offset:1024
	global_load_dwordx4 v[140:143], v[244:245], off offset:2048
	global_load_dwordx4 v[144:147], v[244:245], off offset:3072
	v_lshl_add_u64 v[246:247], v[196:197], 0, v[98:99]
	global_load_dwordx4 v[86:89], v[246:247], off
	global_load_dwordx4 v[90:93], v[246:247], off offset:1024
	global_load_dwordx4 v[94:97], v[246:247], off offset:2048
	global_load_dwordx4 v[112:115], v[246:247], off offset:3072
	s_waitcnt vmcnt(20)
	v_mfma_f32_16x16x128_f8f6f4 v[34:37], v[148:155], v[74:81], 0
	v_mfma_f32_16x16x128_f8f6f4 v[38:41], v[156:163], v[74:81], 0
	v_mov_b32_e32 v209, v207
	v_mov_b32_e32 v210, v208
	s_nop 8
	v_max_f32_e32 v0, v35, v35
	v_max_f32_e32 v42, v34, v34
	v_max_f32_e32 v0, v42, v0
	v_max_f32_e32 v42, v37, v37
	v_max_f32_e32 v43, v36, v36
	v_max_f32_e32 v42, v43, v42
	v_max_f32_e32 v43, v41, v41
	v_max_f32_e32 v44, v40, v40
	v_max_f32_e32 v43, v44, v43
	v_max3_f32 v43, v38, v39, v43
	v_max3_f32 v0, v0, v42, v43
	v_cmp_gt_f32_e32 vcc, v0, v211
	s_cbranch_vccz .LBB0_713
	v_and_b32_e32 v43, 64, v204
	v_xor_b32_e32 v42, 16, v204
	v_add_u32_e32 v43, 64, v43
	v_cmp_lt_i32_e32 vcc, v42, v43
	v_xor_b32_e32 v44, 32, v204
	s_nop 0
	v_cndmask_b32_e32 v42, v204, v42, vcc
	v_lshlrev_b32_e32 v42, 2, v42
	ds_bpermute_b32 v42, v42, v0
	v_max_f32_e32 v0, v0, v0
	v_cmp_lt_i32_e32 vcc, v44, v43
	s_waitcnt lgkmcnt(0)
	v_max_f32_e32 v42, v42, v42
	v_max_f32_e32 v0, v0, v42
	v_cndmask_b32_e32 v42, v204, v44, vcc
	v_lshlrev_b32_e32 v42, 2, v42
	ds_bpermute_b32 v42, v42, v0
	s_waitcnt lgkmcnt(0)
	v_max3_f32 v209, v207, v0, v42
	v_sub_f32_e32 v0, v207, v209
	v_exp_f32_e32 v0, v0
	s_nop 0
	v_mul_f32_e32 v210, v208, v0
	v_pk_mul_f32 v[4:5], v[4:5], v[0:1] op_sel_hi:[1,0]
	v_pk_mul_f32 v[2:3], v[2:3], v[0:1] op_sel_hi:[1,0]
	v_pk_mul_f32 v[8:9], v[8:9], v[0:1] op_sel_hi:[1,0]
	v_pk_mul_f32 v[6:7], v[6:7], v[0:1] op_sel_hi:[1,0]
	v_pk_mul_f32 v[12:13], v[12:13], v[0:1] op_sel_hi:[1,0]
	v_pk_mul_f32 v[10:11], v[10:11], v[0:1] op_sel_hi:[1,0]
	v_pk_mul_f32 v[16:17], v[16:17], v[0:1] op_sel_hi:[1,0]
	v_pk_mul_f32 v[14:15], v[14:15], v[0:1] op_sel_hi:[1,0]
	v_pk_mul_f32 v[20:21], v[20:21], v[0:1] op_sel_hi:[1,0]
	v_pk_mul_f32 v[18:19], v[18:19], v[0:1] op_sel_hi:[1,0]
	v_pk_mul_f32 v[24:25], v[24:25], v[0:1] op_sel_hi:[1,0]
	v_pk_mul_f32 v[22:23], v[22:23], v[0:1] op_sel_hi:[1,0]
	v_pk_mul_f32 v[32:33], v[32:33], v[0:1] op_sel_hi:[1,0]
	v_pk_mul_f32 v[30:31], v[30:31], v[0:1] op_sel_hi:[1,0]
	v_pk_mul_f32 v[28:29], v[28:29], v[0:1] op_sel_hi:[1,0]
	v_pk_mul_f32 v[26:27], v[26:27], v[0:1] op_sel_hi:[1,0]

; template <bool SLC, bool NOMASK> ...
;     ...
;     load_frag8(nxt, KF, VF, SLC ? (dnext & 0xfffff) : dnext, lane);
;     f32x4 sa[2] = {(f32x4){0.f, 0.f, 0.f, 0.f}, (f32x4){0.f, 0.f, 0.f, 0.f}};
; #pragma unroll
;     for (int T = 0; T < 2; ++T)
; #pragma unroll
;         for (int s2 = 0; s2 < 4; ++s2) sa[T] = __builtin_amdgcn_mfma_f32_16x16x32_fp8_fp8(cur.k[T][s2], qf[s2], sa[T], 0, 0, 0);
;     float sc[8]; bool vd[8]; float mx = -1e30f;
;     const bool act = lo == 0 || !SLC;
;     if (NOMASK) {
; #pragma unroll
;         for (int j = 0; j < 8; ++j) { sc[j] = sa[j >> 2][j & 3]; vd[j] = act; }
;         mx = fmaxf(fmaxf(fmaxf(sc[0], sc[1]), fmaxf(sc[2], sc[3])), fmaxf(fmaxf(sc[4], sc[5]), fmaxf(sc[6], sc[7])));
;         mx = act ? mx : -1e30f;
;     } else {
; #pragma unroll
;         for (int T = 0; T < 2; ++T)
; #pragma unroll
;             for (int r = 0; r < 4; ++r) { const int p = pos0 + 16 * T + 4 * kq + r; const bool v = (p >= lo) & (p <= hi); const float x = sa[T][r];
;                 sc[4 * T + r] = x; vd[4 * T + r] = v; mx = v ? fmaxf(mx, x) : mx; }
;     }
.LBB0_714:
	v_lshl_add_u64 v[244:245], v[198:199], 0, v[98:99]
	global_load_dwordx4 v[132:135], v[244:245], off
	global_load_dwordx4 v[136:139], v[244:245], off offset:1024
	global_load_dwordx4 v[140:143], v[244:245], off offset:2048
	global_load_dwordx4 v[144:147], v[244:245], off offset:3072
	v_lshl_add_u64 v[246:247], v[196:197], 0, v[98:99]
	global_load_dwordx4 v[86:89], v[246:247], off
	global_load_dwordx4 v[90:93], v[246:247], off offset:1024
	global_load_dwordx4 v[94:97], v[246:247], off offset:2048
	global_load_dwordx4 v[112:115], v[246:247], off offset:3072
	s_waitcnt vmcnt(20)
	v_mfma_f32_16x16x128_f8f6f4 v[34:37], v[148:155], v[74:81], 0
	v_or_b32_e32 v0, s76, v203
	v_cmp_ge_i32_e32 vcc, v0, v105
	v_cmp_le_i32_e64 s[4:5], v0, v206
	v_mfma_f32_16x16x128_f8f6f4 v[38:41], v[156:163], v[74:81], 0
	s_and_b64 s[10:11], vcc, s[4:5]
	v_or_b32_e32 v43, 1, v0
	v_cmp_ge_i32_e32 vcc, v43, v105
	v_cmp_lt_i32_e64 s[4:5], v0, v206
	s_and_b64 s[6:7], s[4:5], vcc
	s_nop 5
	v_max_f32_e32 v42, v34, v34
	v_max_f32_e32 v42, 0xf149f2ca, v42
	v_cndmask_b32_e64 v42, v205, v42, s[10:11]
	v_max_f32_e32 v43, v35, v35
	v_max_f32_e32 v43, v42, v43
	v_cndmask_b32_e64 v42, v42, v43, s[6:7]
	v_or_b32_e32 v43, 2, v0
	v_cmp_ge_i32_e32 vcc, v43, v105
	v_cmp_le_i32_e64 s[4:5], v43, v206
	v_max_f32_e32 v43, v36, v36
	v_max_f32_e32 v43, v42, v43
	s_and_b64 s[8:9], vcc, s[4:5]
	v_cndmask_b32_e64 v42, v42, v43, s[8:9]
	v_or_b32_e32 v43, 3, v0
	v_cmp_ge_i32_e32 vcc, v43, v105
	v_cmp_le_i32_e64 s[4:5], v43, v206
	v_max_f32_e32 v43, v37, v37
	v_max_f32_e32 v43, v42, v43
	s_and_b64 s[4:5], vcc, s[4:5]
	v_cndmask_b32_e64 v42, v42, v43, s[4:5]
	v_or_b32_e32 v43, 16, v0
	v_cmp_ge_i32_e32 vcc, v43, v105
	v_cmp_le_i32_e64 s[12:13], v43, v206
	v_max_f32_e32 v43, v38, v38
	v_max_f32_e32 v43, v42, v43
	s_and_b64 s[18:19], vcc, s[12:13]
	v_cndmask_b32_e64 v42, v42, v43, s[18:19]
	v_or_b32_e32 v43, 17, v0
	v_cmp_ge_i32_e32 vcc, v43, v105
	v_cmp_le_i32_e64 s[12:13], v43, v206
	v_max_f32_e32 v43, v42, v42
	v_max_f32_e32 v44, v39, v39
	v_max_f32_e32 v43, v43, v44
	s_and_b64 s[14:15], vcc, s[12:13]
	v_cndmask_b32_e64 v42, v42, v43, s[14:15]
	v_or_b32_e32 v43, 18, v0
	v_cmp_ge_i32_e32 vcc, v43, v105
	v_cmp_le_i32_e64 s[12:13], v43, v206
	v_max_f32_e32 v43, v42, v42
	v_max_f32_e32 v44, v40, v40
	v_max_f32_e32 v43, v43, v44
	s_and_b64 s[16:17], vcc, s[12:13]
	v_cndmask_b32_e64 v42, v42, v43, s[16:17]
	v_or_b32_e32 v0, 19, v0
	v_cmp_ge_i32_e32 vcc, v0, v105
	v_cmp_le_i32_e64 s[12:13], v0, v206
	v_max_f32_e32 v0, v42, v42
	v_max_f32_e32 v43, v41, v41
	v_max_f32_e32 v0, v0, v43
	s_and_b64 s[12:13], vcc, s[12:13]
	v_cndmask_b32_e64 v0, v42, v0, s[12:13]
	v_cmp_gt_f32_e32 vcc, v0, v211
	s_cbranch_vccz .LBB0_716
	v_and_b32_e32 v43, 64, v204
	v_xor_b32_e32 v42, 16, v204
	v_add_u32_e32 v43, 64, v43
	v_cmp_lt_i32_e32 vcc, v42, v43
	v_xor_b32_e32 v44, 32, v204
	s_nop 0
	v_cndmask_b32_e32 v42, v204, v42, vcc
	v_lshlrev_b32_e32 v42, 2, v42
	ds_bpermute_b32 v42, v42, v0
	v_max_f32_e32 v0, v0, v0
	v_cmp_lt_i32_e32 vcc, v44, v43
	s_waitcnt lgkmcnt(0)
	v_max_f32_e32 v42, v42, v42
	v_max_f32_e32 v0, v0, v42
	v_cndmask_b32_e32 v42, v204, v44, vcc
	v_lshlrev_b32_e32 v42, 2, v42
	ds_bpermute_b32 v42, v42, v0
	s_waitcnt lgkmcnt(0)
	v_max3_f32 v42, v207, v0, v42
	v_sub_f32_e32 v0, v207, v42
	v_exp_f32_e32 v0, v0
	v_mov_b32_e32 v207, v42
	v_mul_f32_e32 v208, v208, v0
	v_pk_mul_f32 v[4:5], v[4:5], v[0:1] op_sel_hi:[1,0]
	v_pk_mul_f32 v[2:3], v[2:3], v[0:1] op_sel_hi:[1,0]
	v_pk_mul_f32 v[8:9], v[8:9], v[0:1] op_sel_hi:[1,0]
	v_pk_mul_f32 v[6:7], v[6:7], v[0:1] op_sel_hi:[1,0]
	v_pk_mul_f32 v[12:13], v[12:13], v[0:1] op_sel_hi:[1,0]
	v_pk_mul_f32 v[10:11], v[10:11], v[0:1] op_sel_hi:[1,0]
	v_pk_mul_f32 v[16:17], v[16:17], v[0:1] op_sel_hi:[1,0]
	v_pk_mul_f32 v[14:15], v[14:15], v[0:1] op_sel_hi:[1,0]
	v_pk_mul_f32 v[20:21], v[20:21], v[0:1] op_sel_hi:[1,0]
	v_pk_mul_f32 v[18:19], v[18:19], v[0:1] op_sel_hi:[1,0]
	v_pk_mul_f32 v[24:25], v[24:25], v[0:1] op_sel_hi:[1,0]
	v_pk_mul_f32 v[22:23], v[22:23], v[0:1] op_sel_hi:[1,0]
	v_pk_mul_f32 v[32:33], v[32:33], v[0:1] op_sel_hi:[1,0]
	v_pk_mul_f32 v[30:31], v[30:31], v[0:1] op_sel_hi:[1,0]
	v_pk_mul_f32 v[28:29], v[28:29], v[0:1] op_sel_hi:[1,0]
	v_pk_mul_f32 v[26:27], v[26:27], v[0:1] op_sel_hi:[1,0]

; template <bool SLC, bool NOMASK> ...
;     ...
;     load_frag8(nxt, KF, VF, SLC ? (dnext & 0xfffff) : dnext, lane);
;     f32x4 sa[2] = {(f32x4){0.f, 0.f, 0.f, 0.f}, (f32x4){0.f, 0.f, 0.f, 0.f}};
; #pragma unroll
;     for (int T = 0; T < 2; ++T)
; #pragma unroll
;         for (int s2 = 0; s2 < 4; ++s2) sa[T] = __builtin_amdgcn_mfma_f32_16x16x32_fp8_fp8(cur.k[T][s2], qf[s2], sa[T], 0, 0, 0);
;     float sc[8]; bool vd[8]; float mx = -1e30f;
;     const bool act = lo == 0 || !SLC;
;     if (NOMASK) {
; #pragma unroll
;         for (int j = 0; j < 8; ++j) { sc[j] = sa[j >> 2][j & 3]; vd[j] = act; }
;         mx = fmaxf(fmaxf(fmaxf(sc[0], sc[1]), fmaxf(sc[2], sc[3])), fmaxf(fmaxf(sc[4], sc[5]), fmaxf(sc[6], sc[7])));
;         mx = act ? mx : -1e30f;
;     } else {
; #pragma unroll
;         for (int T = 0; T < 2; ++T)
; #pragma unroll
;             for (int r = 0; r < 4; ++r) { const int p = pos0 + 16 * T + 4 * kq + r; const bool v = (p >= lo) & (p <= hi); const float x = sa[T][r];
;                 sc[4 * T + r] = x; vd[4 * T + r] = v; mx = v ? fmaxf(mx, x) : mx; }
;     }
;     if (__builtin_amdgcn_ballot_w64(mx > st.m + 4.f) != 0ull) {
;         mx = fmaxf(mx, __shfl_xor(mx, 16)); mx = fmaxf(mx, __shfl_xor(mx, 32));
;         const float mn = fmaxf(st.m, mx), alpha = __builtin_amdgcn_exp2f(st.m - mn); st.m = mn; st.l *= alpha;
; #pragma unroll
;         for (int j = 0; j < 8; ++j) st.o[j] = st.o[j] * alpha;
;     }
; __device__ __forceinline__ void dilated_unit(int unit, const bf16_t* proj, const bf16_t* kbf, bf16_t* nsaout, int lane) {
;     ...
;         auto desc = [&](int i) { return 32 * (first + i); };
;         attn_run_frag8<false>(q8, kb8 + hoff, vb8 + hoff, desc, last - first + 1, lo, hi, 0, st, lane);
.LBB0_717:
	s_add_i32 s66, s66, 4
	s_min_i32 s4, s66, s74
	s_add_i32 s6, s4, s73
	s_lshl_b32 s76, s6, 5
	s_and_b32 s4, s76, 0x3fffffe0
	s_lshr_b32 s26, s4, 4
	s_lshl_b64 s[4:5], s[26:27], 11
	s_and_b32 s26, s6, 0x1ffffff
	s_and_b32 s8, s42, 0x2000000
	s_lshl_b64 s[6:7], s[26:27], 12
	s_cmp_eq_u32 s8, 0
	v_lshl_add_u64 v[198:199], v[82:83], 0, s[4:5]
	v_lshl_add_u64 v[196:197], v[84:85], 0, s[6:7]
	s_mov_b64 s[4:5], -1
	v_add_f32_e32 v211, 4.0, v209
	s_cbranch_scc1 .LBB0_721
	v_lshl_add_u64 v[244:245], v[198:199], 0, v[98:99]
	global_load_dwordx4 v[148:151], v[244:245], off
	global_load_dwordx4 v[152:155], v[244:245], off offset:1024
	global_load_dwordx4 v[156:159], v[244:245], off offset:2048
	global_load_dwordx4 v[160:163], v[244:245], off offset:3072
	v_lshl_add_u64 v[246:247], v[196:197], 0, v[98:99]
	global_load_dwordx4 v[116:119], v[246:247], off
	global_load_dwordx4 v[120:123], v[246:247], off offset:1024
	global_load_dwordx4 v[124:127], v[246:247], off offset:2048
	global_load_dwordx4 v[128:131], v[246:247], off offset:3072
	s_waitcnt vmcnt(20)
	v_mfma_f32_16x16x128_f8f6f4 v[2:5], v[180:187], v[74:81], 0
	v_mfma_f32_16x16x128_f8f6f4 v[6:9], v[188:195], v[74:81], 0
	v_mov_b32_e32 v207, v209
	v_mov_b32_e32 v208, v210
	s_nop 8
	v_max_f32_e32 v0, v3, v3
	v_max_f32_e32 v10, v2, v2
	v_max_f32_e32 v0, v10, v0
	v_max_f32_e32 v10, v5, v5
	v_max_f32_e32 v11, v4, v4
	v_max_f32_e32 v10, v11, v10
	v_max_f32_e32 v11, v9, v9
	v_max_f32_e32 v12, v8, v8
	v_max_f32_e32 v11, v12, v11
	v_max3_f32 v11, v6, v7, v11
	v_max3_f32 v0, v0, v10, v11
	v_cmp_gt_f32_e32 vcc, v0, v211
	s_cbranch_vccz .LBB0_720
	v_and_b32_e32 v11, 64, v204
	v_xor_b32_e32 v10, 16, v204
	v_add_u32_e32 v11, 64, v11
	v_cmp_lt_i32_e32 vcc, v10, v11
	v_xor_b32_e32 v12, 32, v204
	s_nop 0
	v_cndmask_b32_e32 v10, v204, v10, vcc
	v_lshlrev_b32_e32 v10, 2, v10
	ds_bpermute_b32 v10, v10, v0
	v_max_f32_e32 v0, v0, v0
	v_cmp_lt_i32_e32 vcc, v12, v11
	s_waitcnt lgkmcnt(0)
	v_max_f32_e32 v10, v10, v10
	v_max_f32_e32 v0, v0, v10
	v_cndmask_b32_e32 v10, v204, v12, vcc
	v_lshlrev_b32_e32 v10, 2, v10
	ds_bpermute_b32 v10, v10, v0
	s_waitcnt lgkmcnt(0)
	v_max3_f32 v207, v209, v0, v10
	v_sub_f32_e32 v0, v209, v207
	v_exp_f32_e32 v0, v0
	s_nop 0
	v_mul_f32_e32 v208, v210, v0
	v_pk_mul_f32 v[36:37], v[36:37], v[0:1] op_sel_hi:[1,0]
	v_pk_mul_f32 v[34:35], v[34:35], v[0:1] op_sel_hi:[1,0]
	v_pk_mul_f32 v[40:41], v[40:41], v[0:1] op_sel_hi:[1,0]
	v_pk_mul_f32 v[38:39], v[38:39], v[0:1] op_sel_hi:[1,0]
	v_pk_mul_f32 v[44:45], v[44:45], v[0:1] op_sel_hi:[1,0]
	v_pk_mul_f32 v[42:43], v[42:43], v[0:1] op_sel_hi:[1,0]
	v_pk_mul_f32 v[48:49], v[48:49], v[0:1] op_sel_hi:[1,0]
	v_pk_mul_f32 v[46:47], v[46:47], v[0:1] op_sel_hi:[1,0]
	v_pk_mul_f32 v[52:53], v[52:53], v[0:1] op_sel_hi:[1,0]
	v_pk_mul_f32 v[50:51], v[50:51], v[0:1] op_sel_hi:[1,0]
	v_pk_mul_f32 v[56:57], v[56:57], v[0:1] op_sel_hi:[1,0]
	v_pk_mul_f32 v[54:55], v[54:55], v[0:1] op_sel_hi:[1,0]
	v_pk_mul_f32 v[60:61], v[60:61], v[0:1] op_sel_hi:[1,0]
	v_pk_mul_f32 v[58:59], v[58:59], v[0:1] op_sel_hi:[1,0]
	v_pk_mul_f32 v[64:65], v[64:65], v[0:1] op_sel_hi:[1,0]
	v_pk_mul_f32 v[62:63], v[62:63], v[0:1] op_sel_hi:[1,0]

; template <bool SLC, bool NOMASK> ...
;     ...
;     load_frag8(nxt, KF, VF, SLC ? (dnext & 0xfffff) : dnext, lane);
;     f32x4 sa[2] = {(f32x4){0.f, 0.f, 0.f, 0.f}, (f32x4){0.f, 0.f, 0.f, 0.f}};
; #pragma unroll
;     for (int T = 0; T < 2; ++T)
; #pragma unroll
;         for (int s2 = 0; s2 < 4; ++s2) sa[T] = __builtin_amdgcn_mfma_f32_16x16x32_fp8_fp8(cur.k[T][s2], qf[s2], sa[T], 0, 0, 0);
;     float sc[8]; bool vd[8]; float mx = -1e30f;
;     const bool act = lo == 0 || !SLC;
;     if (NOMASK) {
; #pragma unroll
;         for (int j = 0; j < 8; ++j) { sc[j] = sa[j >> 2][j & 3]; vd[j] = act; }
;         mx = fmaxf(fmaxf(fmaxf(sc[0], sc[1]), fmaxf(sc[2], sc[3])), fmaxf(fmaxf(sc[4], sc[5]), fmaxf(sc[6], sc[7])));
;         mx = act ? mx : -1e30f;
;     } else {
; #pragma unroll
;         for (int T = 0; T < 2; ++T)
; #pragma unroll
;             for (int r = 0; r < 4; ++r) { const int p = pos0 + 16 * T + 4 * kq + r; const bool v = (p >= lo) & (p <= hi); const float x = sa[T][r];
;                 sc[4 * T + r] = x; vd[4 * T + r] = v; mx = v ? fmaxf(mx, x) : mx; }
;     }
.LBB0_721:
	s_and_b64 vcc, exec, s[4:5]
	s_cbranch_vccz .LBB0_725
	v_lshl_add_u64 v[244:245], v[198:199], 0, v[98:99]
	global_load_dwordx4 v[148:151], v[244:245], off
	global_load_dwordx4 v[152:155], v[244:245], off offset:1024
	global_load_dwordx4 v[156:159], v[244:245], off offset:2048
	global_load_dwordx4 v[160:163], v[244:245], off offset:3072
	v_lshl_add_u64 v[246:247], v[196:197], 0, v[98:99]
	global_load_dwordx4 v[116:119], v[246:247], off
	global_load_dwordx4 v[120:123], v[246:247], off offset:1024
	global_load_dwordx4 v[124:127], v[246:247], off offset:2048
	global_load_dwordx4 v[128:131], v[246:247], off offset:3072
	s_waitcnt vmcnt(20)
	v_mfma_f32_16x16x128_f8f6f4 v[2:5], v[180:187], v[74:81], 0
	v_or_b32_e32 v0, s78, v203
	v_cmp_ge_i32_e32 vcc, v0, v105
	v_cmp_le_i32_e64 s[4:5], v0, v206
	v_mfma_f32_16x16x128_f8f6f4 v[6:9], v[188:195], v[74:81], 0
	s_and_b64 s[10:11], vcc, s[4:5]
	v_or_b32_e32 v11, 1, v0
	v_cmp_ge_i32_e32 vcc, v11, v105
	v_cmp_lt_i32_e64 s[4:5], v0, v206
	s_and_b64 s[6:7], s[4:5], vcc
	s_nop 5
	v_max_f32_e32 v10, v2, v2
	v_max_f32_e32 v10, 0xf149f2ca, v10
	v_cndmask_b32_e64 v10, v205, v10, s[10:11]
	v_max_f32_e32 v11, v3, v3
	v_max_f32_e32 v11, v10, v11
	v_cndmask_b32_e64 v10, v10, v11, s[6:7]
	v_or_b32_e32 v11, 2, v0
	v_cmp_ge_i32_e32 vcc, v11, v105
	v_cmp_le_i32_e64 s[4:5], v11, v206
	v_max_f32_e32 v11, v4, v4
	v_max_f32_e32 v11, v10, v11
	s_and_b64 s[8:9], vcc, s[4:5]
	v_cndmask_b32_e64 v10, v10, v11, s[8:9]
	v_or_b32_e32 v11, 3, v0
	v_cmp_ge_i32_e32 vcc, v11, v105
	v_cmp_le_i32_e64 s[4:5], v11, v206
	v_max_f32_e32 v11, v5, v5
	v_max_f32_e32 v11, v10, v11
	s_and_b64 s[4:5], vcc, s[4:5]
	v_cndmask_b32_e64 v10, v10, v11, s[4:5]
	v_or_b32_e32 v11, 16, v0
	v_cmp_ge_i32_e32 vcc, v11, v105
	v_cmp_le_i32_e64 s[12:13], v11, v206
	v_max_f32_e32 v11, v6, v6
	v_max_f32_e32 v11, v10, v11
	s_and_b64 s[18:19], vcc, s[12:13]
	v_cndmask_b32_e64 v10, v10, v11, s[18:19]
	v_or_b32_e32 v11, 17, v0
	v_cmp_ge_i32_e32 vcc, v11, v105
	v_cmp_le_i32_e64 s[12:13], v11, v206
	v_max_f32_e32 v11, v10, v10
	v_max_f32_e32 v12, v7, v7
	v_max_f32_e32 v11, v11, v12
	s_and_b64 s[14:15], vcc, s[12:13]
	v_cndmask_b32_e64 v10, v10, v11, s[14:15]
	v_or_b32_e32 v11, 18, v0
	v_cmp_ge_i32_e32 vcc, v11, v105
	v_cmp_le_i32_e64 s[12:13], v11, v206
	v_max_f32_e32 v11, v10, v10
	v_max_f32_e32 v12, v8, v8
	v_max_f32_e32 v11, v11, v12
	s_and_b64 s[16:17], vcc, s[12:13]
	v_cndmask_b32_e64 v10, v10, v11, s[16:17]
	v_or_b32_e32 v0, 19, v0
	v_cmp_ge_i32_e32 vcc, v0, v105
	v_cmp_le_i32_e64 s[12:13], v0, v206
	v_max_f32_e32 v0, v10, v10
	v_max_f32_e32 v11, v9, v9
	v_max_f32_e32 v0, v0, v11
	s_and_b64 s[12:13], vcc, s[12:13]
	v_cndmask_b32_e64 v0, v10, v0, s[12:13]
	v_cmp_gt_f32_e32 vcc, v0, v211
	s_cbranch_vccz .LBB0_724
	v_and_b32_e32 v11, 64, v204
	v_xor_b32_e32 v10, 16, v204
	v_add_u32_e32 v11, 64, v11
	v_cmp_lt_i32_e32 vcc, v10, v11
	v_xor_b32_e32 v12, 32, v204
	s_nop 0
	v_cndmask_b32_e32 v10, v204, v10, vcc
	v_lshlrev_b32_e32 v10, 2, v10
	ds_bpermute_b32 v10, v10, v0
	v_max_f32_e32 v0, v0, v0
	v_cmp_lt_i32_e32 vcc, v12, v11
	s_waitcnt lgkmcnt(0)
	v_max_f32_e32 v10, v10, v10
	v_max_f32_e32 v0, v0, v10
	v_cndmask_b32_e32 v10, v204, v12, vcc
	v_lshlrev_b32_e32 v10, 2, v10
	ds_bpermute_b32 v10, v10, v0
	s_waitcnt lgkmcnt(0)
	v_max3_f32 v10, v209, v0, v10
	v_sub_f32_e32 v0, v209, v10
	v_exp_f32_e32 v0, v0
	v_mov_b32_e32 v209, v10
	v_mul_f32_e32 v210, v210, v0
	v_pk_mul_f32 v[36:37], v[36:37], v[0:1] op_sel_hi:[1,0]
	v_pk_mul_f32 v[34:35], v[34:35], v[0:1] op_sel_hi:[1,0]
	v_pk_mul_f32 v[40:41], v[40:41], v[0:1] op_sel_hi:[1,0]
	v_pk_mul_f32 v[38:39], v[38:39], v[0:1] op_sel_hi:[1,0]
	v_pk_mul_f32 v[44:45], v[44:45], v[0:1] op_sel_hi:[1,0]
	v_pk_mul_f32 v[42:43], v[42:43], v[0:1] op_sel_hi:[1,0]
	v_pk_mul_f32 v[48:49], v[48:49], v[0:1] op_sel_hi:[1,0]
	v_pk_mul_f32 v[46:47], v[46:47], v[0:1] op_sel_hi:[1,0]
	v_pk_mul_f32 v[52:53], v[52:53], v[0:1] op_sel_hi:[1,0]
	v_pk_mul_f32 v[50:51], v[50:51], v[0:1] op_sel_hi:[1,0]
	v_pk_mul_f32 v[56:57], v[56:57], v[0:1] op_sel_hi:[1,0]
	v_pk_mul_f32 v[54:55], v[54:55], v[0:1] op_sel_hi:[1,0]
	v_pk_mul_f32 v[60:61], v[60:61], v[0:1] op_sel_hi:[1,0]
	v_pk_mul_f32 v[58:59], v[58:59], v[0:1] op_sel_hi:[1,0]
	v_pk_mul_f32 v[64:65], v[64:65], v[0:1] op_sel_hi:[1,0]
	v_pk_mul_f32 v[62:63], v[62:63], v[0:1] op_sel_hi:[1,0]

; template <bool SLC, bool NOMASK> ...
;     ...
;     load_frag8(nxt, KF, VF, SLC ? (dnext & 0xfffff) : dnext, lane);
;     f32x4 sa[2] = {(f32x4){0.f, 0.f, 0.f, 0.f}, (f32x4){0.f, 0.f, 0.f, 0.f}};
; #pragma unroll
;     for (int T = 0; T < 2; ++T)
; #pragma unroll
;         for (int s2 = 0; s2 < 4; ++s2) sa[T] = __builtin_amdgcn_mfma_f32_16x16x32_fp8_fp8(cur.k[T][s2], qf[s2], sa[T], 0, 0, 0);
;     float sc[8]; bool vd[8]; float mx = -1e30f;
;     const bool act = lo == 0 || !SLC;
;     if (NOMASK) {
; #pragma unroll
;         for (int j = 0; j < 8; ++j) { sc[j] = sa[j >> 2][j & 3]; vd[j] = act; }
;         mx = fmaxf(fmaxf(fmaxf(sc[0], sc[1]), fmaxf(sc[2], sc[3])), fmaxf(fmaxf(sc[4], sc[5]), fmaxf(sc[6], sc[7])));
;         mx = act ? mx : -1e30f;
;     } else {
; #pragma unroll
;         for (int T = 0; T < 2; ++T)
; #pragma unroll
;             for (int r = 0; r < 4; ++r) { const int p = pos0 + 16 * T + 4 * kq + r; const bool v = (p >= lo) & (p <= hi); const float x = sa[T][r];
;                 sc[4 * T + r] = x; vd[4 * T + r] = v; mx = v ? fmaxf(mx, x) : mx; }
;     }
;     if (__builtin_amdgcn_ballot_w64(mx > st.m + 4.f) != 0ull) {
;         mx = fmaxf(mx, __shfl_xor(mx, 16)); mx = fmaxf(mx, __shfl_xor(mx, 32));
;         const float mn = fmaxf(st.m, mx), alpha = __builtin_amdgcn_exp2f(st.m - mn); st.m = mn; st.l *= alpha;
; #pragma unroll
;         for (int j = 0; j < 8; ++j) st.o[j] = st.o[j] * alpha;
;     }
.LBB0_745:
	v_lshl_add_u64 v[244:245], v[198:199], 0, v[98:99]
	global_load_dwordx4 v[180:183], v[244:245], off
	global_load_dwordx4 v[184:187], v[244:245], off offset:1024
	global_load_dwordx4 v[188:191], v[244:245], off offset:2048
	global_load_dwordx4 v[192:195], v[244:245], off offset:3072
	v_lshl_add_u64 v[246:247], v[196:197], 0, v[98:99]
	global_load_dwordx4 v[164:167], v[246:247], off
	global_load_dwordx4 v[168:171], v[246:247], off offset:1024
	global_load_dwordx4 v[172:175], v[246:247], off offset:2048
	global_load_dwordx4 v[176:179], v[246:247], off offset:3072
	s_waitcnt vmcnt(20)
	v_mfma_f32_16x16x128_f8f6f4 v[2:5], v[132:139], v[74:81], 0
	v_mfma_f32_16x16x128_f8f6f4 v[6:9], v[140:147], v[74:81], 0
	v_mov_b32_e32 v205, v208
	v_mov_b32_e32 v206, v207
	s_nop 8
	v_max_f32_e32 v0, v3, v3
	v_max_f32_e32 v10, v2, v2
	v_max_f32_e32 v0, v10, v0
	v_max_f32_e32 v10, v5, v5
	v_max_f32_e32 v11, v4, v4
	v_max_f32_e32 v10, v11, v10
	v_max_f32_e32 v11, v9, v9
	v_max_f32_e32 v12, v8, v8
	v_max_f32_e32 v11, v12, v11
	v_max3_f32 v11, v6, v7, v11
	v_max3_f32 v0, v0, v10, v11
	v_add_f32_e32 v10, 4.0, v208
	v_cmp_gt_f32_e32 vcc, v0, v10
	s_cbranch_vccz .LBB0_747
	v_and_b32_e32 v11, 64, v200
	v_xor_b32_e32 v10, 16, v200
	v_add_u32_e32 v11, 64, v11
	v_cmp_lt_i32_e32 vcc, v10, v11
	v_xor_b32_e32 v12, 32, v200
	s_nop 0
	v_cndmask_b32_e32 v10, v200, v10, vcc
	v_lshlrev_b32_e32 v10, 2, v10
	ds_bpermute_b32 v10, v10, v0
	v_max_f32_e32 v0, v0, v0
	v_cmp_lt_i32_e32 vcc, v12, v11
	s_waitcnt lgkmcnt(0)
	v_max_f32_e32 v10, v10, v10
	v_max_f32_e32 v0, v0, v10
	v_cndmask_b32_e32 v10, v200, v12, vcc
	v_lshlrev_b32_e32 v10, 2, v10
	ds_bpermute_b32 v10, v10, v0
	s_waitcnt lgkmcnt(0)
	v_max3_f32 v205, v208, v0, v10
	v_sub_f32_e32 v0, v208, v205
	v_exp_f32_e32 v0, v0
	s_nop 0
	v_mul_f32_e32 v206, v207, v0
	v_pk_mul_f32 v[36:37], v[36:37], v[0:1] op_sel_hi:[1,0]
	v_pk_mul_f32 v[34:35], v[34:35], v[0:1] op_sel_hi:[1,0]
	v_pk_mul_f32 v[40:41], v[40:41], v[0:1] op_sel_hi:[1,0]
	v_pk_mul_f32 v[38:39], v[38:39], v[0:1] op_sel_hi:[1,0]
	v_pk_mul_f32 v[44:45], v[44:45], v[0:1] op_sel_hi:[1,0]
	v_pk_mul_f32 v[42:43], v[42:43], v[0:1] op_sel_hi:[1,0]
	v_pk_mul_f32 v[56:57], v[56:57], v[0:1] op_sel_hi:[1,0]
	v_pk_mul_f32 v[54:55], v[54:55], v[0:1] op_sel_hi:[1,0]
	v_pk_mul_f32 v[64:65], v[64:65], v[0:1] op_sel_hi:[1,0]
	v_pk_mul_f32 v[62:63], v[62:63], v[0:1] op_sel_hi:[1,0]
	v_pk_mul_f32 v[60:61], v[60:61], v[0:1] op_sel_hi:[1,0]
	v_pk_mul_f32 v[58:59], v[58:59], v[0:1] op_sel_hi:[1,0]
	v_pk_mul_f32 v[52:53], v[52:53], v[0:1] op_sel_hi:[1,0]
	v_pk_mul_f32 v[50:51], v[50:51], v[0:1] op_sel_hi:[1,0]
	v_pk_mul_f32 v[48:49], v[48:49], v[0:1] op_sel_hi:[1,0]
	v_pk_mul_f32 v[46:47], v[46:47], v[0:1] op_sel_hi:[1,0]

; template <bool SLC, bool NOMASK> ...
;     ...
;     load_frag8(nxt, KF, VF, SLC ? (dnext & 0xfffff) : dnext, lane);
;     f32x4 sa[2] = {(f32x4){0.f, 0.f, 0.f, 0.f}, (f32x4){0.f, 0.f, 0.f, 0.f}};
; #pragma unroll
;     for (int T = 0; T < 2; ++T)
; #pragma unroll
;         for (int s2 = 0; s2 < 4; ++s2) sa[T] = __builtin_amdgcn_mfma_f32_16x16x32_fp8_fp8(cur.k[T][s2], qf[s2], sa[T], 0, 0, 0);
;     float sc[8]; bool vd[8]; float mx = -1e30f;
;     const bool act = lo == 0 || !SLC;
;     if (NOMASK) {
; #pragma unroll
;         for (int j = 0; j < 8; ++j) { sc[j] = sa[j >> 2][j & 3]; vd[j] = act; }
;         mx = fmaxf(fmaxf(fmaxf(sc[0], sc[1]), fmaxf(sc[2], sc[3])), fmaxf(fmaxf(sc[4], sc[5]), fmaxf(sc[6], sc[7])));
;         mx = act ? mx : -1e30f;
;     } else {
; #pragma unroll
;         for (int T = 0; T < 2; ++T)
; #pragma unroll
;             for (int r = 0; r < 4; ++r) { const int p = pos0 + 16 * T + 4 * kq + r; const bool v = (p >= lo) & (p <= hi); const float x = sa[T][r];
;                 sc[4 * T + r] = x; vd[4 * T + r] = v; mx = v ? fmaxf(mx, x) : mx; }
;     }
.LBB0_748:
	v_lshl_add_u64 v[244:245], v[198:199], 0, v[98:99]
	global_load_dwordx4 v[180:183], v[244:245], off
	global_load_dwordx4 v[184:187], v[244:245], off offset:1024
	global_load_dwordx4 v[188:191], v[244:245], off offset:2048
	global_load_dwordx4 v[192:195], v[244:245], off offset:3072
	v_lshl_add_u64 v[246:247], v[196:197], 0, v[98:99]
	global_load_dwordx4 v[164:167], v[246:247], off
	global_load_dwordx4 v[168:171], v[246:247], off offset:1024
	global_load_dwordx4 v[172:175], v[246:247], off offset:2048
	global_load_dwordx4 v[176:179], v[246:247], off offset:3072
	s_waitcnt vmcnt(20)
	v_mfma_f32_16x16x128_f8f6f4 v[2:5], v[132:139], v[74:81], 0
	v_or_b32_e32 v0, s62, v107
	v_cmp_ge_i32_e32 vcc, v0, v105
	v_cmp_le_i32_e64 s[4:5], v0, v204
	v_mfma_f32_16x16x128_f8f6f4 v[6:9], v[140:147], v[74:81], 0
	s_and_b64 s[10:11], vcc, s[4:5]
	v_or_b32_e32 v11, 1, v0
	v_cmp_ge_i32_e32 vcc, v11, v105
	v_cmp_lt_i32_e64 s[4:5], v0, v204
	s_and_b64 s[6:7], s[4:5], vcc
	s_nop 5
	v_max_f32_e32 v10, v2, v2
	v_max_f32_e32 v10, 0xf149f2ca, v10
	v_cndmask_b32_e64 v10, v203, v10, s[10:11]
	v_max_f32_e32 v11, v3, v3
	v_max_f32_e32 v11, v10, v11
	v_cndmask_b32_e64 v10, v10, v11, s[6:7]
	v_or_b32_e32 v11, 2, v0
	v_cmp_ge_i32_e32 vcc, v11, v105
	v_cmp_le_i32_e64 s[4:5], v11, v204
	v_max_f32_e32 v11, v4, v4
	v_max_f32_e32 v11, v10, v11
	s_and_b64 s[8:9], vcc, s[4:5]
	v_cndmask_b32_e64 v10, v10, v11, s[8:9]
	v_or_b32_e32 v11, 3, v0
	v_cmp_ge_i32_e32 vcc, v11, v105
	v_cmp_le_i32_e64 s[4:5], v11, v204
	v_max_f32_e32 v11, v5, v5
	v_max_f32_e32 v11, v10, v11
	s_and_b64 s[4:5], vcc, s[4:5]
	v_cndmask_b32_e64 v10, v10, v11, s[4:5]
	v_or_b32_e32 v11, 16, v0
	v_cmp_ge_i32_e32 vcc, v11, v105
	v_cmp_le_i32_e64 s[12:13], v11, v204
	v_max_f32_e32 v11, v6, v6
	v_max_f32_e32 v11, v10, v11
	s_and_b64 s[18:19], vcc, s[12:13]
	v_cndmask_b32_e64 v10, v10, v11, s[18:19]
	v_or_b32_e32 v11, 17, v0
	v_cmp_ge_i32_e32 vcc, v11, v105
	v_cmp_le_i32_e64 s[12:13], v11, v204
	v_max_f32_e32 v11, v10, v10
	v_max_f32_e32 v12, v7, v7
	v_max_f32_e32 v11, v11, v12
	s_and_b64 s[14:15], vcc, s[12:13]
	v_cndmask_b32_e64 v10, v10, v11, s[14:15]
	v_or_b32_e32 v11, 18, v0
	v_cmp_ge_i32_e32 vcc, v11, v105
	v_cmp_le_i32_e64 s[12:13], v11, v204
	v_max_f32_e32 v11, v10, v10
	v_max_f32_e32 v12, v8, v8
	v_max_f32_e32 v11, v11, v12
	s_and_b64 s[16:17], vcc, s[12:13]
	v_cndmask_b32_e64 v10, v10, v11, s[16:17]
	v_or_b32_e32 v0, 19, v0
	v_cmp_ge_i32_e32 vcc, v0, v105
	v_cmp_le_i32_e64 s[12:13], v0, v204
	v_max_f32_e32 v0, v10, v10
	v_max_f32_e32 v11, v9, v9
	v_max_f32_e32 v0, v0, v11
	s_and_b64 s[12:13], vcc, s[12:13]
	v_cndmask_b32_e64 v0, v10, v0, s[12:13]
	v_add_f32_e32 v10, 4.0, v208
	v_cmp_gt_f32_e32 vcc, v0, v10
	s_cbranch_vccz .LBB0_750
	v_and_b32_e32 v11, 64, v200
	v_xor_b32_e32 v10, 16, v200
	v_add_u32_e32 v11, 64, v11
	v_cmp_lt_i32_e32 vcc, v10, v11
	v_xor_b32_e32 v12, 32, v200
	s_nop 0
	v_cndmask_b32_e32 v10, v200, v10, vcc
	v_lshlrev_b32_e32 v10, 2, v10
	ds_bpermute_b32 v10, v10, v0
	v_max_f32_e32 v0, v0, v0
	v_cmp_lt_i32_e32 vcc, v12, v11
	s_waitcnt lgkmcnt(0)
	v_max_f32_e32 v10, v10, v10
	v_max_f32_e32 v0, v0, v10
	v_cndmask_b32_e32 v10, v200, v12, vcc
	v_lshlrev_b32_e32 v10, 2, v10
	ds_bpermute_b32 v10, v10, v0
	s_waitcnt lgkmcnt(0)
	v_max3_f32 v10, v208, v0, v10
	v_sub_f32_e32 v0, v208, v10
	v_exp_f32_e32 v0, v0
	v_mov_b32_e32 v208, v10
	v_mul_f32_e32 v207, v207, v0
	v_pk_mul_f32 v[36:37], v[36:37], v[0:1] op_sel_hi:[1,0]
	v_pk_mul_f32 v[34:35], v[34:35], v[0:1] op_sel_hi:[1,0]
	v_pk_mul_f32 v[40:41], v[40:41], v[0:1] op_sel_hi:[1,0]
	v_pk_mul_f32 v[38:39], v[38:39], v[0:1] op_sel_hi:[1,0]
	v_pk_mul_f32 v[44:45], v[44:45], v[0:1] op_sel_hi:[1,0]
	v_pk_mul_f32 v[42:43], v[42:43], v[0:1] op_sel_hi:[1,0]
	v_pk_mul_f32 v[56:57], v[56:57], v[0:1] op_sel_hi:[1,0]
	v_pk_mul_f32 v[54:55], v[54:55], v[0:1] op_sel_hi:[1,0]
	v_pk_mul_f32 v[64:65], v[64:65], v[0:1] op_sel_hi:[1,0]
	v_pk_mul_f32 v[62:63], v[62:63], v[0:1] op_sel_hi:[1,0]
	v_pk_mul_f32 v[60:61], v[60:61], v[0:1] op_sel_hi:[1,0]
	v_pk_mul_f32 v[58:59], v[58:59], v[0:1] op_sel_hi:[1,0]
	v_pk_mul_f32 v[52:53], v[52:53], v[0:1] op_sel_hi:[1,0]
	v_pk_mul_f32 v[50:51], v[50:51], v[0:1] op_sel_hi:[1,0]
	v_pk_mul_f32 v[48:49], v[48:49], v[0:1] op_sel_hi:[1,0]
	v_pk_mul_f32 v[46:47], v[46:47], v[0:1] op_sel_hi:[1,0]

; template <bool SLC, bool NOMASK> ...
;     ...
;     load_frag8(nxt, KF, VF, SLC ? (dnext & 0xfffff) : dnext, lane);
;     f32x4 sa[2] = {(f32x4){0.f, 0.f, 0.f, 0.f}, (f32x4){0.f, 0.f, 0.f, 0.f}};
; #pragma unroll
;     for (int T = 0; T < 2; ++T)
; #pragma unroll
;         for (int s2 = 0; s2 < 4; ++s2) sa[T] = __builtin_amdgcn_mfma_f32_16x16x32_fp8_fp8(cur.k[T][s2], qf[s2], sa[T], 0, 0, 0);
;     float sc[8]; bool vd[8]; float mx = -1e30f;
;     const bool act = lo == 0 || !SLC;
;     if (NOMASK) {
; #pragma unroll
;         for (int j = 0; j < 8; ++j) { sc[j] = sa[j >> 2][j & 3]; vd[j] = act; }
;         mx = fmaxf(fmaxf(fmaxf(sc[0], sc[1]), fmaxf(sc[2], sc[3])), fmaxf(fmaxf(sc[4], sc[5]), fmaxf(sc[6], sc[7])));
;         mx = act ? mx : -1e30f;
;     } else {
; #pragma unroll
;         for (int T = 0; T < 2; ++T)
; #pragma unroll
;             for (int r = 0; r < 4; ++r) { const int p = pos0 + 16 * T + 4 * kq + r; const bool v = (p >= lo) & (p <= hi); const float x = sa[T][r];
;                 sc[4 * T + r] = x; vd[4 * T + r] = v; mx = v ? fmaxf(mx, x) : mx; }
;     }
;     if (__builtin_amdgcn_ballot_w64(mx > st.m + 4.f) != 0ull) {
;         mx = fmaxf(mx, __shfl_xor(mx, 16)); mx = fmaxf(mx, __shfl_xor(mx, 32));
;         const float mn = fmaxf(st.m, mx), alpha = __builtin_amdgcn_exp2f(st.m - mn); st.m = mn; st.l *= alpha;
; #pragma unroll
;         for (int j = 0; j < 8; ++j) st.o[j] = st.o[j] * alpha;
;     }
.LBB0_752:
	v_lshl_add_u64 v[244:245], v[198:199], 0, v[98:99]
	global_load_dwordx4 v[132:135], v[244:245], off
	global_load_dwordx4 v[136:139], v[244:245], off offset:1024
	global_load_dwordx4 v[140:143], v[244:245], off offset:2048
	global_load_dwordx4 v[144:147], v[244:245], off offset:3072
	v_lshl_add_u64 v[246:247], v[196:197], 0, v[98:99]
	global_load_dwordx4 v[86:89], v[246:247], off
	global_load_dwordx4 v[90:93], v[246:247], off offset:1024
	global_load_dwordx4 v[94:97], v[246:247], off offset:2048
	global_load_dwordx4 v[112:115], v[246:247], off offset:3072
	s_waitcnt vmcnt(20)
	v_mfma_f32_16x16x128_f8f6f4 v[34:37], v[148:155], v[74:81], 0
	v_mfma_f32_16x16x128_f8f6f4 v[38:41], v[156:163], v[74:81], 0
	v_mov_b32_e32 v207, v205
	v_mov_b32_e32 v208, v206
	s_nop 8
	v_max_f32_e32 v0, v35, v35
	v_max_f32_e32 v42, v34, v34
	v_max_f32_e32 v0, v42, v0
	v_max_f32_e32 v42, v37, v37
	v_max_f32_e32 v43, v36, v36
	v_max_f32_e32 v42, v43, v42
	v_max_f32_e32 v43, v41, v41
	v_max_f32_e32 v44, v40, v40
	v_max_f32_e32 v43, v44, v43
	v_max3_f32 v43, v38, v39, v43
	v_max3_f32 v0, v0, v42, v43
	v_add_f32_e32 v42, 4.0, v205
	v_cmp_gt_f32_e32 vcc, v0, v42
	s_cbranch_vccz .LBB0_754
	v_and_b32_e32 v43, 64, v200
	v_xor_b32_e32 v42, 16, v200
	v_add_u32_e32 v43, 64, v43
	v_cmp_lt_i32_e32 vcc, v42, v43
	v_xor_b32_e32 v44, 32, v200
	s_nop 0
	v_cndmask_b32_e32 v42, v200, v42, vcc
	v_lshlrev_b32_e32 v42, 2, v42
	ds_bpermute_b32 v42, v42, v0
	v_max_f32_e32 v0, v0, v0
	v_cmp_lt_i32_e32 vcc, v44, v43
	s_waitcnt lgkmcnt(0)
	v_max_f32_e32 v42, v42, v42
	v_max_f32_e32 v0, v0, v42
	v_cndmask_b32_e32 v42, v200, v44, vcc
	v_lshlrev_b32_e32 v42, 2, v42
	ds_bpermute_b32 v42, v42, v0
	s_waitcnt lgkmcnt(0)
	v_max3_f32 v207, v205, v0, v42
	v_sub_f32_e32 v0, v205, v207
	v_exp_f32_e32 v0, v0
	s_nop 0
	v_mul_f32_e32 v208, v206, v0
	v_pk_mul_f32 v[4:5], v[4:5], v[0:1] op_sel_hi:[1,0]
	v_pk_mul_f32 v[2:3], v[2:3], v[0:1] op_sel_hi:[1,0]
	v_pk_mul_f32 v[8:9], v[8:9], v[0:1] op_sel_hi:[1,0]
	v_pk_mul_f32 v[6:7], v[6:7], v[0:1] op_sel_hi:[1,0]
	v_pk_mul_f32 v[12:13], v[12:13], v[0:1] op_sel_hi:[1,0]
	v_pk_mul_f32 v[10:11], v[10:11], v[0:1] op_sel_hi:[1,0]
	v_pk_mul_f32 v[16:17], v[16:17], v[0:1] op_sel_hi:[1,0]
	v_pk_mul_f32 v[14:15], v[14:15], v[0:1] op_sel_hi:[1,0]
	v_pk_mul_f32 v[20:21], v[20:21], v[0:1] op_sel_hi:[1,0]
	v_pk_mul_f32 v[18:19], v[18:19], v[0:1] op_sel_hi:[1,0]
	v_pk_mul_f32 v[24:25], v[24:25], v[0:1] op_sel_hi:[1,0]
	v_pk_mul_f32 v[22:23], v[22:23], v[0:1] op_sel_hi:[1,0]
	v_pk_mul_f32 v[32:33], v[32:33], v[0:1] op_sel_hi:[1,0]
	v_pk_mul_f32 v[30:31], v[30:31], v[0:1] op_sel_hi:[1,0]
	v_pk_mul_f32 v[28:29], v[28:29], v[0:1] op_sel_hi:[1,0]
	v_pk_mul_f32 v[26:27], v[26:27], v[0:1] op_sel_hi:[1,0]

; template <bool SLC, bool NOMASK> ...
;     ...
;     load_frag8(nxt, KF, VF, SLC ? (dnext & 0xfffff) : dnext, lane);
;     f32x4 sa[2] = {(f32x4){0.f, 0.f, 0.f, 0.f}, (f32x4){0.f, 0.f, 0.f, 0.f}};
; #pragma unroll
;     for (int T = 0; T < 2; ++T)
; #pragma unroll
;         for (int s2 = 0; s2 < 4; ++s2) sa[T] = __builtin_amdgcn_mfma_f32_16x16x32_fp8_fp8(cur.k[T][s2], qf[s2], sa[T], 0, 0, 0);
;     float sc[8]; bool vd[8]; float mx = -1e30f;
;     const bool act = lo == 0 || !SLC;
;     if (NOMASK) {
; #pragma unroll
;         for (int j = 0; j < 8; ++j) { sc[j] = sa[j >> 2][j & 3]; vd[j] = act; }
;         mx = fmaxf(fmaxf(fmaxf(sc[0], sc[1]), fmaxf(sc[2], sc[3])), fmaxf(fmaxf(sc[4], sc[5]), fmaxf(sc[6], sc[7])));
;         mx = act ? mx : -1e30f;
;     } else {
; #pragma unroll
;         for (int T = 0; T < 2; ++T)
; #pragma unroll
;             for (int r = 0; r < 4; ++r) { const int p = pos0 + 16 * T + 4 * kq + r; const bool v = (p >= lo) & (p <= hi); const float x = sa[T][r];
;                 sc[4 * T + r] = x; vd[4 * T + r] = v; mx = v ? fmaxf(mx, x) : mx; }
;     }
.LBB0_755:
	v_lshl_add_u64 v[244:245], v[198:199], 0, v[98:99]
	global_load_dwordx4 v[132:135], v[244:245], off
	global_load_dwordx4 v[136:139], v[244:245], off offset:1024
	global_load_dwordx4 v[140:143], v[244:245], off offset:2048
	global_load_dwordx4 v[144:147], v[244:245], off offset:3072
	v_lshl_add_u64 v[246:247], v[196:197], 0, v[98:99]
	global_load_dwordx4 v[86:89], v[246:247], off
	global_load_dwordx4 v[90:93], v[246:247], off offset:1024
	global_load_dwordx4 v[94:97], v[246:247], off offset:2048
	global_load_dwordx4 v[112:115], v[246:247], off offset:3072
	s_waitcnt vmcnt(20)
	v_mfma_f32_16x16x128_f8f6f4 v[34:37], v[148:155], v[74:81], 0
	v_or_b32_e32 v0, s63, v107
	v_cmp_ge_i32_e32 vcc, v0, v105
	v_cmp_le_i32_e64 s[4:5], v0, v204
	v_mfma_f32_16x16x128_f8f6f4 v[38:41], v[156:163], v[74:81], 0
	s_and_b64 s[10:11], vcc, s[4:5]
	v_or_b32_e32 v43, 1, v0
	v_cmp_ge_i32_e32 vcc, v43, v105
	v_cmp_lt_i32_e64 s[4:5], v0, v204
	s_and_b64 s[6:7], s[4:5], vcc
	s_nop 5
	v_max_f32_e32 v42, v34, v34
	v_max_f32_e32 v42, 0xf149f2ca, v42
	v_cndmask_b32_e64 v42, v203, v42, s[10:11]
	v_max_f32_e32 v43, v35, v35
	v_max_f32_e32 v43, v42, v43
	v_cndmask_b32_e64 v42, v42, v43, s[6:7]
	v_or_b32_e32 v43, 2, v0
	v_cmp_ge_i32_e32 vcc, v43, v105
	v_cmp_le_i32_e64 s[4:5], v43, v204
	v_max_f32_e32 v43, v36, v36
	v_max_f32_e32 v43, v42, v43
	s_and_b64 s[8:9], vcc, s[4:5]
	v_cndmask_b32_e64 v42, v42, v43, s[8:9]
	v_or_b32_e32 v43, 3, v0
	v_cmp_ge_i32_e32 vcc, v43, v105
	v_cmp_le_i32_e64 s[4:5], v43, v204
	v_max_f32_e32 v43, v37, v37
	v_max_f32_e32 v43, v42, v43
	s_and_b64 s[4:5], vcc, s[4:5]
	v_cndmask_b32_e64 v42, v42, v43, s[4:5]
	v_or_b32_e32 v43, 16, v0
	v_cmp_ge_i32_e32 vcc, v43, v105
	v_cmp_le_i32_e64 s[12:13], v43, v204
	v_max_f32_e32 v43, v38, v38
	v_max_f32_e32 v43, v42, v43
	s_and_b64 s[18:19], vcc, s[12:13]
	v_cndmask_b32_e64 v42, v42, v43, s[18:19]
	v_or_b32_e32 v43, 17, v0
	v_cmp_ge_i32_e32 vcc, v43, v105
	v_cmp_le_i32_e64 s[12:13], v43, v204
	v_max_f32_e32 v43, v42, v42
	v_max_f32_e32 v44, v39, v39
	v_max_f32_e32 v43, v43, v44
	s_and_b64 s[14:15], vcc, s[12:13]
	v_cndmask_b32_e64 v42, v42, v43, s[14:15]
	v_or_b32_e32 v43, 18, v0
	v_cmp_ge_i32_e32 vcc, v43, v105
	v_cmp_le_i32_e64 s[12:13], v43, v204
	v_max_f32_e32 v43, v42, v42
	v_max_f32_e32 v44, v40, v40
	v_max_f32_e32 v43, v43, v44
	s_and_b64 s[16:17], vcc, s[12:13]
	v_cndmask_b32_e64 v42, v42, v43, s[16:17]
	v_or_b32_e32 v0, 19, v0
	v_cmp_ge_i32_e32 vcc, v0, v105
	v_cmp_le_i32_e64 s[12:13], v0, v204
	v_max_f32_e32 v0, v42, v42
	v_max_f32_e32 v43, v41, v41
	v_max_f32_e32 v0, v0, v43
	s_and_b64 s[12:13], vcc, s[12:13]
	v_cndmask_b32_e64 v0, v42, v0, s[12:13]
	v_add_f32_e32 v42, 4.0, v205
	v_cmp_gt_f32_e32 vcc, v0, v42
	s_cbranch_vccz .LBB0_757
	v_and_b32_e32 v43, 64, v200
	v_xor_b32_e32 v42, 16, v200
	v_add_u32_e32 v43, 64, v43
	v_cmp_lt_i32_e32 vcc, v42, v43
	v_xor_b32_e32 v44, 32, v200
	s_nop 0
	v_cndmask_b32_e32 v42, v200, v42, vcc
	v_lshlrev_b32_e32 v42, 2, v42
	ds_bpermute_b32 v42, v42, v0
	v_max_f32_e32 v0, v0, v0
	v_cmp_lt_i32_e32 vcc, v44, v43
	s_waitcnt lgkmcnt(0)
	v_max_f32_e32 v42, v42, v42
	v_max_f32_e32 v0, v0, v42
	v_cndmask_b32_e32 v42, v200, v44, vcc
	v_lshlrev_b32_e32 v42, 2, v42
	ds_bpermute_b32 v42, v42, v0
	s_waitcnt lgkmcnt(0)
	v_max3_f32 v42, v205, v0, v42
	v_sub_f32_e32 v0, v205, v42
	v_exp_f32_e32 v0, v0
	v_mov_b32_e32 v205, v42
	v_mul_f32_e32 v206, v206, v0
	v_pk_mul_f32 v[4:5], v[4:5], v[0:1] op_sel_hi:[1,0]
	v_pk_mul_f32 v[2:3], v[2:3], v[0:1] op_sel_hi:[1,0]
	v_pk_mul_f32 v[8:9], v[8:9], v[0:1] op_sel_hi:[1,0]
	v_pk_mul_f32 v[6:7], v[6:7], v[0:1] op_sel_hi:[1,0]
	v_pk_mul_f32 v[12:13], v[12:13], v[0:1] op_sel_hi:[1,0]
	v_pk_mul_f32 v[10:11], v[10:11], v[0:1] op_sel_hi:[1,0]
	v_pk_mul_f32 v[16:17], v[16:17], v[0:1] op_sel_hi:[1,0]
	v_pk_mul_f32 v[14:15], v[14:15], v[0:1] op_sel_hi:[1,0]
	v_pk_mul_f32 v[20:21], v[20:21], v[0:1] op_sel_hi:[1,0]
	v_pk_mul_f32 v[18:19], v[18:19], v[0:1] op_sel_hi:[1,0]
	v_pk_mul_f32 v[24:25], v[24:25], v[0:1] op_sel_hi:[1,0]
	v_pk_mul_f32 v[22:23], v[22:23], v[0:1] op_sel_hi:[1,0]
	v_pk_mul_f32 v[32:33], v[32:33], v[0:1] op_sel_hi:[1,0]
	v_pk_mul_f32 v[30:31], v[30:31], v[0:1] op_sel_hi:[1,0]
	v_pk_mul_f32 v[28:29], v[28:29], v[0:1] op_sel_hi:[1,0]
	v_pk_mul_f32 v[26:27], v[26:27], v[0:1] op_sel_hi:[1,0]

; template <bool SLC, bool NOMASK> ...
;     ...
;     load_frag8(nxt, KF, VF, SLC ? (dnext & 0xfffff) : dnext, lane);
;     f32x4 sa[2] = {(f32x4){0.f, 0.f, 0.f, 0.f}, (f32x4){0.f, 0.f, 0.f, 0.f}};
; #pragma unroll
;     for (int T = 0; T < 2; ++T)
; #pragma unroll
;         for (int s2 = 0; s2 < 4; ++s2) sa[T] = __builtin_amdgcn_mfma_f32_16x16x32_fp8_fp8(cur.k[T][s2], qf[s2], sa[T], 0, 0, 0);
;     float sc[8]; bool vd[8]; float mx = -1e30f;
;     const bool act = lo == 0 || !SLC;
;     if (NOMASK) {
; #pragma unroll
;         for (int j = 0; j < 8; ++j) { sc[j] = sa[j >> 2][j & 3]; vd[j] = act; }
;         mx = fmaxf(fmaxf(fmaxf(sc[0], sc[1]), fmaxf(sc[2], sc[3])), fmaxf(fmaxf(sc[4], sc[5]), fmaxf(sc[6], sc[7])));
;         mx = act ? mx : -1e30f;
;     } else {
; #pragma unroll
;         for (int T = 0; T < 2; ++T)
; #pragma unroll
;             for (int r = 0; r < 4; ++r) { const int p = pos0 + 16 * T + 4 * kq + r; const bool v = (p >= lo) & (p <= hi); const float x = sa[T][r];
;                 sc[4 * T + r] = x; vd[4 * T + r] = v; mx = v ? fmaxf(mx, x) : mx; }
;     }
;     if (__builtin_amdgcn_ballot_w64(mx > st.m + 4.f) != 0ull) {
;         mx = fmaxf(mx, __shfl_xor(mx, 16)); mx = fmaxf(mx, __shfl_xor(mx, 32));
;         const float mn = fmaxf(st.m, mx), alpha = __builtin_amdgcn_exp2f(st.m - mn); st.m = mn; st.l *= alpha;
; #pragma unroll
;         for (int j = 0; j < 8; ++j) st.o[j] = st.o[j] * alpha;
;     }
; __device__ __forceinline__ void dilated_unit(int unit, const bf16_t* proj, const bf16_t* kbf, bf16_t* nsaout, int lane) {
;     ...
;         auto desc = [&](int i) { return 32 * (first + i); };
;         attn_run_frag8<false>(q8, kb8 + hoff, vb8 + hoff, desc, last - first + 1, lo, hi, 0, st, lane);
.LBB0_758:
	s_add_i32 s66, s66, 4
	s_min_i32 s4, s66, s61
	s_add_i32 s6, s4, s60
	s_lshl_b32 s63, s6, 5
	s_and_b32 s4, s63, 0x3fffffe0
	s_lshr_b32 s24, s4, 4
	s_lshl_b64 s[4:5], s[24:25], 11
	s_and_b32 s24, s6, 0x1ffffff
	s_and_b32 s8, s42, 0x2000000
	s_lshl_b64 s[6:7], s[24:25], 12
	s_cmp_eq_u32 s8, 0
	v_lshl_add_u64 v[198:199], v[82:83], 0, s[4:5]
	v_lshl_add_u64 v[196:197], v[84:85], 0, s[6:7]
	s_mov_b64 s[4:5], -1
	v_add_f32_e32 v209, 4.0, v207
	s_cbranch_scc1 .LBB0_762
	v_lshl_add_u64 v[244:245], v[198:199], 0, v[98:99]
	global_load_dwordx4 v[148:151], v[244:245], off
	global_load_dwordx4 v[152:155], v[244:245], off offset:1024
	global_load_dwordx4 v[156:159], v[244:245], off offset:2048
	global_load_dwordx4 v[160:163], v[244:245], off offset:3072
	v_lshl_add_u64 v[246:247], v[196:197], 0, v[98:99]
	global_load_dwordx4 v[116:119], v[246:247], off
	global_load_dwordx4 v[120:123], v[246:247], off offset:1024
	global_load_dwordx4 v[124:127], v[246:247], off offset:2048
	global_load_dwordx4 v[128:131], v[246:247], off offset:3072
	s_waitcnt vmcnt(20)
	v_mfma_f32_16x16x128_f8f6f4 v[2:5], v[180:187], v[74:81], 0
	v_mfma_f32_16x16x128_f8f6f4 v[6:9], v[188:195], v[74:81], 0
	v_mov_b32_e32 v205, v207
	v_mov_b32_e32 v206, v208
	s_nop 8
	v_max_f32_e32 v0, v3, v3
	v_max_f32_e32 v10, v2, v2
	v_max_f32_e32 v0, v10, v0
	v_max_f32_e32 v10, v5, v5
	v_max_f32_e32 v11, v4, v4
	v_max_f32_e32 v10, v11, v10
	v_max_f32_e32 v11, v9, v9
	v_max_f32_e32 v12, v8, v8
	v_max_f32_e32 v11, v12, v11
	v_max3_f32 v11, v6, v7, v11
	v_max3_f32 v0, v0, v10, v11
	v_cmp_gt_f32_e32 vcc, v0, v209
	s_cbranch_vccz .LBB0_761
	v_and_b32_e32 v11, 64, v200
	v_xor_b32_e32 v10, 16, v200
	v_add_u32_e32 v11, 64, v11
	v_cmp_lt_i32_e32 vcc, v10, v11
	v_xor_b32_e32 v12, 32, v200
	s_nop 0
	v_cndmask_b32_e32 v10, v200, v10, vcc
	v_lshlrev_b32_e32 v10, 2, v10
	ds_bpermute_b32 v10, v10, v0
	v_max_f32_e32 v0, v0, v0
	v_cmp_lt_i32_e32 vcc, v12, v11
	s_waitcnt lgkmcnt(0)
	v_max_f32_e32 v10, v10, v10
	v_max_f32_e32 v0, v0, v10
	v_cndmask_b32_e32 v10, v200, v12, vcc
	v_lshlrev_b32_e32 v10, 2, v10
	ds_bpermute_b32 v10, v10, v0
	s_waitcnt lgkmcnt(0)
	v_max3_f32 v205, v207, v0, v10
	v_sub_f32_e32 v0, v207, v205
	v_exp_f32_e32 v0, v0
	s_nop 0
	v_mul_f32_e32 v206, v208, v0
	v_pk_mul_f32 v[36:37], v[36:37], v[0:1] op_sel_hi:[1,0]
	v_pk_mul_f32 v[34:35], v[34:35], v[0:1] op_sel_hi:[1,0]
	v_pk_mul_f32 v[40:41], v[40:41], v[0:1] op_sel_hi:[1,0]
	v_pk_mul_f32 v[38:39], v[38:39], v[0:1] op_sel_hi:[1,0]
	v_pk_mul_f32 v[44:45], v[44:45], v[0:1] op_sel_hi:[1,0]
	v_pk_mul_f32 v[42:43], v[42:43], v[0:1] op_sel_hi:[1,0]
	v_pk_mul_f32 v[48:49], v[48:49], v[0:1] op_sel_hi:[1,0]
	v_pk_mul_f32 v[46:47], v[46:47], v[0:1] op_sel_hi:[1,0]
	v_pk_mul_f32 v[52:53], v[52:53], v[0:1] op_sel_hi:[1,0]
	v_pk_mul_f32 v[50:51], v[50:51], v[0:1] op_sel_hi:[1,0]
	v_pk_mul_f32 v[56:57], v[56:57], v[0:1] op_sel_hi:[1,0]
	v_pk_mul_f32 v[54:55], v[54:55], v[0:1] op_sel_hi:[1,0]
	v_pk_mul_f32 v[60:61], v[60:61], v[0:1] op_sel_hi:[1,0]
	v_pk_mul_f32 v[58:59], v[58:59], v[0:1] op_sel_hi:[1,0]
	v_pk_mul_f32 v[64:65], v[64:65], v[0:1] op_sel_hi:[1,0]
	v_pk_mul_f32 v[62:63], v[62:63], v[0:1] op_sel_hi:[1,0]

; template <bool SLC, bool NOMASK> ...
;     ...
;     load_frag8(nxt, KF, VF, SLC ? (dnext & 0xfffff) : dnext, lane);
;     f32x4 sa[2] = {(f32x4){0.f, 0.f, 0.f, 0.f}, (f32x4){0.f, 0.f, 0.f, 0.f}};
; #pragma unroll
;     for (int T = 0; T < 2; ++T)
; #pragma unroll
;         for (int s2 = 0; s2 < 4; ++s2) sa[T] = __builtin_amdgcn_mfma_f32_16x16x32_fp8_fp8(cur.k[T][s2], qf[s2], sa[T], 0, 0, 0);
;     float sc[8]; bool vd[8]; float mx = -1e30f;
;     const bool act = lo == 0 || !SLC;
;     if (NOMASK) {
; #pragma unroll
;         for (int j = 0; j < 8; ++j) { sc[j] = sa[j >> 2][j & 3]; vd[j] = act; }
;         mx = fmaxf(fmaxf(fmaxf(sc[0], sc[1]), fmaxf(sc[2], sc[3])), fmaxf(fmaxf(sc[4], sc[5]), fmaxf(sc[6], sc[7])));
;         mx = act ? mx : -1e30f;
;     } else {
; #pragma unroll
;         for (int T = 0; T < 2; ++T)
; #pragma unroll
;             for (int r = 0; r < 4; ++r) { const int p = pos0 + 16 * T + 4 * kq + r; const bool v = (p >= lo) & (p <= hi); const float x = sa[T][r];
;                 sc[4 * T + r] = x; vd[4 * T + r] = v; mx = v ? fmaxf(mx, x) : mx; }
;     }
.LBB0_762:
	s_and_b64 vcc, exec, s[4:5]
	s_cbranch_vccz .LBB0_766
	v_lshl_add_u64 v[244:245], v[198:199], 0, v[98:99]
	global_load_dwordx4 v[148:151], v[244:245], off
	global_load_dwordx4 v[152:155], v[244:245], off offset:1024
	global_load_dwordx4 v[156:159], v[244:245], off offset:2048
	global_load_dwordx4 v[160:163], v[244:245], off offset:3072
	v_lshl_add_u64 v[246:247], v[196:197], 0, v[98:99]
	global_load_dwordx4 v[116:119], v[246:247], off
	global_load_dwordx4 v[120:123], v[246:247], off offset:1024
	global_load_dwordx4 v[124:127], v[246:247], off offset:2048
	global_load_dwordx4 v[128:131], v[246:247], off offset:3072
	s_waitcnt vmcnt(20)
	v_mfma_f32_16x16x128_f8f6f4 v[2:5], v[180:187], v[74:81], 0
	v_or_b32_e32 v0, s68, v107
	v_cmp_ge_i32_e32 vcc, v0, v105
	v_cmp_le_i32_e64 s[4:5], v0, v204
	v_mfma_f32_16x16x128_f8f6f4 v[6:9], v[188:195], v[74:81], 0
	s_and_b64 s[10:11], vcc, s[4:5]
	v_or_b32_e32 v11, 1, v0
	v_cmp_ge_i32_e32 vcc, v11, v105
	v_cmp_lt_i32_e64 s[4:5], v0, v204
	s_and_b64 s[6:7], s[4:5], vcc
	s_nop 5
	v_max_f32_e32 v10, v2, v2
	v_max_f32_e32 v10, 0xf149f2ca, v10
	v_cndmask_b32_e64 v10, v203, v10, s[10:11]
	v_max_f32_e32 v11, v3, v3
	v_max_f32_e32 v11, v10, v11
	v_cndmask_b32_e64 v10, v10, v11, s[6:7]
	v_or_b32_e32 v11, 2, v0
	v_cmp_ge_i32_e32 vcc, v11, v105
	v_cmp_le_i32_e64 s[4:5], v11, v204
	v_max_f32_e32 v11, v4, v4
	v_max_f32_e32 v11, v10, v11
	s_and_b64 s[8:9], vcc, s[4:5]
	v_cndmask_b32_e64 v10, v10, v11, s[8:9]
	v_or_b32_e32 v11, 3, v0
	v_cmp_ge_i32_e32 vcc, v11, v105
	v_cmp_le_i32_e64 s[4:5], v11, v204
	v_max_f32_e32 v11, v5, v5
	v_max_f32_e32 v11, v10, v11
	s_and_b64 s[4:5], vcc, s[4:5]
	v_cndmask_b32_e64 v10, v10, v11, s[4:5]
	v_or_b32_e32 v11, 16, v0
	v_cmp_ge_i32_e32 vcc, v11, v105
	v_cmp_le_i32_e64 s[12:13], v11, v204
	v_max_f32_e32 v11, v6, v6
	v_max_f32_e32 v11, v10, v11
	s_and_b64 s[18:19], vcc, s[12:13]
	v_cndmask_b32_e64 v10, v10, v11, s[18:19]
	v_or_b32_e32 v11, 17, v0
	v_cmp_ge_i32_e32 vcc, v11, v105
	v_cmp_le_i32_e64 s[12:13], v11, v204
	v_max_f32_e32 v11, v10, v10
	v_max_f32_e32 v12, v7, v7
	v_max_f32_e32 v11, v11, v12
	s_and_b64 s[14:15], vcc, s[12:13]
	v_cndmask_b32_e64 v10, v10, v11, s[14:15]
	v_or_b32_e32 v11, 18, v0
	v_cmp_ge_i32_e32 vcc, v11, v105
	v_cmp_le_i32_e64 s[12:13], v11, v204
	v_max_f32_e32 v11, v10, v10
	v_max_f32_e32 v12, v8, v8
	v_max_f32_e32 v11, v11, v12
	s_and_b64 s[16:17], vcc, s[12:13]
	v_cndmask_b32_e64 v10, v10, v11, s[16:17]
	v_or_b32_e32 v0, 19, v0
	v_cmp_ge_i32_e32 vcc, v0, v105
	v_cmp_le_i32_e64 s[12:13], v0, v204
	v_max_f32_e32 v0, v10, v10
	v_max_f32_e32 v11, v9, v9
	v_max_f32_e32 v0, v0, v11
	s_and_b64 s[12:13], vcc, s[12:13]
	v_cndmask_b32_e64 v0, v10, v0, s[12:13]
	v_cmp_gt_f32_e32 vcc, v0, v209
	s_cbranch_vccz .LBB0_765
	v_and_b32_e32 v11, 64, v200
	v_xor_b32_e32 v10, 16, v200
	v_add_u32_e32 v11, 64, v11
	v_cmp_lt_i32_e32 vcc, v10, v11
	v_xor_b32_e32 v12, 32, v200
	s_nop 0
	v_cndmask_b32_e32 v10, v200, v10, vcc
	v_lshlrev_b32_e32 v10, 2, v10
	ds_bpermute_b32 v10, v10, v0
	v_max_f32_e32 v0, v0, v0
	v_cmp_lt_i32_e32 vcc, v12, v11
	s_waitcnt lgkmcnt(0)
	v_max_f32_e32 v10, v10, v10
	v_max_f32_e32 v0, v0, v10
	v_cndmask_b32_e32 v10, v200, v12, vcc
	v_lshlrev_b32_e32 v10, 2, v10
	ds_bpermute_b32 v10, v10, v0
	s_waitcnt lgkmcnt(0)
	v_max3_f32 v10, v207, v0, v10
	v_sub_f32_e32 v0, v207, v10
	v_exp_f32_e32 v0, v0
	v_mov_b32_e32 v207, v10
	v_mul_f32_e32 v208, v208, v0
	v_pk_mul_f32 v[36:37], v[36:37], v[0:1] op_sel_hi:[1,0]
	v_pk_mul_f32 v[34:35], v[34:35], v[0:1] op_sel_hi:[1,0]
	v_pk_mul_f32 v[40:41], v[40:41], v[0:1] op_sel_hi:[1,0]
	v_pk_mul_f32 v[38:39], v[38:39], v[0:1] op_sel_hi:[1,0]
	v_pk_mul_f32 v[44:45], v[44:45], v[0:1] op_sel_hi:[1,0]
	v_pk_mul_f32 v[42:43], v[42:43], v[0:1] op_sel_hi:[1,0]
	v_pk_mul_f32 v[48:49], v[48:49], v[0:1] op_sel_hi:[1,0]
	v_pk_mul_f32 v[46:47], v[46:47], v[0:1] op_sel_hi:[1,0]
	v_pk_mul_f32 v[52:53], v[52:53], v[0:1] op_sel_hi:[1,0]
	v_pk_mul_f32 v[50:51], v[50:51], v[0:1] op_sel_hi:[1,0]
	v_pk_mul_f32 v[56:57], v[56:57], v[0:1] op_sel_hi:[1,0]
	v_pk_mul_f32 v[54:55], v[54:55], v[0:1] op_sel_hi:[1,0]
	v_pk_mul_f32 v[60:61], v[60:61], v[0:1] op_sel_hi:[1,0]
	v_pk_mul_f32 v[58:59], v[58:59], v[0:1] op_sel_hi:[1,0]
	v_pk_mul_f32 v[64:65], v[64:65], v[0:1] op_sel_hi:[1,0]
	v_pk_mul_f32 v[62:63], v[62:63], v[0:1] op_sel_hi:[1,0]

; template <bool SLC, bool NOMASK> ...
;     ...
;     const int pos0 = SLC ? (dcur & 0xfffff) : dcur;
;     const int lo = SLC ? ((((dcur >> 20) == qi) | ((dcur >> 20) == 4)) ? 0 : (1 << 30)) : lo_in;
;     load_frag8(nxt, KF, VF, SLC ? (dnext & 0xfffff) : dnext, lane);
;     f32x4 sa[2] = {(f32x4){0.f, 0.f, 0.f, 0.f}, (f32x4){0.f, 0.f, 0.f, 0.f}};
; #pragma unroll
;     for (int T = 0; T < 2; ++T)
; #pragma unroll
;         for (int s2 = 0; s2 < 4; ++s2) sa[T] = __builtin_amdgcn_mfma_f32_16x16x32_fp8_fp8(cur.k[T][s2], qf[s2], sa[T], 0, 0, 0);
;     float sc[8]; bool vd[8]; float mx = -1e30f;
;     const bool act = lo == 0 || !SLC;
;     if (NOMASK) {
; #pragma unroll
;         for (int j = 0; j < 8; ++j) { sc[j] = sa[j >> 2][j & 3]; vd[j] = act; }
;         mx = fmaxf(fmaxf(fmaxf(sc[0], sc[1]), fmaxf(sc[2], sc[3])), fmaxf(fmaxf(sc[4], sc[5]), fmaxf(sc[6], sc[7])));
;         mx = act ? mx : -1e30f;
;     } else {
; #pragma unroll
;         for (int T = 0; T < 2; ++T)
; #pragma unroll
;             for (int r = 0; r < 4; ++r) { const int p = pos0 + 16 * T + 4 * kq + r; const bool v = (p >= lo) & (p <= hi); const float x = sa[T][r];
;                 sc[4 * T + r] = x; vd[4 * T + r] = v; mx = v ? fmaxf(mx, x) : mx; }
;     }
;     if (__builtin_amdgcn_ballot_w64(mx > st.m + 4.f) != 0ull) {
;         mx = fmaxf(mx, __shfl_xor(mx, 16)); mx = fmaxf(mx, __shfl_xor(mx, 32));
;         const float mn = fmaxf(st.m, mx), alpha = __builtin_amdgcn_exp2f(st.m - mn); st.m = mn; st.l *= alpha;
; #pragma unroll
;         for (int j = 0; j < 8; ++j) st.o[j] = st.o[j] * alpha;
;     }
.LBB0_867:
	s_and_b32 s13, s12, 0xfffffbff
	s_cmp_eq_u32 s13, 4
	s_cselect_b64 s[10:11], -1, 0
	s_lshl_b32 s14, s66, 7
	s_and_b32 s50, s14, 0x7fff800
	v_lshl_add_u64 v[10:11], v[86:87], 0, s[50:51]
	s_and_b32 s50, s14, 0x7fff000
	v_lshl_add_u64 v[244:245], v[10:11], 0, v[118:119]
	global_load_dwordx4 v[186:189], v[244:245], off
	global_load_dwordx4 v[190:193], v[244:245], off offset:1024
	global_load_dwordx4 v[194:197], v[244:245], off offset:2048
	global_load_dwordx4 v[198:201], v[244:245], off offset:3072
	v_lshl_add_u64 v[10:11], v[88:89], 0, s[50:51]
	v_lshl_add_u64 v[246:247], v[10:11], 0, v[118:119]
	global_load_dwordx4 v[170:173], v[246:247], off
	global_load_dwordx4 v[174:177], v[246:247], off offset:1024
	global_load_dwordx4 v[178:181], v[246:247], off offset:2048
	global_load_dwordx4 v[182:185], v[246:247], off offset:3072
	s_waitcnt vmcnt(20)
	v_mfma_f32_16x16x128_f8f6f4 v[2:5], v[138:145], v[78:85], 0
	v_cmp_eq_u32_e32 vcc, s13, v209
	s_or_b64 s[10:11], s[10:11], vcc
	v_mfma_f32_16x16x128_f8f6f4 v[6:9], v[146:153], v[78:85], 0
	v_mov_b32_e32 v133, v203
	s_nop 7
	v_max_f32_e32 v0, v3, v3
	v_max_f32_e32 v10, v2, v2
	v_max_f32_e32 v0, v10, v0
	v_max_f32_e32 v10, v5, v5
	v_max_f32_e32 v11, v4, v4
	v_max_f32_e32 v10, v11, v10
	v_max_f32_e32 v11, v9, v9
	v_max_f32_e32 v12, v8, v8
	v_max_f32_e32 v11, v12, v11
	v_max3_f32 v11, v6, v7, v11
	v_max3_f32 v0, v0, v10, v11
	v_cndmask_b32_e64 v34, v223, v0, s[10:11]
	v_cmp_gt_f32_e32 vcc, v34, v204
	v_mov_b32_e32 v0, v202
	s_cbranch_vccz .LBB0_869
	ds_bpermute_b32 v0, v227, v34
	v_max_f32_e32 v10, v34, v34
	s_waitcnt lgkmcnt(0)
	v_max_f32_e32 v0, v0, v0
	v_max_f32_e32 v0, v10, v0
	ds_bpermute_b32 v10, v226, v0
	s_waitcnt lgkmcnt(0)
	v_max3_f32 v0, v202, v0, v10
	v_sub_f32_e32 v10, v202, v0
	v_exp_f32_e32 v34, v10
	s_nop 0
	v_mul_f32_e32 v133, v203, v34
	v_pk_mul_f32 v[66:67], v[66:67], v[34:35] op_sel_hi:[1,0]
	v_pk_mul_f32 v[64:65], v[64:65], v[34:35] op_sel_hi:[1,0]
	v_pk_mul_f32 v[62:63], v[62:63], v[34:35] op_sel_hi:[1,0]
	v_pk_mul_f32 v[60:61], v[60:61], v[34:35] op_sel_hi:[1,0]
	v_pk_mul_f32 v[58:59], v[58:59], v[34:35] op_sel_hi:[1,0]
	v_pk_mul_f32 v[56:57], v[56:57], v[34:35] op_sel_hi:[1,0]
	v_pk_mul_f32 v[54:55], v[54:55], v[34:35] op_sel_hi:[1,0]
	v_pk_mul_f32 v[52:53], v[52:53], v[34:35] op_sel_hi:[1,0]
	v_pk_mul_f32 v[50:51], v[50:51], v[34:35] op_sel_hi:[1,0]
	v_pk_mul_f32 v[48:49], v[48:49], v[34:35] op_sel_hi:[1,0]
	v_pk_mul_f32 v[46:47], v[46:47], v[34:35] op_sel_hi:[1,0]
	v_pk_mul_f32 v[44:45], v[44:45], v[34:35] op_sel_hi:[1,0]
	v_pk_mul_f32 v[42:43], v[42:43], v[34:35] op_sel_hi:[1,0]
	v_pk_mul_f32 v[40:41], v[40:41], v[34:35] op_sel_hi:[1,0]
	v_pk_mul_f32 v[38:39], v[38:39], v[34:35] op_sel_hi:[1,0]
	v_pk_mul_f32 v[36:37], v[36:37], v[34:35] op_sel_hi:[1,0]

; template <bool SLC, bool NOMASK> ...
;     ...
;     const int pos0 = SLC ? (dcur & 0xfffff) : dcur;
;     const int lo = SLC ? ((((dcur >> 20) == qi) | ((dcur >> 20) == 4)) ? 0 : (1 << 30)) : lo_in;
;     load_frag8(nxt, KF, VF, SLC ? (dnext & 0xfffff) : dnext, lane);
;     f32x4 sa[2] = {(f32x4){0.f, 0.f, 0.f, 0.f}, (f32x4){0.f, 0.f, 0.f, 0.f}};
; #pragma unroll
;     for (int T = 0; T < 2; ++T)
; #pragma unroll
;         for (int s2 = 0; s2 < 4; ++s2) sa[T] = __builtin_amdgcn_mfma_f32_16x16x32_fp8_fp8(cur.k[T][s2], qf[s2], sa[T], 0, 0, 0);
;     float sc[8]; bool vd[8]; float mx = -1e30f;
;     const bool act = lo == 0 || !SLC;
;     if (NOMASK) {
; #pragma unroll
;         for (int j = 0; j < 8; ++j) { sc[j] = sa[j >> 2][j & 3]; vd[j] = act; }
;         mx = fmaxf(fmaxf(fmaxf(sc[0], sc[1]), fmaxf(sc[2], sc[3])), fmaxf(fmaxf(sc[4], sc[5]), fmaxf(sc[6], sc[7])));
;         mx = act ? mx : -1e30f;
;     } else {
; #pragma unroll
;         for (int T = 0; T < 2; ++T)
; #pragma unroll
;             for (int r = 0; r < 4; ++r) { const int p = pos0 + 16 * T + 4 * kq + r; const bool v = (p >= lo) & (p <= hi); const float x = sa[T][r];
;                 sc[4 * T + r] = x; vd[4 * T + r] = v; mx = v ? fmaxf(mx, x) : mx; }
;     }
;     if (__builtin_amdgcn_ballot_w64(mx > st.m + 4.f) != 0ull) {
;         mx = fmaxf(mx, __shfl_xor(mx, 16)); mx = fmaxf(mx, __shfl_xor(mx, 32));
;         const float mn = fmaxf(st.m, mx), alpha = __builtin_amdgcn_exp2f(st.m - mn); st.m = mn; st.l *= alpha;
; #pragma unroll
;         for (int j = 0; j < 8; ++j) st.o[j] = st.o[j] * alpha;
;     }
.LBB0_870:
	s_cmp_eq_u32 s12, 4
	s_cselect_b64 s[10:11], -1, 0
	s_lshl_b32 s13, s66, 7
	s_and_b32 s50, s13, 0x7fff800
	v_lshl_add_u64 v[10:11], v[86:87], 0, s[50:51]
	s_and_b32 s50, s13, 0x7fff000
	v_lshl_add_u64 v[244:245], v[10:11], 0, v[118:119]
	global_load_dwordx4 v[186:189], v[244:245], off
	global_load_dwordx4 v[190:193], v[244:245], off offset:1024
	global_load_dwordx4 v[194:197], v[244:245], off offset:2048
	global_load_dwordx4 v[198:201], v[244:245], off offset:3072
	v_lshl_add_u64 v[10:11], v[88:89], 0, s[50:51]
	v_lshl_add_u64 v[246:247], v[10:11], 0, v[118:119]
	global_load_dwordx4 v[170:173], v[246:247], off
	global_load_dwordx4 v[174:177], v[246:247], off offset:1024
	global_load_dwordx4 v[178:181], v[246:247], off offset:2048
	global_load_dwordx4 v[182:185], v[246:247], off offset:3072
	s_waitcnt vmcnt(20)
	v_mfma_f32_16x16x128_f8f6f4 v[2:5], v[138:145], v[78:85], 0
	s_and_b32 s13, s59, 0xfffff
	v_cmp_eq_u32_e32 vcc, s12, v209
	v_add_u32_e32 v0, s13, v211
	v_mfma_f32_16x16x128_f8f6f4 v[6:9], v[146:153], v[78:85], 0
	s_or_b64 s[18:19], s[10:11], vcc
	v_cmp_le_i32_e32 vcc, v0, v132
	s_and_b64 s[16:17], s[18:19], vcc
	v_cmp_lt_i32_e32 vcc, v0, v132
	s_and_b64 s[12:13], s[18:19], vcc
	s_nop 5
	v_max_f32_e32 v10, v2, v2
	v_max_f32_e32 v10, 0xf149f2ca, v10
	v_cndmask_b32_e64 v10, v223, v10, s[16:17]
	v_max_f32_e32 v11, v3, v3
	v_max_f32_e32 v11, v10, v11
	v_cndmask_b32_e64 v10, v10, v11, s[12:13]
	v_add_u32_e32 v11, 2, v0
	v_cmp_le_i32_e32 vcc, v11, v132
	v_max_f32_e32 v11, v4, v4
	v_max_f32_e32 v11, v10, v11
	s_and_b64 s[14:15], s[18:19], vcc
	v_cndmask_b32_e64 v10, v10, v11, s[14:15]
	v_add_u32_e32 v11, 3, v0
	v_cmp_le_i32_e32 vcc, v11, v132
	v_max_f32_e32 v11, v5, v5
	v_max_f32_e32 v11, v10, v11
	s_and_b64 s[10:11], s[18:19], vcc
	v_cndmask_b32_e64 v10, v10, v11, s[10:11]
	v_add_u32_e32 v11, 16, v0
	v_cmp_le_i32_e32 vcc, v11, v132
	v_max_f32_e32 v11, v6, v6
	v_max_f32_e32 v11, v10, v11
	s_and_b64 s[24:25], s[18:19], vcc
	v_cndmask_b32_e64 v10, v10, v11, s[24:25]
	v_add_u32_e32 v11, 17, v0
	v_cmp_le_i32_e32 vcc, v11, v132
	v_max_f32_e32 v11, v10, v10
	v_max_f32_e32 v12, v7, v7
	v_max_f32_e32 v11, v11, v12
	s_and_b64 s[20:21], s[18:19], vcc
	v_cndmask_b32_e64 v10, v10, v11, s[20:21]
	v_add_u32_e32 v11, 18, v0
	v_cmp_le_i32_e32 vcc, v11, v132
	v_max_f32_e32 v11, v10, v10
	v_max_f32_e32 v12, v8, v8
	v_max_f32_e32 v11, v11, v12
	s_and_b64 s[22:23], s[18:19], vcc
	v_cndmask_b32_e64 v10, v10, v11, s[22:23]
	v_add_u32_e32 v0, 19, v0
	v_cmp_le_i32_e32 vcc, v0, v132
	v_max_f32_e32 v0, v10, v10
	v_max_f32_e32 v11, v9, v9
	v_max_f32_e32 v0, v0, v11
	s_and_b64 s[18:19], s[18:19], vcc
	v_cndmask_b32_e64 v0, v10, v0, s[18:19]
	v_cmp_gt_f32_e32 vcc, v0, v204
	s_cbranch_vccz .LBB0_872
	ds_bpermute_b32 v10, v227, v0
	v_max_f32_e32 v0, v0, v0
	s_waitcnt lgkmcnt(0)
	v_max_f32_e32 v10, v10, v10
	v_max_f32_e32 v0, v0, v10
	ds_bpermute_b32 v10, v226, v0
	s_waitcnt lgkmcnt(0)
	v_max3_f32 v10, v202, v0, v10
	v_sub_f32_e32 v0, v202, v10
	v_exp_f32_e32 v0, v0
	v_mov_b32_e32 v202, v10
	v_mul_f32_e32 v203, v203, v0
	v_pk_mul_f32 v[66:67], v[66:67], v[0:1] op_sel_hi:[1,0]
	v_pk_mul_f32 v[64:65], v[64:65], v[0:1] op_sel_hi:[1,0]
	v_pk_mul_f32 v[62:63], v[62:63], v[0:1] op_sel_hi:[1,0]
	v_pk_mul_f32 v[60:61], v[60:61], v[0:1] op_sel_hi:[1,0]
	v_pk_mul_f32 v[58:59], v[58:59], v[0:1] op_sel_hi:[1,0]
	v_pk_mul_f32 v[56:57], v[56:57], v[0:1] op_sel_hi:[1,0]
	v_pk_mul_f32 v[54:55], v[54:55], v[0:1] op_sel_hi:[1,0]
	v_pk_mul_f32 v[52:53], v[52:53], v[0:1] op_sel_hi:[1,0]
	v_pk_mul_f32 v[50:51], v[50:51], v[0:1] op_sel_hi:[1,0]
	v_pk_mul_f32 v[48:49], v[48:49], v[0:1] op_sel_hi:[1,0]
	v_pk_mul_f32 v[46:47], v[46:47], v[0:1] op_sel_hi:[1,0]
	v_pk_mul_f32 v[44:45], v[44:45], v[0:1] op_sel_hi:[1,0]
	v_pk_mul_f32 v[42:43], v[42:43], v[0:1] op_sel_hi:[1,0]
	v_pk_mul_f32 v[40:41], v[40:41], v[0:1] op_sel_hi:[1,0]
	v_pk_mul_f32 v[38:39], v[38:39], v[0:1] op_sel_hi:[1,0]
	v_pk_mul_f32 v[36:37], v[36:37], v[0:1] op_sel_hi:[1,0]

; template <bool SLC, bool NOMASK> ...
;     ...
;     const int pos0 = SLC ? (dcur & 0xfffff) : dcur;
;     const int lo = SLC ? ((((dcur >> 20) == qi) | ((dcur >> 20) == 4)) ? 0 : (1 << 30)) : lo_in;
;     load_frag8(nxt, KF, VF, SLC ? (dnext & 0xfffff) : dnext, lane);
;     f32x4 sa[2] = {(f32x4){0.f, 0.f, 0.f, 0.f}, (f32x4){0.f, 0.f, 0.f, 0.f}};
; #pragma unroll
;     for (int T = 0; T < 2; ++T)
; #pragma unroll
;         for (int s2 = 0; s2 < 4; ++s2) sa[T] = __builtin_amdgcn_mfma_f32_16x16x32_fp8_fp8(cur.k[T][s2], qf[s2], sa[T], 0, 0, 0);
;     float sc[8]; bool vd[8]; float mx = -1e30f;
;     const bool act = lo == 0 || !SLC;
;     if (NOMASK) {
; #pragma unroll
;         for (int j = 0; j < 8; ++j) { sc[j] = sa[j >> 2][j & 3]; vd[j] = act; }
;         mx = fmaxf(fmaxf(fmaxf(sc[0], sc[1]), fmaxf(sc[2], sc[3])), fmaxf(fmaxf(sc[4], sc[5]), fmaxf(sc[6], sc[7])));
;         mx = act ? mx : -1e30f;
;     } else {
; #pragma unroll
;         for (int T = 0; T < 2; ++T)
; #pragma unroll
;             for (int r = 0; r < 4; ++r) { const int p = pos0 + 16 * T + 4 * kq + r; const bool v = (p >= lo) & (p <= hi); const float x = sa[T][r];
;                 sc[4 * T + r] = x; vd[4 * T + r] = v; mx = v ? fmaxf(mx, x) : mx; }
;     }
;     if (__builtin_amdgcn_ballot_w64(mx > st.m + 4.f) != 0ull) {
;         mx = fmaxf(mx, __shfl_xor(mx, 16)); mx = fmaxf(mx, __shfl_xor(mx, 32));
;         const float mn = fmaxf(st.m, mx), alpha = __builtin_amdgcn_exp2f(st.m - mn); st.m = mn; st.l *= alpha;
; #pragma unroll
;         for (int j = 0; j < 8; ++j) st.o[j] = st.o[j] * alpha;
;     }
.LBB0_874:
	s_and_b32 s13, s12, 0xfffffbff
	s_cmp_eq_u32 s13, 4
	s_cselect_b64 s[10:11], -1, 0
	s_lshl_b32 s14, s59, 7
	s_and_b32 s50, s14, 0x7fff800
	v_lshl_add_u64 v[44:45], v[86:87], 0, s[50:51]
	s_and_b32 s50, s14, 0x7fff000
	v_lshl_add_u64 v[244:245], v[44:45], 0, v[118:119]
	global_load_dwordx4 v[138:141], v[244:245], off
	global_load_dwordx4 v[142:145], v[244:245], off offset:1024
	global_load_dwordx4 v[146:149], v[244:245], off offset:2048
	global_load_dwordx4 v[150:153], v[244:245], off offset:3072
	v_lshl_add_u64 v[44:45], v[88:89], 0, s[50:51]
	v_lshl_add_u64 v[246:247], v[44:45], 0, v[118:119]
	global_load_dwordx4 v[90:93], v[246:247], off
	global_load_dwordx4 v[94:97], v[246:247], off offset:1024
	global_load_dwordx4 v[98:101], v[246:247], off offset:2048
	global_load_dwordx4 v[102:105], v[246:247], off offset:3072
	s_waitcnt vmcnt(20)
	v_mfma_f32_16x16x128_f8f6f4 v[36:39], v[154:161], v[78:85], 0
	v_cmp_eq_u32_e32 vcc, s13, v209
	s_or_b64 s[10:11], s[10:11], vcc
	v_mfma_f32_16x16x128_f8f6f4 v[40:43], v[162:169], v[78:85], 0
	v_mov_b32_e32 v203, v0
	s_nop 7
	v_max_f32_e32 v3, v37, v37
	v_max_f32_e32 v44, v36, v36
	v_max_f32_e32 v3, v44, v3
	v_max_f32_e32 v44, v39, v39
	v_max_f32_e32 v45, v38, v38
	v_max_f32_e32 v44, v45, v44
	v_max_f32_e32 v45, v43, v43
	v_max_f32_e32 v46, v42, v42
	v_max_f32_e32 v45, v46, v45
	v_max3_f32 v45, v40, v41, v45
	v_max3_f32 v3, v3, v44, v45
	v_cndmask_b32_e64 v202, v223, v3, s[10:11]
	v_cmp_gt_f32_e32 vcc, v202, v2
	v_mov_b32_e32 v3, v133
	s_cbranch_vccz .LBB0_876
	ds_bpermute_b32 v3, v227, v202
	v_max_f32_e32 v44, v202, v202
	s_waitcnt lgkmcnt(0)
	v_max_f32_e32 v3, v3, v3
	v_max_f32_e32 v3, v44, v3
	ds_bpermute_b32 v44, v226, v3
	s_waitcnt lgkmcnt(0)
	v_max3_f32 v203, v0, v3, v44
	v_sub_f32_e32 v3, v0, v203
	v_exp_f32_e32 v72, v3
	s_nop 0
	v_mul_f32_e32 v3, v133, v72
	v_pk_mul_f32 v[10:11], v[10:11], v[72:73] op_sel_hi:[1,0]
	v_pk_mul_f32 v[8:9], v[8:9], v[72:73] op_sel_hi:[1,0]
	v_pk_mul_f32 v[14:15], v[14:15], v[72:73] op_sel_hi:[1,0]
	v_pk_mul_f32 v[12:13], v[12:13], v[72:73] op_sel_hi:[1,0]
	v_pk_mul_f32 v[18:19], v[18:19], v[72:73] op_sel_hi:[1,0]
	v_pk_mul_f32 v[16:17], v[16:17], v[72:73] op_sel_hi:[1,0]
	v_pk_mul_f32 v[22:23], v[22:23], v[72:73] op_sel_hi:[1,0]
	v_pk_mul_f32 v[20:21], v[20:21], v[72:73] op_sel_hi:[1,0]
	v_pk_mul_f32 v[26:27], v[26:27], v[72:73] op_sel_hi:[1,0]
	v_pk_mul_f32 v[24:25], v[24:25], v[72:73] op_sel_hi:[1,0]
	v_pk_mul_f32 v[34:35], v[34:35], v[72:73] op_sel_hi:[1,0]
	v_pk_mul_f32 v[32:33], v[32:33], v[72:73] op_sel_hi:[1,0]
	v_pk_mul_f32 v[30:31], v[30:31], v[72:73] op_sel_hi:[1,0]
	v_pk_mul_f32 v[28:29], v[28:29], v[72:73] op_sel_hi:[1,0]
	v_pk_mul_f32 v[6:7], v[6:7], v[72:73] op_sel_hi:[1,0]
	v_pk_mul_f32 v[4:5], v[4:5], v[72:73] op_sel_hi:[1,0]

; template <bool SLC, bool NOMASK> ...
;     ...
;     const int pos0 = SLC ? (dcur & 0xfffff) : dcur;
;     const int lo = SLC ? ((((dcur >> 20) == qi) | ((dcur >> 20) == 4)) ? 0 : (1 << 30)) : lo_in;
;     load_frag8(nxt, KF, VF, SLC ? (dnext & 0xfffff) : dnext, lane);
;     f32x4 sa[2] = {(f32x4){0.f, 0.f, 0.f, 0.f}, (f32x4){0.f, 0.f, 0.f, 0.f}};
; #pragma unroll
;     for (int T = 0; T < 2; ++T)
; #pragma unroll
;         for (int s2 = 0; s2 < 4; ++s2) sa[T] = __builtin_amdgcn_mfma_f32_16x16x32_fp8_fp8(cur.k[T][s2], qf[s2], sa[T], 0, 0, 0);
;     float sc[8]; bool vd[8]; float mx = -1e30f;
;     const bool act = lo == 0 || !SLC;
;     if (NOMASK) {
; #pragma unroll
;         for (int j = 0; j < 8; ++j) { sc[j] = sa[j >> 2][j & 3]; vd[j] = act; }
;         mx = fmaxf(fmaxf(fmaxf(sc[0], sc[1]), fmaxf(sc[2], sc[3])), fmaxf(fmaxf(sc[4], sc[5]), fmaxf(sc[6], sc[7])));
;         mx = act ? mx : -1e30f;
;     } else {
; #pragma unroll
;         for (int T = 0; T < 2; ++T)
; #pragma unroll
;             for (int r = 0; r < 4; ++r) { const int p = pos0 + 16 * T + 4 * kq + r; const bool v = (p >= lo) & (p <= hi); const float x = sa[T][r];
;                 sc[4 * T + r] = x; vd[4 * T + r] = v; mx = v ? fmaxf(mx, x) : mx; }
;     }
;     if (__builtin_amdgcn_ballot_w64(mx > st.m + 4.f) != 0ull) {
;         mx = fmaxf(mx, __shfl_xor(mx, 16)); mx = fmaxf(mx, __shfl_xor(mx, 32));
;         const float mn = fmaxf(st.m, mx), alpha = __builtin_amdgcn_exp2f(st.m - mn); st.m = mn; st.l *= alpha;
; #pragma unroll
;         for (int j = 0; j < 8; ++j) st.o[j] = st.o[j] * alpha;
;     }
.LBB0_877:
	s_cmp_eq_u32 s12, 4
	s_cselect_b64 s[10:11], -1, 0
	s_lshl_b32 s13, s59, 7
	s_and_b32 s50, s13, 0x7fff800
	v_lshl_add_u64 v[44:45], v[86:87], 0, s[50:51]
	s_and_b32 s50, s13, 0x7fff000
	v_lshl_add_u64 v[244:245], v[44:45], 0, v[118:119]
	global_load_dwordx4 v[138:141], v[244:245], off
	global_load_dwordx4 v[142:145], v[244:245], off offset:1024
	global_load_dwordx4 v[146:149], v[244:245], off offset:2048
	global_load_dwordx4 v[150:153], v[244:245], off offset:3072
	v_lshl_add_u64 v[44:45], v[88:89], 0, s[50:51]
	v_lshl_add_u64 v[246:247], v[44:45], 0, v[118:119]
	global_load_dwordx4 v[90:93], v[246:247], off
	global_load_dwordx4 v[94:97], v[246:247], off offset:1024
	global_load_dwordx4 v[98:101], v[246:247], off offset:2048
	global_load_dwordx4 v[102:105], v[246:247], off offset:3072
	s_waitcnt vmcnt(20)
	v_mfma_f32_16x16x128_f8f6f4 v[36:39], v[154:161], v[78:85], 0
	s_and_b32 s13, s97, 0xfffff
	v_cmp_eq_u32_e32 vcc, s12, v209
	v_add_u32_e32 v3, s13, v211
	v_mfma_f32_16x16x128_f8f6f4 v[40:43], v[162:169], v[78:85], 0
	s_or_b64 s[18:19], s[10:11], vcc
	v_cmp_le_i32_e32 vcc, v3, v132
	s_and_b64 s[16:17], s[18:19], vcc
	v_cmp_lt_i32_e32 vcc, v3, v132
	s_and_b64 s[12:13], s[18:19], vcc
	s_nop 5
	v_max_f32_e32 v44, v36, v36
	v_max_f32_e32 v44, 0xf149f2ca, v44
	v_cndmask_b32_e64 v44, v223, v44, s[16:17]
	v_max_f32_e32 v45, v37, v37
	v_max_f32_e32 v45, v44, v45
	v_cndmask_b32_e64 v44, v44, v45, s[12:13]
	v_add_u32_e32 v45, 2, v3
	v_cmp_le_i32_e32 vcc, v45, v132
	v_max_f32_e32 v45, v38, v38
	v_max_f32_e32 v45, v44, v45
	s_and_b64 s[14:15], s[18:19], vcc
	v_cndmask_b32_e64 v44, v44, v45, s[14:15]
	v_add_u32_e32 v45, 3, v3
	v_cmp_le_i32_e32 vcc, v45, v132
	v_max_f32_e32 v45, v39, v39
	v_max_f32_e32 v45, v44, v45
	s_and_b64 s[10:11], s[18:19], vcc
	v_cndmask_b32_e64 v44, v44, v45, s[10:11]
	v_add_u32_e32 v45, 16, v3
	v_cmp_le_i32_e32 vcc, v45, v132
	v_max_f32_e32 v45, v40, v40
	v_max_f32_e32 v45, v44, v45
	s_and_b64 s[24:25], s[18:19], vcc
	v_cndmask_b32_e64 v44, v44, v45, s[24:25]
	v_add_u32_e32 v45, 17, v3
	v_cmp_le_i32_e32 vcc, v45, v132
	v_max_f32_e32 v45, v44, v44
	v_max_f32_e32 v46, v41, v41
	v_max_f32_e32 v45, v45, v46
	s_and_b64 s[20:21], s[18:19], vcc
	v_cndmask_b32_e64 v44, v44, v45, s[20:21]
	v_add_u32_e32 v45, 18, v3
	v_cmp_le_i32_e32 vcc, v45, v132
	v_max_f32_e32 v45, v44, v44
	v_max_f32_e32 v46, v42, v42
	v_max_f32_e32 v45, v45, v46
	s_and_b64 s[22:23], s[18:19], vcc
	v_cndmask_b32_e64 v44, v44, v45, s[22:23]
	v_add_u32_e32 v3, 19, v3
	v_cmp_le_i32_e32 vcc, v3, v132
	v_max_f32_e32 v3, v44, v44
	v_max_f32_e32 v45, v43, v43
	v_max_f32_e32 v3, v3, v45
	s_and_b64 s[18:19], s[18:19], vcc
	v_cndmask_b32_e64 v3, v44, v3, s[18:19]
	v_cmp_gt_f32_e32 vcc, v3, v2
	s_cbranch_vccz .LBB0_879
	ds_bpermute_b32 v2, v227, v3
	v_max_f32_e32 v3, v3, v3
	s_waitcnt lgkmcnt(0)
	v_max_f32_e32 v2, v2, v2
	v_max_f32_e32 v2, v3, v2
	ds_bpermute_b32 v3, v226, v2
	s_waitcnt lgkmcnt(0)
	v_max3_f32 v2, v0, v2, v3
	v_sub_f32_e32 v0, v0, v2
	v_exp_f32_e32 v0, v0
	s_nop 0
	v_mul_f32_e32 v133, v133, v0
	v_pk_mul_f32 v[10:11], v[10:11], v[0:1] op_sel_hi:[1,0]
	v_pk_mul_f32 v[8:9], v[8:9], v[0:1] op_sel_hi:[1,0]
	v_pk_mul_f32 v[14:15], v[14:15], v[0:1] op_sel_hi:[1,0]
	v_pk_mul_f32 v[12:13], v[12:13], v[0:1] op_sel_hi:[1,0]
	v_pk_mul_f32 v[18:19], v[18:19], v[0:1] op_sel_hi:[1,0]
	v_pk_mul_f32 v[16:17], v[16:17], v[0:1] op_sel_hi:[1,0]
	v_pk_mul_f32 v[22:23], v[22:23], v[0:1] op_sel_hi:[1,0]
	v_pk_mul_f32 v[20:21], v[20:21], v[0:1] op_sel_hi:[1,0]
	v_pk_mul_f32 v[26:27], v[26:27], v[0:1] op_sel_hi:[1,0]
	v_pk_mul_f32 v[24:25], v[24:25], v[0:1] op_sel_hi:[1,0]
	v_pk_mul_f32 v[34:35], v[34:35], v[0:1] op_sel_hi:[1,0]
	v_pk_mul_f32 v[32:33], v[32:33], v[0:1] op_sel_hi:[1,0]
	v_pk_mul_f32 v[30:31], v[30:31], v[0:1] op_sel_hi:[1,0]
	v_pk_mul_f32 v[28:29], v[28:29], v[0:1] op_sel_hi:[1,0]
	v_pk_mul_f32 v[6:7], v[6:7], v[0:1] op_sel_hi:[1,0]
	v_pk_mul_f32 v[4:5], v[4:5], v[0:1] op_sel_hi:[1,0]
	v_mov_b32_e32 v0, v2

; template <bool SLC, bool NOMASK> ...
;     ...
;     const int pos0 = SLC ? (dcur & 0xfffff) : dcur;
;     const int lo = SLC ? ((((dcur >> 20) == qi) | ((dcur >> 20) == 4)) ? 0 : (1 << 30)) : lo_in;
;     load_frag8(nxt, KF, VF, SLC ? (dnext & 0xfffff) : dnext, lane);
;     f32x4 sa[2] = {(f32x4){0.f, 0.f, 0.f, 0.f}, (f32x4){0.f, 0.f, 0.f, 0.f}};
; #pragma unroll
;     for (int T = 0; T < 2; ++T)
; #pragma unroll
;         for (int s2 = 0; s2 < 4; ++s2) sa[T] = __builtin_amdgcn_mfma_f32_16x16x32_fp8_fp8(cur.k[T][s2], qf[s2], sa[T], 0, 0, 0);
;     float sc[8]; bool vd[8]; float mx = -1e30f;
;     const bool act = lo == 0 || !SLC;
;     if (NOMASK) {
; #pragma unroll
;         for (int j = 0; j < 8; ++j) { sc[j] = sa[j >> 2][j & 3]; vd[j] = act; }
;         mx = fmaxf(fmaxf(fmaxf(sc[0], sc[1]), fmaxf(sc[2], sc[3])), fmaxf(fmaxf(sc[4], sc[5]), fmaxf(sc[6], sc[7])));
;         mx = act ? mx : -1e30f;
;     } else {
; #pragma unroll
;         for (int T = 0; T < 2; ++T)
; #pragma unroll
;             for (int r = 0; r < 4; ++r) { const int p = pos0 + 16 * T + 4 * kq + r; const bool v = (p >= lo) & (p <= hi); const float x = sa[T][r];
;                 sc[4 * T + r] = x; vd[4 * T + r] = v; mx = v ? fmaxf(mx, x) : mx; }
;     }
;     if (__builtin_amdgcn_ballot_w64(mx > st.m + 4.f) != 0ull) {
;         mx = fmaxf(mx, __shfl_xor(mx, 16)); mx = fmaxf(mx, __shfl_xor(mx, 32));
;         const float mn = fmaxf(st.m, mx), alpha = __builtin_amdgcn_exp2f(st.m - mn); st.m = mn; st.l *= alpha;
; #pragma unroll
;         for (int j = 0; j < 8; ++j) st.o[j] = st.o[j] * alpha;
;     }
; template <bool SLC, class Desc>
; __device__ __forceinline__ void attn_run_frag8(const i64_t (&qf)[4], const unsigned char* __restrict__ KF, const unsigned char* __restrict__ VF, const Desc& desc, int n,
;                                                int lo_in, int hi, int qi, AState& st, int lane) {
;     ...
;     for (int i = 0; i < n; i += 3) {
;         const int d2 = desc(i + 2 < n ? i + 2 : n - 1);
;         F8_STEP(fa, fc, d0, d2);
;         if (i + 1 >= n) break;
;         const int d3 = desc(i + 3 < n ? i + 3 : n - 1);
;         F8_STEP(fb, fa, d1, d3);
;         if (i + 2 >= n) break;
;         const int d4 = desc(i + 4 < n ? i + 4 : n - 1);
;         F8_STEP(fc, fb, d2, d4);
.LBB0_880:
	s_cmp_lt_u32 s58, s56
	s_cselect_b32 s10, s58, s57
	s_lshl_b32 s10, s10, 2
	s_add_i32 s10, s3, s10
	v_mov_b32_e32 v0, s10
	ds_read_b32 v0, v0 offset:13632
	s_and_b32 s13, s66, 2.0
	s_ashr_i32 s12, s66, 20
	s_mov_b64 s[10:11], -1
	s_cmp_eq_u32 s13, 0
	s_waitcnt lgkmcnt(0)
	v_readfirstlane_b32 s97, v0
	v_add_f32_e32 v0, 4.0, v203
	s_cbranch_scc1 .LBB0_884
	s_and_b32 s13, s12, 0xfffffbff
	s_cmp_eq_u32 s13, 4
	s_cselect_b64 s[10:11], -1, 0
	s_lshl_b32 s14, s97, 7
	s_and_b32 s50, s14, 0x7fff800
	v_lshl_add_u64 v[10:11], v[86:87], 0, s[50:51]
	s_and_b32 s50, s14, 0x7fff000
	v_lshl_add_u64 v[244:245], v[10:11], 0, v[118:119]
	global_load_dwordx4 v[154:157], v[244:245], off
	global_load_dwordx4 v[158:161], v[244:245], off offset:1024
	global_load_dwordx4 v[162:165], v[244:245], off offset:2048
	global_load_dwordx4 v[166:169], v[244:245], off offset:3072
	v_lshl_add_u64 v[10:11], v[88:89], 0, s[50:51]
	v_lshl_add_u64 v[246:247], v[10:11], 0, v[118:119]
	global_load_dwordx4 v[106:109], v[246:247], off
	global_load_dwordx4 v[110:113], v[246:247], off offset:1024
	global_load_dwordx4 v[114:117], v[246:247], off offset:2048
	global_load_dwordx4 v[134:137], v[246:247], off offset:3072
	s_waitcnt vmcnt(20)
	v_mfma_f32_16x16x128_f8f6f4 v[2:5], v[186:193], v[78:85], 0
	v_cmp_eq_u32_e32 vcc, s13, v209
	s_or_b64 s[10:11], s[10:11], vcc
	v_mfma_f32_16x16x128_f8f6f4 v[6:9], v[194:201], v[78:85], 0
	v_mov_b32_e32 v202, v203
	v_mov_b32_e32 v133, v204
	s_nop 6
	v_max_f32_e32 v10, v3, v3
	v_max_f32_e32 v11, v2, v2
	v_max_f32_e32 v10, v11, v10
	v_max_f32_e32 v11, v5, v5
	v_max_f32_e32 v12, v4, v4
	v_max_f32_e32 v11, v12, v11
	v_max_f32_e32 v12, v9, v9
	v_max_f32_e32 v13, v8, v8
	v_max_f32_e32 v12, v13, v12
	v_max3_f32 v12, v6, v7, v12
	v_max3_f32 v10, v10, v11, v12
	v_cndmask_b32_e64 v34, v223, v10, s[10:11]
	v_cmp_gt_f32_e32 vcc, v34, v0
	s_cbranch_vccz .LBB0_883
	ds_bpermute_b32 v10, v227, v34
	v_max_f32_e32 v11, v34, v34
	s_waitcnt lgkmcnt(0)
	v_max_f32_e32 v10, v10, v10
	v_max_f32_e32 v10, v11, v10
	ds_bpermute_b32 v11, v226, v10
	s_waitcnt lgkmcnt(0)
	v_max3_f32 v202, v203, v10, v11
	v_sub_f32_e32 v10, v203, v202
	v_exp_f32_e32 v34, v10
	s_nop 0
	v_mul_f32_e32 v133, v204, v34
	v_pk_mul_f32 v[38:39], v[38:39], v[34:35] op_sel_hi:[1,0]
	v_pk_mul_f32 v[36:37], v[36:37], v[34:35] op_sel_hi:[1,0]
	v_pk_mul_f32 v[42:43], v[42:43], v[34:35] op_sel_hi:[1,0]
	v_pk_mul_f32 v[40:41], v[40:41], v[34:35] op_sel_hi:[1,0]
	v_pk_mul_f32 v[46:47], v[46:47], v[34:35] op_sel_hi:[1,0]
	v_pk_mul_f32 v[44:45], v[44:45], v[34:35] op_sel_hi:[1,0]
	v_pk_mul_f32 v[50:51], v[50:51], v[34:35] op_sel_hi:[1,0]
	v_pk_mul_f32 v[48:49], v[48:49], v[34:35] op_sel_hi:[1,0]
	v_pk_mul_f32 v[54:55], v[54:55], v[34:35] op_sel_hi:[1,0]
	v_pk_mul_f32 v[52:53], v[52:53], v[34:35] op_sel_hi:[1,0]
	v_pk_mul_f32 v[58:59], v[58:59], v[34:35] op_sel_hi:[1,0]
	v_pk_mul_f32 v[56:57], v[56:57], v[34:35] op_sel_hi:[1,0]
	v_pk_mul_f32 v[62:63], v[62:63], v[34:35] op_sel_hi:[1,0]
	v_pk_mul_f32 v[60:61], v[60:61], v[34:35] op_sel_hi:[1,0]
	v_pk_mul_f32 v[66:67], v[66:67], v[34:35] op_sel_hi:[1,0]
	v_pk_mul_f32 v[64:65], v[64:65], v[34:35] op_sel_hi:[1,0]

; template <bool SLC, bool NOMASK> ...
;     ...
;     const int pos0 = SLC ? (dcur & 0xfffff) : dcur;
;     const int lo = SLC ? ((((dcur >> 20) == qi) | ((dcur >> 20) == 4)) ? 0 : (1 << 30)) : lo_in;
;     load_frag8(nxt, KF, VF, SLC ? (dnext & 0xfffff) : dnext, lane);
;     f32x4 sa[2] = {(f32x4){0.f, 0.f, 0.f, 0.f}, (f32x4){0.f, 0.f, 0.f, 0.f}};
; #pragma unroll
;     for (int T = 0; T < 2; ++T)
; #pragma unroll
;         for (int s2 = 0; s2 < 4; ++s2) sa[T] = __builtin_amdgcn_mfma_f32_16x16x32_fp8_fp8(cur.k[T][s2], qf[s2], sa[T], 0, 0, 0);
;     float sc[8]; bool vd[8]; float mx = -1e30f;
;     const bool act = lo == 0 || !SLC;
;     if (NOMASK) {
; #pragma unroll
;         for (int j = 0; j < 8; ++j) { sc[j] = sa[j >> 2][j & 3]; vd[j] = act; }
;         mx = fmaxf(fmaxf(fmaxf(sc[0], sc[1]), fmaxf(sc[2], sc[3])), fmaxf(fmaxf(sc[4], sc[5]), fmaxf(sc[6], sc[7])));
;         mx = act ? mx : -1e30f;
;     } else {
; #pragma unroll
;         for (int T = 0; T < 2; ++T)
; #pragma unroll
;             for (int r = 0; r < 4; ++r) { const int p = pos0 + 16 * T + 4 * kq + r; const bool v = (p >= lo) & (p <= hi); const float x = sa[T][r];
;                 sc[4 * T + r] = x; vd[4 * T + r] = v; mx = v ? fmaxf(mx, x) : mx; }
;     }
;     if (__builtin_amdgcn_ballot_w64(mx > st.m + 4.f) != 0ull) {
;         mx = fmaxf(mx, __shfl_xor(mx, 16)); mx = fmaxf(mx, __shfl_xor(mx, 32));
;         const float mn = fmaxf(st.m, mx), alpha = __builtin_amdgcn_exp2f(st.m - mn); st.m = mn; st.l *= alpha;
; #pragma unroll
;         for (int j = 0; j < 8; ++j) st.o[j] = st.o[j] * alpha;
;     }
.LBB0_884:
	s_and_b64 vcc, exec, s[10:11]
	s_cbranch_vccz .LBB0_888
	s_cmp_eq_u32 s12, 4
	s_cselect_b64 s[10:11], -1, 0
	s_lshl_b32 s13, s97, 7
	s_and_b32 s50, s13, 0x7fff800
	v_lshl_add_u64 v[10:11], v[86:87], 0, s[50:51]
	s_and_b32 s50, s13, 0x7fff000
	v_lshl_add_u64 v[244:245], v[10:11], 0, v[118:119]
	global_load_dwordx4 v[154:157], v[244:245], off
	global_load_dwordx4 v[158:161], v[244:245], off offset:1024
	global_load_dwordx4 v[162:165], v[244:245], off offset:2048
	global_load_dwordx4 v[166:169], v[244:245], off offset:3072
	v_lshl_add_u64 v[10:11], v[88:89], 0, s[50:51]
	v_lshl_add_u64 v[246:247], v[10:11], 0, v[118:119]
	global_load_dwordx4 v[106:109], v[246:247], off
	global_load_dwordx4 v[110:113], v[246:247], off offset:1024
	global_load_dwordx4 v[114:117], v[246:247], off offset:2048
	global_load_dwordx4 v[134:137], v[246:247], off offset:3072
	s_waitcnt vmcnt(20)
	v_mfma_f32_16x16x128_f8f6f4 v[2:5], v[186:193], v[78:85], 0
	s_and_b32 s13, s66, 0xfffff
	v_cmp_eq_u32_e32 vcc, s12, v209
	v_add_u32_e32 v10, s13, v211
	v_mfma_f32_16x16x128_f8f6f4 v[6:9], v[194:201], v[78:85], 0
	s_or_b64 s[18:19], s[10:11], vcc
	v_cmp_le_i32_e32 vcc, v10, v132
	s_and_b64 s[16:17], s[18:19], vcc
	v_cmp_lt_i32_e32 vcc, v10, v132
	s_and_b64 s[12:13], s[18:19], vcc
	s_nop 5
	v_max_f32_e32 v11, v2, v2
	v_max_f32_e32 v11, 0xf149f2ca, v11
	v_cndmask_b32_e64 v11, v223, v11, s[16:17]
	v_max_f32_e32 v12, v3, v3
	v_max_f32_e32 v12, v11, v12
	v_cndmask_b32_e64 v11, v11, v12, s[12:13]
	v_add_u32_e32 v12, 2, v10
	v_cmp_le_i32_e32 vcc, v12, v132
	v_max_f32_e32 v12, v4, v4
	v_max_f32_e32 v12, v11, v12
	s_and_b64 s[14:15], s[18:19], vcc
	v_cndmask_b32_e64 v11, v11, v12, s[14:15]
	v_add_u32_e32 v12, 3, v10
	v_cmp_le_i32_e32 vcc, v12, v132
	v_max_f32_e32 v12, v5, v5
	v_max_f32_e32 v12, v11, v12
	s_and_b64 s[10:11], s[18:19], vcc
	v_cndmask_b32_e64 v11, v11, v12, s[10:11]
	v_add_u32_e32 v12, 16, v10
	v_cmp_le_i32_e32 vcc, v12, v132
	v_max_f32_e32 v12, v6, v6
	v_max_f32_e32 v12, v11, v12
	s_and_b64 s[24:25], s[18:19], vcc
	v_cndmask_b32_e64 v11, v11, v12, s[24:25]
	v_add_u32_e32 v12, 17, v10
	v_cmp_le_i32_e32 vcc, v12, v132
	v_max_f32_e32 v12, v11, v11
	v_max_f32_e32 v13, v7, v7
	v_max_f32_e32 v12, v12, v13
	s_and_b64 s[20:21], s[18:19], vcc
	v_cndmask_b32_e64 v11, v11, v12, s[20:21]
	v_add_u32_e32 v12, 18, v10
	v_cmp_le_i32_e32 vcc, v12, v132
	v_max_f32_e32 v12, v11, v11
	v_max_f32_e32 v13, v8, v8
	v_max_f32_e32 v12, v12, v13
	s_and_b64 s[22:23], s[18:19], vcc
	v_cndmask_b32_e64 v11, v11, v12, s[22:23]
	v_add_u32_e32 v10, 19, v10
	v_cmp_le_i32_e32 vcc, v10, v132
	v_max_f32_e32 v10, v11, v11
	v_max_f32_e32 v12, v9, v9
	v_max_f32_e32 v10, v10, v12
	s_and_b64 s[18:19], s[18:19], vcc
	v_cndmask_b32_e64 v10, v11, v10, s[18:19]
	v_cmp_gt_f32_e32 vcc, v10, v0
	s_cbranch_vccz .LBB0_887
	ds_bpermute_b32 v0, v227, v10
	v_max_f32_e32 v10, v10, v10
	s_waitcnt lgkmcnt(0)
	v_max_f32_e32 v0, v0, v0
	v_max_f32_e32 v0, v10, v0
	ds_bpermute_b32 v10, v226, v0
	s_waitcnt lgkmcnt(0)
	v_max3_f32 v10, v203, v0, v10
	v_sub_f32_e32 v0, v203, v10
	v_exp_f32_e32 v0, v0
	v_mov_b32_e32 v203, v10
	v_mul_f32_e32 v204, v204, v0
	v_pk_mul_f32 v[38:39], v[38:39], v[0:1] op_sel_hi:[1,0]
	v_pk_mul_f32 v[36:37], v[36:37], v[0:1] op_sel_hi:[1,0]
	v_pk_mul_f32 v[42:43], v[42:43], v[0:1] op_sel_hi:[1,0]
	v_pk_mul_f32 v[40:41], v[40:41], v[0:1] op_sel_hi:[1,0]
	v_pk_mul_f32 v[46:47], v[46:47], v[0:1] op_sel_hi:[1,0]
	v_pk_mul_f32 v[44:45], v[44:45], v[0:1] op_sel_hi:[1,0]
	v_pk_mul_f32 v[50:51], v[50:51], v[0:1] op_sel_hi:[1,0]
	v_pk_mul_f32 v[48:49], v[48:49], v[0:1] op_sel_hi:[1,0]
	v_pk_mul_f32 v[54:55], v[54:55], v[0:1] op_sel_hi:[1,0]
	v_pk_mul_f32 v[52:53], v[52:53], v[0:1] op_sel_hi:[1,0]
	v_pk_mul_f32 v[58:59], v[58:59], v[0:1] op_sel_hi:[1,0]
	v_pk_mul_f32 v[56:57], v[56:57], v[0:1] op_sel_hi:[1,0]
	v_pk_mul_f32 v[62:63], v[62:63], v[0:1] op_sel_hi:[1,0]
	v_pk_mul_f32 v[60:61], v[60:61], v[0:1] op_sel_hi:[1,0]
	v_pk_mul_f32 v[66:67], v[66:67], v[0:1] op_sel_hi:[1,0]
	v_pk_mul_f32 v[64:65], v[64:65], v[0:1] op_sel_hi:[1,0]

; template <bool SLC, bool NOMASK> ...
;     ...
;     load_frag8(nxt, KF, VF, SLC ? (dnext & 0xfffff) : dnext, lane);
;     f32x4 sa[2] = {(f32x4){0.f, 0.f, 0.f, 0.f}, (f32x4){0.f, 0.f, 0.f, 0.f}};
; #pragma unroll
;     for (int T = 0; T < 2; ++T)
; #pragma unroll
;         for (int s2 = 0; s2 < 4; ++s2) sa[T] = __builtin_amdgcn_mfma_f32_16x16x32_fp8_fp8(cur.k[T][s2], qf[s2], sa[T], 0, 0, 0);
;     float sc[8]; bool vd[8]; float mx = -1e30f;
;     const bool act = lo == 0 || !SLC;
;     if (NOMASK) {
; #pragma unroll
;         for (int j = 0; j < 8; ++j) { sc[j] = sa[j >> 2][j & 3]; vd[j] = act; }
;         mx = fmaxf(fmaxf(fmaxf(sc[0], sc[1]), fmaxf(sc[2], sc[3])), fmaxf(fmaxf(sc[4], sc[5]), fmaxf(sc[6], sc[7])));
;         mx = act ? mx : -1e30f;
;     } else {
; #pragma unroll
;         for (int T = 0; T < 2; ++T)
; #pragma unroll
;             for (int r = 0; r < 4; ++r) { const int p = pos0 + 16 * T + 4 * kq + r; const bool v = (p >= lo) & (p <= hi); const float x = sa[T][r];
;                 sc[4 * T + r] = x; vd[4 * T + r] = v; mx = v ? fmaxf(mx, x) : mx; }
;     }
;     if (__builtin_amdgcn_ballot_w64(mx > st.m + 4.f) != 0ull) {
;         mx = fmaxf(mx, __shfl_xor(mx, 16)); mx = fmaxf(mx, __shfl_xor(mx, 32));
;         const float mn = fmaxf(st.m, mx), alpha = __builtin_amdgcn_exp2f(st.m - mn); st.m = mn; st.l *= alpha;
; #pragma unroll
;         for (int j = 0; j < 8; ++j) st.o[j] = st.o[j] * alpha;
;     }
.LBB0_900:
	v_lshl_add_u64 v[244:245], v[204:205], 0, v[118:119]
	global_load_dwordx4 v[186:189], v[244:245], off
	global_load_dwordx4 v[190:193], v[244:245], off offset:1024
	global_load_dwordx4 v[194:197], v[244:245], off offset:2048
	global_load_dwordx4 v[198:201], v[244:245], off offset:3072
	v_lshl_add_u64 v[246:247], v[202:203], 0, v[118:119]
	global_load_dwordx4 v[170:173], v[246:247], off
	global_load_dwordx4 v[174:177], v[246:247], off offset:1024
	global_load_dwordx4 v[178:181], v[246:247], off offset:2048
	global_load_dwordx4 v[182:185], v[246:247], off offset:3072
	s_waitcnt vmcnt(20)
	v_mfma_f32_16x16x128_f8f6f4 v[2:5], v[138:145], v[78:85], 0
	v_mfma_f32_16x16x128_f8f6f4 v[6:9], v[146:153], v[78:85], 0
	v_mov_b32_e32 v229, v133
	v_mov_b32_e32 v34, v230
	s_nop 8
	v_max_f32_e32 v0, v3, v3
	v_max_f32_e32 v10, v2, v2
	v_max_f32_e32 v0, v10, v0
	v_max_f32_e32 v10, v5, v5
	v_max_f32_e32 v11, v4, v4
	v_max_f32_e32 v10, v11, v10
	v_max_f32_e32 v11, v9, v9
	v_max_f32_e32 v12, v8, v8
	v_max_f32_e32 v11, v12, v11
	v_max3_f32 v11, v6, v7, v11
	v_max3_f32 v0, v0, v10, v11
	v_cmp_gt_f32_e32 vcc, v0, v231
	s_cbranch_vccz .LBB0_902
	ds_bpermute_b32 v10, v227, v0
	v_max_f32_e32 v0, v0, v0
	s_waitcnt lgkmcnt(0)
	v_max_f32_e32 v10, v10, v10
	v_max_f32_e32 v0, v0, v10
	ds_bpermute_b32 v10, v226, v0
	s_waitcnt lgkmcnt(0)
	v_max3_f32 v229, v133, v0, v10
	v_sub_f32_e32 v0, v133, v229
	v_exp_f32_e32 v0, v0
	s_nop 0
	v_mul_f32_e32 v34, v230, v0
	v_pk_mul_f32 v[66:67], v[66:67], v[0:1] op_sel_hi:[1,0]
	v_pk_mul_f32 v[64:65], v[64:65], v[0:1] op_sel_hi:[1,0]
	v_pk_mul_f32 v[62:63], v[62:63], v[0:1] op_sel_hi:[1,0]
	v_pk_mul_f32 v[60:61], v[60:61], v[0:1] op_sel_hi:[1,0]
	v_pk_mul_f32 v[58:59], v[58:59], v[0:1] op_sel_hi:[1,0]
	v_pk_mul_f32 v[56:57], v[56:57], v[0:1] op_sel_hi:[1,0]
	v_pk_mul_f32 v[54:55], v[54:55], v[0:1] op_sel_hi:[1,0]
	v_pk_mul_f32 v[52:53], v[52:53], v[0:1] op_sel_hi:[1,0]
	v_pk_mul_f32 v[50:51], v[50:51], v[0:1] op_sel_hi:[1,0]
	v_pk_mul_f32 v[48:49], v[48:49], v[0:1] op_sel_hi:[1,0]
	v_pk_mul_f32 v[46:47], v[46:47], v[0:1] op_sel_hi:[1,0]
	v_pk_mul_f32 v[44:45], v[44:45], v[0:1] op_sel_hi:[1,0]
	v_pk_mul_f32 v[42:43], v[42:43], v[0:1] op_sel_hi:[1,0]
	v_pk_mul_f32 v[40:41], v[40:41], v[0:1] op_sel_hi:[1,0]
	v_pk_mul_f32 v[38:39], v[38:39], v[0:1] op_sel_hi:[1,0]
	v_pk_mul_f32 v[36:37], v[36:37], v[0:1] op_sel_hi:[1,0]

; template <bool SLC, bool NOMASK> ...
;     ...
;     load_frag8(nxt, KF, VF, SLC ? (dnext & 0xfffff) : dnext, lane);
;     f32x4 sa[2] = {(f32x4){0.f, 0.f, 0.f, 0.f}, (f32x4){0.f, 0.f, 0.f, 0.f}};
; #pragma unroll
;     for (int T = 0; T < 2; ++T)
; #pragma unroll
;         for (int s2 = 0; s2 < 4; ++s2) sa[T] = __builtin_amdgcn_mfma_f32_16x16x32_fp8_fp8(cur.k[T][s2], qf[s2], sa[T], 0, 0, 0);
;     float sc[8]; bool vd[8]; float mx = -1e30f;
;     const bool act = lo == 0 || !SLC;
;     if (NOMASK) {
; #pragma unroll
;         for (int j = 0; j < 8; ++j) { sc[j] = sa[j >> 2][j & 3]; vd[j] = act; }
;         mx = fmaxf(fmaxf(fmaxf(sc[0], sc[1]), fmaxf(sc[2], sc[3])), fmaxf(fmaxf(sc[4], sc[5]), fmaxf(sc[6], sc[7])));
;         mx = act ? mx : -1e30f;
;     } else {
; #pragma unroll
;         for (int T = 0; T < 2; ++T)
; #pragma unroll
;             for (int r = 0; r < 4; ++r) { const int p = pos0 + 16 * T + 4 * kq + r; const bool v = (p >= lo) & (p <= hi); const float x = sa[T][r];
;                 sc[4 * T + r] = x; vd[4 * T + r] = v; mx = v ? fmaxf(mx, x) : mx; }
;     }
;     if (__builtin_amdgcn_ballot_w64(mx > st.m + 4.f) != 0ull) {
;         mx = fmaxf(mx, __shfl_xor(mx, 16)); mx = fmaxf(mx, __shfl_xor(mx, 32));
;         const float mn = fmaxf(st.m, mx), alpha = __builtin_amdgcn_exp2f(st.m - mn); st.m = mn; st.l *= alpha;
; #pragma unroll
;         for (int j = 0; j < 8; ++j) st.o[j] = st.o[j] * alpha;
;     }
.LBB0_903:
	v_lshl_add_u64 v[244:245], v[204:205], 0, v[118:119]
	global_load_dwordx4 v[186:189], v[244:245], off
	global_load_dwordx4 v[190:193], v[244:245], off offset:1024
	global_load_dwordx4 v[194:197], v[244:245], off offset:2048
	global_load_dwordx4 v[198:201], v[244:245], off offset:3072
	v_lshl_add_u64 v[246:247], v[202:203], 0, v[118:119]
	global_load_dwordx4 v[170:173], v[246:247], off
	global_load_dwordx4 v[174:177], v[246:247], off offset:1024
	global_load_dwordx4 v[178:181], v[246:247], off offset:2048
	global_load_dwordx4 v[182:185], v[246:247], off offset:3072
	s_waitcnt vmcnt(20)
	v_mfma_f32_16x16x128_f8f6f4 v[2:5], v[138:145], v[78:85], 0
	v_add_u32_e32 v0, s14, v211
	v_cmp_ge_i32_e32 vcc, v0, v35
	v_cmp_le_i32_e64 s[10:11], v0, v132
	v_mfma_f32_16x16x128_f8f6f4 v[6:9], v[146:153], v[78:85], 0
	s_and_b64 s[16:17], vcc, s[10:11]
	v_add_u32_e32 v11, 1, v0
	v_cmp_ge_i32_e32 vcc, v11, v35
	v_cmp_lt_i32_e64 s[10:11], v0, v132
	s_and_b64 s[12:13], s[10:11], vcc
	s_nop 5
	v_max_f32_e32 v10, v2, v2
	v_max_f32_e32 v10, 0xf149f2ca, v10
	v_cndmask_b32_e64 v10, v223, v10, s[16:17]
	v_max_f32_e32 v11, v3, v3
	v_max_f32_e32 v11, v10, v11
	v_cndmask_b32_e64 v10, v10, v11, s[12:13]
	v_add_u32_e32 v11, 2, v0
	v_cmp_ge_i32_e32 vcc, v11, v35
	v_cmp_le_i32_e64 s[10:11], v11, v132
	v_max_f32_e32 v11, v4, v4
	v_max_f32_e32 v11, v10, v11
	s_and_b64 s[14:15], vcc, s[10:11]
	v_cndmask_b32_e64 v10, v10, v11, s[14:15]
	v_add_u32_e32 v11, 3, v0
	v_cmp_ge_i32_e32 vcc, v11, v35
	v_cmp_le_i32_e64 s[10:11], v11, v132
	v_max_f32_e32 v11, v5, v5
	v_max_f32_e32 v11, v10, v11
	s_and_b64 s[10:11], vcc, s[10:11]
	v_cndmask_b32_e64 v10, v10, v11, s[10:11]
	v_add_u32_e32 v11, 16, v0
	v_cmp_ge_i32_e32 vcc, v11, v35
	v_cmp_le_i32_e64 s[18:19], v11, v132
	v_max_f32_e32 v11, v6, v6
	v_max_f32_e32 v11, v10, v11
	s_and_b64 s[24:25], vcc, s[18:19]
	v_cndmask_b32_e64 v10, v10, v11, s[24:25]
	v_add_u32_e32 v11, 17, v0
	v_cmp_ge_i32_e32 vcc, v11, v35
	v_cmp_le_i32_e64 s[18:19], v11, v132
	v_max_f32_e32 v11, v10, v10
	v_max_f32_e32 v12, v7, v7
	v_max_f32_e32 v11, v11, v12
	s_and_b64 s[20:21], vcc, s[18:19]
	v_cndmask_b32_e64 v10, v10, v11, s[20:21]
	v_add_u32_e32 v11, 18, v0
	v_cmp_ge_i32_e32 vcc, v11, v35
	v_cmp_le_i32_e64 s[18:19], v11, v132
	v_max_f32_e32 v11, v10, v10
	v_max_f32_e32 v12, v8, v8
	v_max_f32_e32 v11, v11, v12
	s_and_b64 s[22:23], vcc, s[18:19]
	v_cndmask_b32_e64 v10, v10, v11, s[22:23]
	v_add_u32_e32 v0, 19, v0
	v_cmp_ge_i32_e32 vcc, v0, v35
	v_cmp_le_i32_e64 s[18:19], v0, v132
	v_max_f32_e32 v0, v10, v10
	v_max_f32_e32 v11, v9, v9
	v_max_f32_e32 v0, v0, v11
	s_and_b64 s[18:19], vcc, s[18:19]
	v_cndmask_b32_e64 v0, v10, v0, s[18:19]
	v_cmp_gt_f32_e32 vcc, v0, v231
	s_cbranch_vccz .LBB0_905
	ds_bpermute_b32 v10, v227, v0
	v_max_f32_e32 v0, v0, v0
	s_waitcnt lgkmcnt(0)
	v_max_f32_e32 v10, v10, v10
	v_max_f32_e32 v0, v0, v10
	ds_bpermute_b32 v10, v226, v0
	s_waitcnt lgkmcnt(0)
	v_max3_f32 v10, v133, v0, v10
	v_sub_f32_e32 v0, v133, v10
	v_exp_f32_e32 v0, v0
	v_mov_b32_e32 v133, v10
	v_mul_f32_e32 v230, v230, v0
	v_pk_mul_f32 v[66:67], v[66:67], v[0:1] op_sel_hi:[1,0]
	v_pk_mul_f32 v[64:65], v[64:65], v[0:1] op_sel_hi:[1,0]
	v_pk_mul_f32 v[62:63], v[62:63], v[0:1] op_sel_hi:[1,0]
	v_pk_mul_f32 v[60:61], v[60:61], v[0:1] op_sel_hi:[1,0]
	v_pk_mul_f32 v[58:59], v[58:59], v[0:1] op_sel_hi:[1,0]
	v_pk_mul_f32 v[56:57], v[56:57], v[0:1] op_sel_hi:[1,0]
	v_pk_mul_f32 v[54:55], v[54:55], v[0:1] op_sel_hi:[1,0]
	v_pk_mul_f32 v[52:53], v[52:53], v[0:1] op_sel_hi:[1,0]
	v_pk_mul_f32 v[50:51], v[50:51], v[0:1] op_sel_hi:[1,0]
	v_pk_mul_f32 v[48:49], v[48:49], v[0:1] op_sel_hi:[1,0]
	v_pk_mul_f32 v[46:47], v[46:47], v[0:1] op_sel_hi:[1,0]
	v_pk_mul_f32 v[44:45], v[44:45], v[0:1] op_sel_hi:[1,0]
	v_pk_mul_f32 v[42:43], v[42:43], v[0:1] op_sel_hi:[1,0]
	v_pk_mul_f32 v[40:41], v[40:41], v[0:1] op_sel_hi:[1,0]
	v_pk_mul_f32 v[38:39], v[38:39], v[0:1] op_sel_hi:[1,0]
	v_pk_mul_f32 v[36:37], v[36:37], v[0:1] op_sel_hi:[1,0]

; template <bool SLC, bool NOMASK> ...
;     ...
;     load_frag8(nxt, KF, VF, SLC ? (dnext & 0xfffff) : dnext, lane);
;     f32x4 sa[2] = {(f32x4){0.f, 0.f, 0.f, 0.f}, (f32x4){0.f, 0.f, 0.f, 0.f}};
; #pragma unroll
;     for (int T = 0; T < 2; ++T)
; #pragma unroll
;         for (int s2 = 0; s2 < 4; ++s2) sa[T] = __builtin_amdgcn_mfma_f32_16x16x32_fp8_fp8(cur.k[T][s2], qf[s2], sa[T], 0, 0, 0);
;     float sc[8]; bool vd[8]; float mx = -1e30f;
;     const bool act = lo == 0 || !SLC;
;     if (NOMASK) {
; #pragma unroll
;         for (int j = 0; j < 8; ++j) { sc[j] = sa[j >> 2][j & 3]; vd[j] = act; }
;         mx = fmaxf(fmaxf(fmaxf(sc[0], sc[1]), fmaxf(sc[2], sc[3])), fmaxf(fmaxf(sc[4], sc[5]), fmaxf(sc[6], sc[7])));
;         mx = act ? mx : -1e30f;
;     } else {
; #pragma unroll
;         for (int T = 0; T < 2; ++T)
; #pragma unroll
;             for (int r = 0; r < 4; ++r) { const int p = pos0 + 16 * T + 4 * kq + r; const bool v = (p >= lo) & (p <= hi); const float x = sa[T][r];
;                 sc[4 * T + r] = x; vd[4 * T + r] = v; mx = v ? fmaxf(mx, x) : mx; }
;     }
;     if (__builtin_amdgcn_ballot_w64(mx > st.m + 4.f) != 0ull) {
;         mx = fmaxf(mx, __shfl_xor(mx, 16)); mx = fmaxf(mx, __shfl_xor(mx, 32));
;         const float mn = fmaxf(st.m, mx), alpha = __builtin_amdgcn_exp2f(st.m - mn); st.m = mn; st.l *= alpha;
; #pragma unroll
;         for (int j = 0; j < 8; ++j) st.o[j] = st.o[j] * alpha;
;     }
.LBB0_907:
	v_lshl_add_u64 v[244:245], v[204:205], 0, v[118:119]
	global_load_dwordx4 v[138:141], v[244:245], off
	global_load_dwordx4 v[142:145], v[244:245], off offset:1024
	global_load_dwordx4 v[146:149], v[244:245], off offset:2048
	global_load_dwordx4 v[150:153], v[244:245], off offset:3072
	v_lshl_add_u64 v[246:247], v[202:203], 0, v[118:119]
	global_load_dwordx4 v[90:93], v[246:247], off
	global_load_dwordx4 v[94:97], v[246:247], off offset:1024
	global_load_dwordx4 v[98:101], v[246:247], off offset:2048
	global_load_dwordx4 v[102:105], v[246:247], off offset:3072
	s_waitcnt vmcnt(20)
	v_mfma_f32_16x16x128_f8f6f4 v[36:39], v[154:161], v[78:85], 0
	v_mfma_f32_16x16x128_f8f6f4 v[40:43], v[162:169], v[78:85], 0
	v_mov_b32_e32 v230, v229
	v_mov_b32_e32 v231, v34
	s_nop 8
	v_max_f32_e32 v0, v37, v37
	v_max_f32_e32 v44, v36, v36
	v_max_f32_e32 v0, v44, v0
	v_max_f32_e32 v44, v39, v39
	v_max_f32_e32 v45, v38, v38
	v_max_f32_e32 v44, v45, v44
	v_max_f32_e32 v45, v43, v43
	v_max_f32_e32 v46, v42, v42
	v_max_f32_e32 v45, v46, v45
	v_max3_f32 v45, v40, v41, v45
	v_max3_f32 v0, v0, v44, v45
	v_cmp_gt_f32_e32 vcc, v0, v133
	s_cbranch_vccz .LBB0_909
	ds_bpermute_b32 v44, v227, v0
	v_max_f32_e32 v0, v0, v0
	s_waitcnt lgkmcnt(0)
	v_max_f32_e32 v44, v44, v44
	v_max_f32_e32 v0, v0, v44
	ds_bpermute_b32 v44, v226, v0
	s_waitcnt lgkmcnt(0)
	v_max3_f32 v230, v229, v0, v44
	v_sub_f32_e32 v0, v229, v230
	v_exp_f32_e32 v0, v0
	s_nop 0
	v_mul_f32_e32 v231, v34, v0
	v_pk_mul_f32 v[8:9], v[8:9], v[0:1] op_sel_hi:[1,0]
	v_pk_mul_f32 v[6:7], v[6:7], v[0:1] op_sel_hi:[1,0]
	v_pk_mul_f32 v[12:13], v[12:13], v[0:1] op_sel_hi:[1,0]
	v_pk_mul_f32 v[10:11], v[10:11], v[0:1] op_sel_hi:[1,0]
	v_pk_mul_f32 v[16:17], v[16:17], v[0:1] op_sel_hi:[1,0]
	v_pk_mul_f32 v[14:15], v[14:15], v[0:1] op_sel_hi:[1,0]
	v_pk_mul_f32 v[20:21], v[20:21], v[0:1] op_sel_hi:[1,0]
	v_pk_mul_f32 v[18:19], v[18:19], v[0:1] op_sel_hi:[1,0]
	v_pk_mul_f32 v[24:25], v[24:25], v[0:1] op_sel_hi:[1,0]
	v_pk_mul_f32 v[22:23], v[22:23], v[0:1] op_sel_hi:[1,0]
	v_pk_mul_f32 v[28:29], v[28:29], v[0:1] op_sel_hi:[1,0]
	v_pk_mul_f32 v[26:27], v[26:27], v[0:1] op_sel_hi:[1,0]
	v_pk_mul_f32 v[32:33], v[32:33], v[0:1] op_sel_hi:[1,0]
	v_pk_mul_f32 v[30:31], v[30:31], v[0:1] op_sel_hi:[1,0]
	v_pk_mul_f32 v[4:5], v[4:5], v[0:1] op_sel_hi:[1,0]
	v_pk_mul_f32 v[2:3], v[2:3], v[0:1] op_sel_hi:[1,0]

; template <bool SLC, bool NOMASK> ...
;     ...
;     load_frag8(nxt, KF, VF, SLC ? (dnext & 0xfffff) : dnext, lane);
;     f32x4 sa[2] = {(f32x4){0.f, 0.f, 0.f, 0.f}, (f32x4){0.f, 0.f, 0.f, 0.f}};
; #pragma unroll
;     for (int T = 0; T < 2; ++T)
; #pragma unroll
;         for (int s2 = 0; s2 < 4; ++s2) sa[T] = __builtin_amdgcn_mfma_f32_16x16x32_fp8_fp8(cur.k[T][s2], qf[s2], sa[T], 0, 0, 0);
;     float sc[8]; bool vd[8]; float mx = -1e30f;
;     const bool act = lo == 0 || !SLC;
;     if (NOMASK) {
; #pragma unroll
;         for (int j = 0; j < 8; ++j) { sc[j] = sa[j >> 2][j & 3]; vd[j] = act; }
;         mx = fmaxf(fmaxf(fmaxf(sc[0], sc[1]), fmaxf(sc[2], sc[3])), fmaxf(fmaxf(sc[4], sc[5]), fmaxf(sc[6], sc[7])));
;         mx = act ? mx : -1e30f;
;     } else {
; #pragma unroll
;         for (int T = 0; T < 2; ++T)
; #pragma unroll
;             for (int r = 0; r < 4; ++r) { const int p = pos0 + 16 * T + 4 * kq + r; const bool v = (p >= lo) & (p <= hi); const float x = sa[T][r];
;                 sc[4 * T + r] = x; vd[4 * T + r] = v; mx = v ? fmaxf(mx, x) : mx; }
;     }
;     if (__builtin_amdgcn_ballot_w64(mx > st.m + 4.f) != 0ull) {
;         mx = fmaxf(mx, __shfl_xor(mx, 16)); mx = fmaxf(mx, __shfl_xor(mx, 32));
;         const float mn = fmaxf(st.m, mx), alpha = __builtin_amdgcn_exp2f(st.m - mn); st.m = mn; st.l *= alpha;
; #pragma unroll
;         for (int j = 0; j < 8; ++j) st.o[j] = st.o[j] * alpha;
;     }
.LBB0_910:
	v_lshl_add_u64 v[244:245], v[204:205], 0, v[118:119]
	global_load_dwordx4 v[138:141], v[244:245], off
	global_load_dwordx4 v[142:145], v[244:245], off offset:1024
	global_load_dwordx4 v[146:149], v[244:245], off offset:2048
	global_load_dwordx4 v[150:153], v[244:245], off offset:3072
	v_lshl_add_u64 v[246:247], v[202:203], 0, v[118:119]
	global_load_dwordx4 v[90:93], v[246:247], off
	global_load_dwordx4 v[94:97], v[246:247], off offset:1024
	global_load_dwordx4 v[98:101], v[246:247], off offset:2048
	global_load_dwordx4 v[102:105], v[246:247], off offset:3072
	s_waitcnt vmcnt(20)
	v_mfma_f32_16x16x128_f8f6f4 v[36:39], v[154:161], v[78:85], 0
	v_add_u32_e32 v0, s66, v211
	v_cmp_ge_i32_e32 vcc, v0, v35
	v_cmp_le_i32_e64 s[10:11], v0, v132
	v_mfma_f32_16x16x128_f8f6f4 v[40:43], v[162:169], v[78:85], 0
	s_and_b64 s[16:17], vcc, s[10:11]
	v_add_u32_e32 v45, 1, v0
	v_cmp_ge_i32_e32 vcc, v45, v35
	v_cmp_lt_i32_e64 s[10:11], v0, v132
	s_and_b64 s[12:13], s[10:11], vcc
	s_nop 5
	v_max_f32_e32 v44, v36, v36
	v_max_f32_e32 v44, 0xf149f2ca, v44
	v_cndmask_b32_e64 v44, v223, v44, s[16:17]
	v_max_f32_e32 v45, v37, v37
	v_max_f32_e32 v45, v44, v45
	v_cndmask_b32_e64 v44, v44, v45, s[12:13]
	v_add_u32_e32 v45, 2, v0
	v_cmp_ge_i32_e32 vcc, v45, v35
	v_cmp_le_i32_e64 s[10:11], v45, v132
	v_max_f32_e32 v45, v38, v38
	v_max_f32_e32 v45, v44, v45
	s_and_b64 s[14:15], vcc, s[10:11]
	v_cndmask_b32_e64 v44, v44, v45, s[14:15]
	v_add_u32_e32 v45, 3, v0
	v_cmp_ge_i32_e32 vcc, v45, v35
	v_cmp_le_i32_e64 s[10:11], v45, v132
	v_max_f32_e32 v45, v39, v39
	v_max_f32_e32 v45, v44, v45
	s_and_b64 s[10:11], vcc, s[10:11]
	v_cndmask_b32_e64 v44, v44, v45, s[10:11]
	v_add_u32_e32 v45, 16, v0
	v_cmp_ge_i32_e32 vcc, v45, v35
	v_cmp_le_i32_e64 s[18:19], v45, v132
	v_max_f32_e32 v45, v40, v40
	v_max_f32_e32 v45, v44, v45
	s_and_b64 s[24:25], vcc, s[18:19]
	v_cndmask_b32_e64 v44, v44, v45, s[24:25]
	v_add_u32_e32 v45, 17, v0
	v_cmp_ge_i32_e32 vcc, v45, v35
	v_cmp_le_i32_e64 s[18:19], v45, v132
	v_max_f32_e32 v45, v44, v44
	v_max_f32_e32 v46, v41, v41
	v_max_f32_e32 v45, v45, v46
	s_and_b64 s[20:21], vcc, s[18:19]
	v_cndmask_b32_e64 v44, v44, v45, s[20:21]
	v_add_u32_e32 v45, 18, v0
	v_cmp_ge_i32_e32 vcc, v45, v35
	v_cmp_le_i32_e64 s[18:19], v45, v132
	v_max_f32_e32 v45, v44, v44
	v_max_f32_e32 v46, v42, v42
	v_max_f32_e32 v45, v45, v46
	s_and_b64 s[22:23], vcc, s[18:19]
	v_cndmask_b32_e64 v44, v44, v45, s[22:23]
	v_add_u32_e32 v0, 19, v0
	v_cmp_ge_i32_e32 vcc, v0, v35
	v_cmp_le_i32_e64 s[18:19], v0, v132
	v_max_f32_e32 v0, v44, v44
	v_max_f32_e32 v45, v43, v43
	v_max_f32_e32 v0, v0, v45
	s_and_b64 s[18:19], vcc, s[18:19]
	v_cndmask_b32_e64 v0, v44, v0, s[18:19]
	v_cmp_gt_f32_e32 vcc, v0, v133
	s_cbranch_vccz .LBB0_912
	ds_bpermute_b32 v44, v227, v0
	v_max_f32_e32 v0, v0, v0
	s_waitcnt lgkmcnt(0)
	v_max_f32_e32 v44, v44, v44
	v_max_f32_e32 v0, v0, v44
	ds_bpermute_b32 v44, v226, v0
	s_waitcnt lgkmcnt(0)
	v_max3_f32 v44, v229, v0, v44
	v_sub_f32_e32 v0, v229, v44
	v_exp_f32_e32 v0, v0
	v_mov_b32_e32 v229, v44
	v_mul_f32_e32 v34, v34, v0
	v_pk_mul_f32 v[8:9], v[8:9], v[0:1] op_sel_hi:[1,0]
	v_pk_mul_f32 v[6:7], v[6:7], v[0:1] op_sel_hi:[1,0]
	v_pk_mul_f32 v[12:13], v[12:13], v[0:1] op_sel_hi:[1,0]
	v_pk_mul_f32 v[10:11], v[10:11], v[0:1] op_sel_hi:[1,0]
	v_pk_mul_f32 v[16:17], v[16:17], v[0:1] op_sel_hi:[1,0]
	v_pk_mul_f32 v[14:15], v[14:15], v[0:1] op_sel_hi:[1,0]
	v_pk_mul_f32 v[20:21], v[20:21], v[0:1] op_sel_hi:[1,0]
	v_pk_mul_f32 v[18:19], v[18:19], v[0:1] op_sel_hi:[1,0]
	v_pk_mul_f32 v[24:25], v[24:25], v[0:1] op_sel_hi:[1,0]
	v_pk_mul_f32 v[22:23], v[22:23], v[0:1] op_sel_hi:[1,0]
	v_pk_mul_f32 v[28:29], v[28:29], v[0:1] op_sel_hi:[1,0]
	v_pk_mul_f32 v[26:27], v[26:27], v[0:1] op_sel_hi:[1,0]
	v_pk_mul_f32 v[32:33], v[32:33], v[0:1] op_sel_hi:[1,0]
	v_pk_mul_f32 v[30:31], v[30:31], v[0:1] op_sel_hi:[1,0]
	v_pk_mul_f32 v[4:5], v[4:5], v[0:1] op_sel_hi:[1,0]
	v_pk_mul_f32 v[2:3], v[2:3], v[0:1] op_sel_hi:[1,0]

; template <bool SLC, bool NOMASK> ...
;     ...
;     const int pos0 = SLC ? (dcur & 0xfffff) : dcur;
;     const int lo = SLC ? ((((dcur >> 20) == qi) | ((dcur >> 20) == 4)) ? 0 : (1 << 30)) : lo_in;
;     load_frag8(nxt, KF, VF, SLC ? (dnext & 0xfffff) : dnext, lane);
;     f32x4 sa[2] = {(f32x4){0.f, 0.f, 0.f, 0.f}, (f32x4){0.f, 0.f, 0.f, 0.f}};
; #pragma unroll
;     for (int T = 0; T < 2; ++T)
; #pragma unroll
;         for (int s2 = 0; s2 < 4; ++s2) sa[T] = __builtin_amdgcn_mfma_f32_16x16x32_fp8_fp8(cur.k[T][s2], qf[s2], sa[T], 0, 0, 0);
;     float sc[8]; bool vd[8]; float mx = -1e30f;
;     const bool act = lo == 0 || !SLC;
;     if (NOMASK) {
; #pragma unroll
;         for (int j = 0; j < 8; ++j) { sc[j] = sa[j >> 2][j & 3]; vd[j] = act; }
;         mx = fmaxf(fmaxf(fmaxf(sc[0], sc[1]), fmaxf(sc[2], sc[3])), fmaxf(fmaxf(sc[4], sc[5]), fmaxf(sc[6], sc[7])));
;         mx = act ? mx : -1e30f;
;     } else {
; #pragma unroll
;         for (int T = 0; T < 2; ++T)
; #pragma unroll
;             for (int r = 0; r < 4; ++r) { const int p = pos0 + 16 * T + 4 * kq + r; const bool v = (p >= lo) & (p <= hi); const float x = sa[T][r];
;                 sc[4 * T + r] = x; vd[4 * T + r] = v; mx = v ? fmaxf(mx, x) : mx; }
;     }
;     if (__builtin_amdgcn_ballot_w64(mx > st.m + 4.f) != 0ull) {
;         mx = fmaxf(mx, __shfl_xor(mx, 16)); mx = fmaxf(mx, __shfl_xor(mx, 32));
;         const float mn = fmaxf(st.m, mx), alpha = __builtin_amdgcn_exp2f(st.m - mn); st.m = mn; st.l *= alpha;
; #pragma unroll
;         for (int j = 0; j < 8; ++j) st.o[j] = st.o[j] * alpha;
;     }
; __device__ __forceinline__ void nsa_unit(int unit, const bf16_t* proj, const bf16_t* kc, const bf16_t* vc, const bf16_t* gn, const float* cs, const float* sn, ...
;     ...
;       auto desc = [&](int i) { const int p0 = 32 * (first + i); return p0 | ((p0 >= t0 + 3 - 511 && p0 + 31 <= t0) ? (1 << 30) : 0); };
;       unsigned long long goff = (unsigned long long)g * S * 128; asm volatile("" : "+s"(goff));
;       attn_run_frag8<false>(q8, (const unsigned char*)kslf + ((size_t)16 << 20) + goff, (const unsigned char*)kslf + ((size_t)24 << 20) + goff, desc, last - first + 1, lo, tc, 0, st, lane); }
.LBB0_913:
	s_cmp_lt_i32 s59, s56
	s_cselect_b64 s[10:11], -1, 0
	s_or_b32 s12, s59, 31
	s_cmp_gt_i32 s12, s96
	s_cselect_b64 s[12:13], -1, 0
	s_or_b64 s[10:11], s[10:11], s[12:13]
	s_and_b64 s[10:11], s[10:11], exec
	s_cselect_b32 s10, 0, 2.0
	s_add_i32 s58, s58, 4
	s_or_b32 s14, s10, s59
	s_min_i32 s10, s58, s27
	s_add_i32 s12, s10, s26
	s_lshl_b32 s43, s12, 5
	s_and_b32 s10, s43, 0x3fffffe0
	s_lshr_b32 s50, s10, 4
	s_lshl_b64 s[10:11], s[50:51], 11
	s_and_b32 s50, s12, 0x1ffffff
	s_lshl_b64 s[12:13], s[50:51], 12
	s_cmp_lt_u32 s14, 2.0
	v_lshl_add_u64 v[204:205], v[86:87], 0, s[10:11]
	v_lshl_add_u64 v[202:203], v[88:89], 0, s[12:13]
	s_mov_b64 s[10:11], -1
	v_add_f32_e32 v229, 4.0, v230
	s_cbranch_scc1 .LBB0_917
	v_lshl_add_u64 v[244:245], v[204:205], 0, v[118:119]
	global_load_dwordx4 v[154:157], v[244:245], off
	global_load_dwordx4 v[158:161], v[244:245], off offset:1024
	global_load_dwordx4 v[162:165], v[244:245], off offset:2048
	global_load_dwordx4 v[166:169], v[244:245], off offset:3072
	v_lshl_add_u64 v[246:247], v[202:203], 0, v[118:119]
	global_load_dwordx4 v[106:109], v[246:247], off
	global_load_dwordx4 v[110:113], v[246:247], off offset:1024
	global_load_dwordx4 v[114:117], v[246:247], off offset:2048
	global_load_dwordx4 v[134:137], v[246:247], off offset:3072
	s_waitcnt vmcnt(20)
	v_mfma_f32_16x16x128_f8f6f4 v[2:5], v[186:193], v[78:85], 0
	v_mfma_f32_16x16x128_f8f6f4 v[6:9], v[194:201], v[78:85], 0
	v_mov_b32_e32 v133, v230
	v_mov_b32_e32 v34, v231
	s_nop 8
	v_max_f32_e32 v0, v3, v3
	v_max_f32_e32 v10, v2, v2
	v_max_f32_e32 v0, v10, v0
	v_max_f32_e32 v10, v5, v5
	v_max_f32_e32 v11, v4, v4
	v_max_f32_e32 v10, v11, v10
	v_max_f32_e32 v11, v9, v9
	v_max_f32_e32 v12, v8, v8
	v_max_f32_e32 v11, v12, v11
	v_max3_f32 v11, v6, v7, v11
	v_max3_f32 v0, v0, v10, v11
	v_cmp_gt_f32_e32 vcc, v0, v229
	s_cbranch_vccz .LBB0_916
	ds_bpermute_b32 v10, v227, v0
	v_max_f32_e32 v0, v0, v0
	s_waitcnt lgkmcnt(0)
	v_max_f32_e32 v10, v10, v10
	v_max_f32_e32 v0, v0, v10
	ds_bpermute_b32 v10, v226, v0
	s_waitcnt lgkmcnt(0)
	v_max3_f32 v133, v230, v0, v10
	v_sub_f32_e32 v0, v230, v133
	v_exp_f32_e32 v0, v0
	s_nop 0
	v_mul_f32_e32 v34, v231, v0
	v_pk_mul_f32 v[38:39], v[38:39], v[0:1] op_sel_hi:[1,0]
	v_pk_mul_f32 v[36:37], v[36:37], v[0:1] op_sel_hi:[1,0]
	v_pk_mul_f32 v[42:43], v[42:43], v[0:1] op_sel_hi:[1,0]
	v_pk_mul_f32 v[40:41], v[40:41], v[0:1] op_sel_hi:[1,0]
	v_pk_mul_f32 v[46:47], v[46:47], v[0:1] op_sel_hi:[1,0]
	v_pk_mul_f32 v[44:45], v[44:45], v[0:1] op_sel_hi:[1,0]
	v_pk_mul_f32 v[50:51], v[50:51], v[0:1] op_sel_hi:[1,0]
	v_pk_mul_f32 v[48:49], v[48:49], v[0:1] op_sel_hi:[1,0]
	v_pk_mul_f32 v[54:55], v[54:55], v[0:1] op_sel_hi:[1,0]
	v_pk_mul_f32 v[52:53], v[52:53], v[0:1] op_sel_hi:[1,0]
	v_pk_mul_f32 v[58:59], v[58:59], v[0:1] op_sel_hi:[1,0]
	v_pk_mul_f32 v[56:57], v[56:57], v[0:1] op_sel_hi:[1,0]
	v_pk_mul_f32 v[62:63], v[62:63], v[0:1] op_sel_hi:[1,0]
	v_pk_mul_f32 v[60:61], v[60:61], v[0:1] op_sel_hi:[1,0]
	v_pk_mul_f32 v[66:67], v[66:67], v[0:1] op_sel_hi:[1,0]
	v_pk_mul_f32 v[64:65], v[64:65], v[0:1] op_sel_hi:[1,0]

; template <bool SLC, bool NOMASK> ...
;     ...
;     load_frag8(nxt, KF, VF, SLC ? (dnext & 0xfffff) : dnext, lane);
;     f32x4 sa[2] = {(f32x4){0.f, 0.f, 0.f, 0.f}, (f32x4){0.f, 0.f, 0.f, 0.f}};
; #pragma unroll
;     for (int T = 0; T < 2; ++T)
; #pragma unroll
;         for (int s2 = 0; s2 < 4; ++s2) sa[T] = __builtin_amdgcn_mfma_f32_16x16x32_fp8_fp8(cur.k[T][s2], qf[s2], sa[T], 0, 0, 0);
;     float sc[8]; bool vd[8]; float mx = -1e30f;
;     const bool act = lo == 0 || !SLC;
;     if (NOMASK) {
; #pragma unroll
;         for (int j = 0; j < 8; ++j) { sc[j] = sa[j >> 2][j & 3]; vd[j] = act; }
;         mx = fmaxf(fmaxf(fmaxf(sc[0], sc[1]), fmaxf(sc[2], sc[3])), fmaxf(fmaxf(sc[4], sc[5]), fmaxf(sc[6], sc[7])));
;         mx = act ? mx : -1e30f;
;     } else {
; #pragma unroll
;         for (int T = 0; T < 2; ++T)
; #pragma unroll
;             for (int r = 0; r < 4; ++r) { const int p = pos0 + 16 * T + 4 * kq + r; const bool v = (p >= lo) & (p <= hi); const float x = sa[T][r];
;                 sc[4 * T + r] = x; vd[4 * T + r] = v; mx = v ? fmaxf(mx, x) : mx; }
;     }
;     if (__builtin_amdgcn_ballot_w64(mx > st.m + 4.f) != 0ull) {
;         mx = fmaxf(mx, __shfl_xor(mx, 16)); mx = fmaxf(mx, __shfl_xor(mx, 32));
;         const float mn = fmaxf(st.m, mx), alpha = __builtin_amdgcn_exp2f(st.m - mn); st.m = mn; st.l *= alpha;
; #pragma unroll
;         for (int j = 0; j < 8; ++j) st.o[j] = st.o[j] * alpha;
;     }
.LBB0_917:
	s_and_b64 vcc, exec, s[10:11]
	s_cbranch_vccz .LBB0_921
	v_lshl_add_u64 v[244:245], v[204:205], 0, v[118:119]
	global_load_dwordx4 v[154:157], v[244:245], off
	global_load_dwordx4 v[158:161], v[244:245], off offset:1024
	global_load_dwordx4 v[162:165], v[244:245], off offset:2048
	global_load_dwordx4 v[166:169], v[244:245], off offset:3072
	v_lshl_add_u64 v[246:247], v[202:203], 0, v[118:119]
	global_load_dwordx4 v[106:109], v[246:247], off
	global_load_dwordx4 v[110:113], v[246:247], off offset:1024
	global_load_dwordx4 v[114:117], v[246:247], off offset:2048
	global_load_dwordx4 v[134:137], v[246:247], off offset:3072
	s_waitcnt vmcnt(20)
	v_mfma_f32_16x16x128_f8f6f4 v[2:5], v[186:193], v[78:85], 0
	v_or_b32_e32 v0, s59, v211
	v_cmp_ge_i32_e32 vcc, v0, v35
	v_cmp_le_i32_e64 s[10:11], v0, v132
	v_mfma_f32_16x16x128_f8f6f4 v[6:9], v[194:201], v[78:85], 0
	s_and_b64 s[16:17], vcc, s[10:11]
	v_or_b32_e32 v11, 1, v0
	v_cmp_ge_i32_e32 vcc, v11, v35
	v_cmp_lt_i32_e64 s[10:11], v0, v132
	s_and_b64 s[12:13], s[10:11], vcc
	s_nop 5
	v_max_f32_e32 v10, v2, v2
	v_max_f32_e32 v10, 0xf149f2ca, v10
	v_cndmask_b32_e64 v10, v223, v10, s[16:17]
	v_max_f32_e32 v11, v3, v3
	v_max_f32_e32 v11, v10, v11
	v_cndmask_b32_e64 v10, v10, v11, s[12:13]
	v_or_b32_e32 v11, 2, v0
	v_cmp_ge_i32_e32 vcc, v11, v35
	v_cmp_le_i32_e64 s[10:11], v11, v132
	v_max_f32_e32 v11, v4, v4
	v_max_f32_e32 v11, v10, v11
	s_and_b64 s[14:15], vcc, s[10:11]
	v_cndmask_b32_e64 v10, v10, v11, s[14:15]
	v_or_b32_e32 v11, 3, v0
	v_cmp_ge_i32_e32 vcc, v11, v35
	v_cmp_le_i32_e64 s[10:11], v11, v132
	v_max_f32_e32 v11, v5, v5
	v_max_f32_e32 v11, v10, v11
	s_and_b64 s[10:11], vcc, s[10:11]
	v_cndmask_b32_e64 v10, v10, v11, s[10:11]
	v_or_b32_e32 v11, 16, v0
	v_cmp_ge_i32_e32 vcc, v11, v35
	v_cmp_le_i32_e64 s[18:19], v11, v132
	v_max_f32_e32 v11, v6, v6
	v_max_f32_e32 v11, v10, v11
	s_and_b64 s[24:25], vcc, s[18:19]
	v_cndmask_b32_e64 v10, v10, v11, s[24:25]
	v_or_b32_e32 v11, 17, v0
	v_cmp_ge_i32_e32 vcc, v11, v35
	v_cmp_le_i32_e64 s[18:19], v11, v132
	v_max_f32_e32 v11, v10, v10
	v_max_f32_e32 v12, v7, v7
	v_max_f32_e32 v11, v11, v12
	s_and_b64 s[20:21], vcc, s[18:19]
	v_cndmask_b32_e64 v10, v10, v11, s[20:21]
	v_or_b32_e32 v11, 18, v0
	v_cmp_ge_i32_e32 vcc, v11, v35
	v_cmp_le_i32_e64 s[18:19], v11, v132
	v_max_f32_e32 v11, v10, v10
	v_max_f32_e32 v12, v8, v8
	v_max_f32_e32 v11, v11, v12
	s_and_b64 s[22:23], vcc, s[18:19]
	v_cndmask_b32_e64 v10, v10, v11, s[22:23]
	v_or_b32_e32 v0, 19, v0
	v_cmp_ge_i32_e32 vcc, v0, v35
	v_cmp_le_i32_e64 s[18:19], v0, v132
	v_max_f32_e32 v0, v10, v10
	v_max_f32_e32 v11, v9, v9
	v_max_f32_e32 v0, v0, v11
	s_and_b64 s[18:19], vcc, s[18:19]
	v_cndmask_b32_e64 v0, v10, v0, s[18:19]
	v_cmp_gt_f32_e32 vcc, v0, v229
	s_cbranch_vccz .LBB0_920
	ds_bpermute_b32 v10, v227, v0
	v_max_f32_e32 v0, v0, v0
	s_waitcnt lgkmcnt(0)
	v_max_f32_e32 v10, v10, v10
	v_max_f32_e32 v0, v0, v10
	ds_bpermute_b32 v10, v226, v0
	s_waitcnt lgkmcnt(0)
	v_max3_f32 v10, v230, v0, v10
	v_sub_f32_e32 v0, v230, v10
	v_exp_f32_e32 v0, v0
	v_mov_b32_e32 v230, v10
	v_mul_f32_e32 v231, v231, v0
	v_pk_mul_f32 v[38:39], v[38:39], v[0:1] op_sel_hi:[1,0]
	v_pk_mul_f32 v[36:37], v[36:37], v[0:1] op_sel_hi:[1,0]
	v_pk_mul_f32 v[42:43], v[42:43], v[0:1] op_sel_hi:[1,0]
	v_pk_mul_f32 v[40:41], v[40:41], v[0:1] op_sel_hi:[1,0]
	v_pk_mul_f32 v[46:47], v[46:47], v[0:1] op_sel_hi:[1,0]
	v_pk_mul_f32 v[44:45], v[44:45], v[0:1] op_sel_hi:[1,0]
	v_pk_mul_f32 v[50:51], v[50:51], v[0:1] op_sel_hi:[1,0]
	v_pk_mul_f32 v[48:49], v[48:49], v[0:1] op_sel_hi:[1,0]
	v_pk_mul_f32 v[54:55], v[54:55], v[0:1] op_sel_hi:[1,0]
	v_pk_mul_f32 v[52:53], v[52:53], v[0:1] op_sel_hi:[1,0]
	v_pk_mul_f32 v[58:59], v[58:59], v[0:1] op_sel_hi:[1,0]
	v_pk_mul_f32 v[56:57], v[56:57], v[0:1] op_sel_hi:[1,0]
	v_pk_mul_f32 v[62:63], v[62:63], v[0:1] op_sel_hi:[1,0]
	v_pk_mul_f32 v[60:61], v[60:61], v[0:1] op_sel_hi:[1,0]
	v_pk_mul_f32 v[66:67], v[66:67], v[0:1] op_sel_hi:[1,0]
	v_pk_mul_f32 v[64:65], v[64:65], v[0:1] op_sel_hi:[1,0]

; template <bool SLC, bool NOMASK> ...
;     ...
;     const int pos0 = SLC ? (dcur & 0xfffff) : dcur;
;     const int lo = SLC ? ((((dcur >> 20) == qi) | ((dcur >> 20) == 4)) ? 0 : (1 << 30)) : lo_in;
;     load_frag8(nxt, KF, VF, SLC ? (dnext & 0xfffff) : dnext, lane);
;     f32x4 sa[2] = {(f32x4){0.f, 0.f, 0.f, 0.f}, (f32x4){0.f, 0.f, 0.f, 0.f}};
; #pragma unroll
;     for (int T = 0; T < 2; ++T)
; #pragma unroll
;         for (int s2 = 0; s2 < 4; ++s2) sa[T] = __builtin_amdgcn_mfma_f32_16x16x32_fp8_fp8(cur.k[T][s2], qf[s2], sa[T], 0, 0, 0);
;     float sc[8]; bool vd[8]; float mx = -1e30f;
;     const bool act = lo == 0 || !SLC;
;     if (NOMASK) {
; #pragma unroll
;         for (int j = 0; j < 8; ++j) { sc[j] = sa[j >> 2][j & 3]; vd[j] = act; }
;         mx = fmaxf(fmaxf(fmaxf(sc[0], sc[1]), fmaxf(sc[2], sc[3])), fmaxf(fmaxf(sc[4], sc[5]), fmaxf(sc[6], sc[7])));
;         mx = act ? mx : -1e30f;
;     } else {
; #pragma unroll
;         for (int T = 0; T < 2; ++T)
; #pragma unroll
;             for (int r = 0; r < 4; ++r) { const int p = pos0 + 16 * T + 4 * kq + r; const bool v = (p >= lo) & (p <= hi); const float x = sa[T][r];
;                 sc[4 * T + r] = x; vd[4 * T + r] = v; mx = v ? fmaxf(mx, x) : mx; }
;     }
;     if (__builtin_amdgcn_ballot_w64(mx > st.m + 4.f) != 0ull) {
;         mx = fmaxf(mx, __shfl_xor(mx, 16)); mx = fmaxf(mx, __shfl_xor(mx, 32));
;         const float mn = fmaxf(st.m, mx), alpha = __builtin_amdgcn_exp2f(st.m - mn); st.m = mn; st.l *= alpha;
; #pragma unroll
;         for (int j = 0; j < 8; ++j) st.o[j] = st.o[j] * alpha;
;     }
.LBB0_969:
	s_and_b32 s13, s12, 0xfffffbff
	s_cmp_eq_u32 s13, 4
	s_cselect_b64 s[10:11], -1, 0
	s_lshl_b32 s14, s66, 7
	s_and_b32 s50, s14, 0x7fff800
	v_lshl_add_u64 v[10:11], v[86:87], 0, s[50:51]
	s_and_b32 s50, s14, 0x7fff000
	v_lshl_add_u64 v[246:247], v[10:11], 0, v[120:121]
	global_load_dwordx4 v[186:189], v[246:247], off
	global_load_dwordx4 v[190:193], v[246:247], off offset:1024
	global_load_dwordx4 v[194:197], v[246:247], off offset:2048
	global_load_dwordx4 v[198:201], v[246:247], off offset:3072
	v_lshl_add_u64 v[10:11], v[88:89], 0, s[50:51]
	v_lshl_add_u64 v[244:245], v[10:11], 0, v[120:121]
	global_load_dwordx4 v[170:173], v[244:245], off
	global_load_dwordx4 v[174:177], v[244:245], off offset:1024
	global_load_dwordx4 v[178:181], v[244:245], off offset:2048
	global_load_dwordx4 v[182:185], v[244:245], off offset:3072
	s_waitcnt vmcnt(20)
	v_mfma_f32_16x16x128_f8f6f4 v[2:5], v[138:145], v[78:85], 0
	v_cmp_eq_u32_e32 vcc, s13, v209
	s_or_b64 s[10:11], s[10:11], vcc
	v_mfma_f32_16x16x128_f8f6f4 v[6:9], v[146:153], v[78:85], 0
	v_mov_b32_e32 v133, v203
	s_nop 7
	v_max_f32_e32 v0, v3, v3
	v_max_f32_e32 v10, v2, v2
	v_max_f32_e32 v0, v10, v0
	v_max_f32_e32 v10, v5, v5
	v_max_f32_e32 v11, v4, v4
	v_max_f32_e32 v10, v11, v10
	v_max_f32_e32 v11, v9, v9
	v_max_f32_e32 v12, v8, v8
	v_max_f32_e32 v11, v12, v11
	v_max3_f32 v11, v6, v7, v11
	v_max3_f32 v0, v0, v10, v11
	v_cndmask_b32_e64 v34, v220, v0, s[10:11]
	v_cmp_gt_f32_e32 vcc, v34, v204
	v_mov_b32_e32 v0, v202
	s_cbranch_vccz .LBB0_971
	ds_bpermute_b32 v0, v225, v34
	v_max_f32_e32 v10, v34, v34
	s_waitcnt lgkmcnt(0)
	v_max_f32_e32 v0, v0, v0
	v_max_f32_e32 v0, v10, v0
	ds_bpermute_b32 v10, v224, v0
	s_waitcnt lgkmcnt(0)
	v_max3_f32 v0, v202, v0, v10
	v_sub_f32_e32 v10, v202, v0
	v_exp_f32_e32 v34, v10
	s_nop 0
	v_mul_f32_e32 v133, v203, v34
	v_pk_mul_f32 v[66:67], v[66:67], v[34:35] op_sel_hi:[1,0]
	v_pk_mul_f32 v[64:65], v[64:65], v[34:35] op_sel_hi:[1,0]
	v_pk_mul_f32 v[62:63], v[62:63], v[34:35] op_sel_hi:[1,0]
	v_pk_mul_f32 v[60:61], v[60:61], v[34:35] op_sel_hi:[1,0]
	v_pk_mul_f32 v[58:59], v[58:59], v[34:35] op_sel_hi:[1,0]
	v_pk_mul_f32 v[56:57], v[56:57], v[34:35] op_sel_hi:[1,0]
	v_pk_mul_f32 v[54:55], v[54:55], v[34:35] op_sel_hi:[1,0]
	v_pk_mul_f32 v[52:53], v[52:53], v[34:35] op_sel_hi:[1,0]
	v_pk_mul_f32 v[50:51], v[50:51], v[34:35] op_sel_hi:[1,0]
	v_pk_mul_f32 v[48:49], v[48:49], v[34:35] op_sel_hi:[1,0]
	v_pk_mul_f32 v[46:47], v[46:47], v[34:35] op_sel_hi:[1,0]
	v_pk_mul_f32 v[44:45], v[44:45], v[34:35] op_sel_hi:[1,0]
	v_pk_mul_f32 v[42:43], v[42:43], v[34:35] op_sel_hi:[1,0]
	v_pk_mul_f32 v[40:41], v[40:41], v[34:35] op_sel_hi:[1,0]
	v_pk_mul_f32 v[38:39], v[38:39], v[34:35] op_sel_hi:[1,0]
	v_pk_mul_f32 v[36:37], v[36:37], v[34:35] op_sel_hi:[1,0]

; template <bool SLC, bool NOMASK> ...
;     ...
;     const int pos0 = SLC ? (dcur & 0xfffff) : dcur;
;     const int lo = SLC ? ((((dcur >> 20) == qi) | ((dcur >> 20) == 4)) ? 0 : (1 << 30)) : lo_in;
;     load_frag8(nxt, KF, VF, SLC ? (dnext & 0xfffff) : dnext, lane);
;     f32x4 sa[2] = {(f32x4){0.f, 0.f, 0.f, 0.f}, (f32x4){0.f, 0.f, 0.f, 0.f}};
; #pragma unroll
;     for (int T = 0; T < 2; ++T)
; #pragma unroll
;         for (int s2 = 0; s2 < 4; ++s2) sa[T] = __builtin_amdgcn_mfma_f32_16x16x32_fp8_fp8(cur.k[T][s2], qf[s2], sa[T], 0, 0, 0);
;     float sc[8]; bool vd[8]; float mx = -1e30f;
;     const bool act = lo == 0 || !SLC;
;     if (NOMASK) {
; #pragma unroll
;         for (int j = 0; j < 8; ++j) { sc[j] = sa[j >> 2][j & 3]; vd[j] = act; }
;         mx = fmaxf(fmaxf(fmaxf(sc[0], sc[1]), fmaxf(sc[2], sc[3])), fmaxf(fmaxf(sc[4], sc[5]), fmaxf(sc[6], sc[7])));
;         mx = act ? mx : -1e30f;
;     } else {
; #pragma unroll
;         for (int T = 0; T < 2; ++T)
; #pragma unroll
;             for (int r = 0; r < 4; ++r) { const int p = pos0 + 16 * T + 4 * kq + r; const bool v = (p >= lo) & (p <= hi); const float x = sa[T][r];
;                 sc[4 * T + r] = x; vd[4 * T + r] = v; mx = v ? fmaxf(mx, x) : mx; }
;     }
;     if (__builtin_amdgcn_ballot_w64(mx > st.m + 4.f) != 0ull) {
;         mx = fmaxf(mx, __shfl_xor(mx, 16)); mx = fmaxf(mx, __shfl_xor(mx, 32));
;         const float mn = fmaxf(st.m, mx), alpha = __builtin_amdgcn_exp2f(st.m - mn); st.m = mn; st.l *= alpha;
; #pragma unroll
;         for (int j = 0; j < 8; ++j) st.o[j] = st.o[j] * alpha;
;     }
.LBB0_972:
	s_cmp_eq_u32 s12, 4
	s_cselect_b64 s[10:11], -1, 0
	s_lshl_b32 s13, s66, 7
	s_and_b32 s50, s13, 0x7fff800
	v_lshl_add_u64 v[10:11], v[86:87], 0, s[50:51]
	s_and_b32 s50, s13, 0x7fff000
	v_lshl_add_u64 v[246:247], v[10:11], 0, v[120:121]
	global_load_dwordx4 v[186:189], v[246:247], off
	global_load_dwordx4 v[190:193], v[246:247], off offset:1024
	global_load_dwordx4 v[194:197], v[246:247], off offset:2048
	global_load_dwordx4 v[198:201], v[246:247], off offset:3072
	v_lshl_add_u64 v[10:11], v[88:89], 0, s[50:51]
	v_lshl_add_u64 v[244:245], v[10:11], 0, v[120:121]
	global_load_dwordx4 v[170:173], v[244:245], off
	global_load_dwordx4 v[174:177], v[244:245], off offset:1024
	global_load_dwordx4 v[178:181], v[244:245], off offset:2048
	global_load_dwordx4 v[182:185], v[244:245], off offset:3072
	s_waitcnt vmcnt(20)
	v_mfma_f32_16x16x128_f8f6f4 v[2:5], v[138:145], v[78:85], 0
	s_and_b32 s13, s57, 0xfffff
	v_cmp_eq_u32_e32 vcc, s12, v209
	v_add_u32_e32 v0, s13, v210
	v_mfma_f32_16x16x128_f8f6f4 v[6:9], v[146:153], v[78:85], 0
	s_or_b64 s[18:19], s[10:11], vcc
	v_cmp_le_i32_e32 vcc, v0, v132
	s_and_b64 s[16:17], s[18:19], vcc
	v_cmp_lt_i32_e32 vcc, v0, v132
	s_and_b64 s[12:13], s[18:19], vcc
	s_nop 5
	v_max_f32_e32 v10, v2, v2
	v_max_f32_e32 v10, 0xf149f2ca, v10
	v_cndmask_b32_e64 v10, v220, v10, s[16:17]
	v_max_f32_e32 v11, v3, v3
	v_max_f32_e32 v11, v10, v11
	v_cndmask_b32_e64 v10, v10, v11, s[12:13]
	v_add_u32_e32 v11, 2, v0
	v_cmp_le_i32_e32 vcc, v11, v132
	v_max_f32_e32 v11, v4, v4
	v_max_f32_e32 v11, v10, v11
	s_and_b64 s[14:15], s[18:19], vcc
	v_cndmask_b32_e64 v10, v10, v11, s[14:15]
	v_add_u32_e32 v11, 3, v0
	v_cmp_le_i32_e32 vcc, v11, v132
	v_max_f32_e32 v11, v5, v5
	v_max_f32_e32 v11, v10, v11
	s_and_b64 s[10:11], s[18:19], vcc
	v_cndmask_b32_e64 v10, v10, v11, s[10:11]
	v_add_u32_e32 v11, 16, v0
	v_cmp_le_i32_e32 vcc, v11, v132
	v_max_f32_e32 v11, v6, v6
	v_max_f32_e32 v11, v10, v11
	s_and_b64 s[24:25], s[18:19], vcc
	v_cndmask_b32_e64 v10, v10, v11, s[24:25]
	v_add_u32_e32 v11, 17, v0
	v_cmp_le_i32_e32 vcc, v11, v132
	v_max_f32_e32 v11, v10, v10
	v_max_f32_e32 v12, v7, v7
	v_max_f32_e32 v11, v11, v12
	s_and_b64 s[20:21], s[18:19], vcc
	v_cndmask_b32_e64 v10, v10, v11, s[20:21]
	v_add_u32_e32 v11, 18, v0
	v_cmp_le_i32_e32 vcc, v11, v132
	v_max_f32_e32 v11, v10, v10
	v_max_f32_e32 v12, v8, v8
	v_max_f32_e32 v11, v11, v12
	s_and_b64 s[22:23], s[18:19], vcc
	v_cndmask_b32_e64 v10, v10, v11, s[22:23]
	v_add_u32_e32 v0, 19, v0
	v_cmp_le_i32_e32 vcc, v0, v132
	v_max_f32_e32 v0, v10, v10
	v_max_f32_e32 v11, v9, v9
	v_max_f32_e32 v0, v0, v11
	s_and_b64 s[18:19], s[18:19], vcc
	v_cndmask_b32_e64 v0, v10, v0, s[18:19]
	v_cmp_gt_f32_e32 vcc, v0, v204
	s_cbranch_vccz .LBB0_974
	ds_bpermute_b32 v10, v225, v0
	v_max_f32_e32 v0, v0, v0
	s_waitcnt lgkmcnt(0)
	v_max_f32_e32 v10, v10, v10
	v_max_f32_e32 v0, v0, v10
	ds_bpermute_b32 v10, v224, v0
	s_waitcnt lgkmcnt(0)
	v_max3_f32 v10, v202, v0, v10
	v_sub_f32_e32 v0, v202, v10
	v_exp_f32_e32 v0, v0
	v_mov_b32_e32 v202, v10
	v_mul_f32_e32 v203, v203, v0
	v_pk_mul_f32 v[66:67], v[66:67], v[0:1] op_sel_hi:[1,0]
	v_pk_mul_f32 v[64:65], v[64:65], v[0:1] op_sel_hi:[1,0]
	v_pk_mul_f32 v[62:63], v[62:63], v[0:1] op_sel_hi:[1,0]
	v_pk_mul_f32 v[60:61], v[60:61], v[0:1] op_sel_hi:[1,0]
	v_pk_mul_f32 v[58:59], v[58:59], v[0:1] op_sel_hi:[1,0]
	v_pk_mul_f32 v[56:57], v[56:57], v[0:1] op_sel_hi:[1,0]
	v_pk_mul_f32 v[54:55], v[54:55], v[0:1] op_sel_hi:[1,0]
	v_pk_mul_f32 v[52:53], v[52:53], v[0:1] op_sel_hi:[1,0]
	v_pk_mul_f32 v[50:51], v[50:51], v[0:1] op_sel_hi:[1,0]
	v_pk_mul_f32 v[48:49], v[48:49], v[0:1] op_sel_hi:[1,0]
	v_pk_mul_f32 v[46:47], v[46:47], v[0:1] op_sel_hi:[1,0]
	v_pk_mul_f32 v[44:45], v[44:45], v[0:1] op_sel_hi:[1,0]
	v_pk_mul_f32 v[42:43], v[42:43], v[0:1] op_sel_hi:[1,0]
	v_pk_mul_f32 v[40:41], v[40:41], v[0:1] op_sel_hi:[1,0]
	v_pk_mul_f32 v[38:39], v[38:39], v[0:1] op_sel_hi:[1,0]
	v_pk_mul_f32 v[36:37], v[36:37], v[0:1] op_sel_hi:[1,0]

; template <bool SLC, bool NOMASK> ...
;     ...
;     const int pos0 = SLC ? (dcur & 0xfffff) : dcur;
;     const int lo = SLC ? ((((dcur >> 20) == qi) | ((dcur >> 20) == 4)) ? 0 : (1 << 30)) : lo_in;
;     load_frag8(nxt, KF, VF, SLC ? (dnext & 0xfffff) : dnext, lane);
;     f32x4 sa[2] = {(f32x4){0.f, 0.f, 0.f, 0.f}, (f32x4){0.f, 0.f, 0.f, 0.f}};
; #pragma unroll
;     for (int T = 0; T < 2; ++T)
; #pragma unroll
;         for (int s2 = 0; s2 < 4; ++s2) sa[T] = __builtin_amdgcn_mfma_f32_16x16x32_fp8_fp8(cur.k[T][s2], qf[s2], sa[T], 0, 0, 0);
;     float sc[8]; bool vd[8]; float mx = -1e30f;
;     const bool act = lo == 0 || !SLC;
;     if (NOMASK) {
; #pragma unroll
;         for (int j = 0; j < 8; ++j) { sc[j] = sa[j >> 2][j & 3]; vd[j] = act; }
;         mx = fmaxf(fmaxf(fmaxf(sc[0], sc[1]), fmaxf(sc[2], sc[3])), fmaxf(fmaxf(sc[4], sc[5]), fmaxf(sc[6], sc[7])));
;         mx = act ? mx : -1e30f;
;     } else {
; #pragma unroll
;         for (int T = 0; T < 2; ++T)
; #pragma unroll
;             for (int r = 0; r < 4; ++r) { const int p = pos0 + 16 * T + 4 * kq + r; const bool v = (p >= lo) & (p <= hi); const float x = sa[T][r];
;                 sc[4 * T + r] = x; vd[4 * T + r] = v; mx = v ? fmaxf(mx, x) : mx; }
;     }
;     if (__builtin_amdgcn_ballot_w64(mx > st.m + 4.f) != 0ull) {
;         mx = fmaxf(mx, __shfl_xor(mx, 16)); mx = fmaxf(mx, __shfl_xor(mx, 32));
;         const float mn = fmaxf(st.m, mx), alpha = __builtin_amdgcn_exp2f(st.m - mn); st.m = mn; st.l *= alpha;
; #pragma unroll
;         for (int j = 0; j < 8; ++j) st.o[j] = st.o[j] * alpha;
;     }
.LBB0_976:
	s_and_b32 s13, s12, 0xfffffbff
	s_cmp_eq_u32 s13, 4
	s_cselect_b64 s[10:11], -1, 0
	s_lshl_b32 s14, s57, 7
	s_and_b32 s50, s14, 0x7fff800
	v_lshl_add_u64 v[44:45], v[86:87], 0, s[50:51]
	s_and_b32 s50, s14, 0x7fff000
	v_lshl_add_u64 v[246:247], v[44:45], 0, v[120:121]
	global_load_dwordx4 v[138:141], v[246:247], off
	global_load_dwordx4 v[142:145], v[246:247], off offset:1024
	global_load_dwordx4 v[146:149], v[246:247], off offset:2048
	global_load_dwordx4 v[150:153], v[246:247], off offset:3072
	v_lshl_add_u64 v[44:45], v[88:89], 0, s[50:51]
	v_lshl_add_u64 v[244:245], v[44:45], 0, v[120:121]
	global_load_dwordx4 v[90:93], v[244:245], off
	global_load_dwordx4 v[94:97], v[244:245], off offset:1024
	global_load_dwordx4 v[98:101], v[244:245], off offset:2048
	global_load_dwordx4 v[102:105], v[244:245], off offset:3072
	s_waitcnt vmcnt(20)
	v_mfma_f32_16x16x128_f8f6f4 v[36:39], v[154:161], v[78:85], 0
	v_cmp_eq_u32_e32 vcc, s13, v209
	s_or_b64 s[10:11], s[10:11], vcc
	v_mfma_f32_16x16x128_f8f6f4 v[40:43], v[162:169], v[78:85], 0
	v_mov_b32_e32 v203, v0
	s_nop 7
	v_max_f32_e32 v3, v37, v37
	v_max_f32_e32 v44, v36, v36
	v_max_f32_e32 v3, v44, v3
	v_max_f32_e32 v44, v39, v39
	v_max_f32_e32 v45, v38, v38
	v_max_f32_e32 v44, v45, v44
	v_max_f32_e32 v45, v43, v43
	v_max_f32_e32 v46, v42, v42
	v_max_f32_e32 v45, v46, v45
	v_max3_f32 v45, v40, v41, v45
	v_max3_f32 v3, v3, v44, v45
	v_cndmask_b32_e64 v202, v220, v3, s[10:11]
	v_cmp_gt_f32_e32 vcc, v202, v2
	v_mov_b32_e32 v3, v133
	s_cbranch_vccz .LBB0_978
	ds_bpermute_b32 v3, v225, v202
	v_max_f32_e32 v44, v202, v202
	s_waitcnt lgkmcnt(0)
	v_max_f32_e32 v3, v3, v3
	v_max_f32_e32 v3, v44, v3
	ds_bpermute_b32 v44, v224, v3
	s_waitcnt lgkmcnt(0)
	v_max3_f32 v203, v0, v3, v44
	v_sub_f32_e32 v3, v0, v203
	v_exp_f32_e32 v72, v3
	s_nop 0
	v_mul_f32_e32 v3, v133, v72
	v_pk_mul_f32 v[10:11], v[10:11], v[72:73] op_sel_hi:[1,0]
	v_pk_mul_f32 v[8:9], v[8:9], v[72:73] op_sel_hi:[1,0]
	v_pk_mul_f32 v[14:15], v[14:15], v[72:73] op_sel_hi:[1,0]
	v_pk_mul_f32 v[12:13], v[12:13], v[72:73] op_sel_hi:[1,0]
	v_pk_mul_f32 v[18:19], v[18:19], v[72:73] op_sel_hi:[1,0]
	v_pk_mul_f32 v[16:17], v[16:17], v[72:73] op_sel_hi:[1,0]
	v_pk_mul_f32 v[22:23], v[22:23], v[72:73] op_sel_hi:[1,0]
	v_pk_mul_f32 v[20:21], v[20:21], v[72:73] op_sel_hi:[1,0]
	v_pk_mul_f32 v[26:27], v[26:27], v[72:73] op_sel_hi:[1,0]
	v_pk_mul_f32 v[24:25], v[24:25], v[72:73] op_sel_hi:[1,0]
	v_pk_mul_f32 v[34:35], v[34:35], v[72:73] op_sel_hi:[1,0]
	v_pk_mul_f32 v[32:33], v[32:33], v[72:73] op_sel_hi:[1,0]
	v_pk_mul_f32 v[30:31], v[30:31], v[72:73] op_sel_hi:[1,0]
	v_pk_mul_f32 v[28:29], v[28:29], v[72:73] op_sel_hi:[1,0]
	v_pk_mul_f32 v[6:7], v[6:7], v[72:73] op_sel_hi:[1,0]
	v_pk_mul_f32 v[4:5], v[4:5], v[72:73] op_sel_hi:[1,0]

; template <bool SLC, bool NOMASK> ...
;     ...
;     const int pos0 = SLC ? (dcur & 0xfffff) : dcur;
;     const int lo = SLC ? ((((dcur >> 20) == qi) | ((dcur >> 20) == 4)) ? 0 : (1 << 30)) : lo_in;
;     load_frag8(nxt, KF, VF, SLC ? (dnext & 0xfffff) : dnext, lane);
;     f32x4 sa[2] = {(f32x4){0.f, 0.f, 0.f, 0.f}, (f32x4){0.f, 0.f, 0.f, 0.f}};
; #pragma unroll
;     for (int T = 0; T < 2; ++T)
; #pragma unroll
;         for (int s2 = 0; s2 < 4; ++s2) sa[T] = __builtin_amdgcn_mfma_f32_16x16x32_fp8_fp8(cur.k[T][s2], qf[s2], sa[T], 0, 0, 0);
;     float sc[8]; bool vd[8]; float mx = -1e30f;
;     const bool act = lo == 0 || !SLC;
;     if (NOMASK) {
; #pragma unroll
;         for (int j = 0; j < 8; ++j) { sc[j] = sa[j >> 2][j & 3]; vd[j] = act; }
;         mx = fmaxf(fmaxf(fmaxf(sc[0], sc[1]), fmaxf(sc[2], sc[3])), fmaxf(fmaxf(sc[4], sc[5]), fmaxf(sc[6], sc[7])));
;         mx = act ? mx : -1e30f;
;     } else {
; #pragma unroll
;         for (int T = 0; T < 2; ++T)
; #pragma unroll
;             for (int r = 0; r < 4; ++r) { const int p = pos0 + 16 * T + 4 * kq + r; const bool v = (p >= lo) & (p <= hi); const float x = sa[T][r];
;                 sc[4 * T + r] = x; vd[4 * T + r] = v; mx = v ? fmaxf(mx, x) : mx; }
;     }
;     if (__builtin_amdgcn_ballot_w64(mx > st.m + 4.f) != 0ull) {
;         mx = fmaxf(mx, __shfl_xor(mx, 16)); mx = fmaxf(mx, __shfl_xor(mx, 32));
;         const float mn = fmaxf(st.m, mx), alpha = __builtin_amdgcn_exp2f(st.m - mn); st.m = mn; st.l *= alpha;
; #pragma unroll
;         for (int j = 0; j < 8; ++j) st.o[j] = st.o[j] * alpha;
;     }
.LBB0_979:
	s_cmp_eq_u32 s12, 4
	s_cselect_b64 s[10:11], -1, 0
	s_lshl_b32 s13, s57, 7
	s_and_b32 s50, s13, 0x7fff800
	v_lshl_add_u64 v[44:45], v[86:87], 0, s[50:51]
	s_and_b32 s50, s13, 0x7fff000
	v_lshl_add_u64 v[246:247], v[44:45], 0, v[120:121]
	global_load_dwordx4 v[138:141], v[246:247], off
	global_load_dwordx4 v[142:145], v[246:247], off offset:1024
	global_load_dwordx4 v[146:149], v[246:247], off offset:2048
	global_load_dwordx4 v[150:153], v[246:247], off offset:3072
	v_lshl_add_u64 v[44:45], v[88:89], 0, s[50:51]
	v_lshl_add_u64 v[244:245], v[44:45], 0, v[120:121]
	global_load_dwordx4 v[90:93], v[244:245], off
	global_load_dwordx4 v[94:97], v[244:245], off offset:1024
	global_load_dwordx4 v[98:101], v[244:245], off offset:2048
	global_load_dwordx4 v[102:105], v[244:245], off offset:3072
	s_waitcnt vmcnt(20)
	v_mfma_f32_16x16x128_f8f6f4 v[36:39], v[154:161], v[78:85], 0
	s_and_b32 s13, s92, 0xfffff
	v_cmp_eq_u32_e32 vcc, s12, v209
	v_add_u32_e32 v3, s13, v210
	v_mfma_f32_16x16x128_f8f6f4 v[40:43], v[162:169], v[78:85], 0
	s_or_b64 s[18:19], s[10:11], vcc
	v_cmp_le_i32_e32 vcc, v3, v132
	s_and_b64 s[16:17], s[18:19], vcc
	v_cmp_lt_i32_e32 vcc, v3, v132
	s_and_b64 s[12:13], s[18:19], vcc
	s_nop 5
	v_max_f32_e32 v44, v36, v36
	v_max_f32_e32 v44, 0xf149f2ca, v44
	v_cndmask_b32_e64 v44, v220, v44, s[16:17]
	v_max_f32_e32 v45, v37, v37
	v_max_f32_e32 v45, v44, v45
	v_cndmask_b32_e64 v44, v44, v45, s[12:13]
	v_add_u32_e32 v45, 2, v3
	v_cmp_le_i32_e32 vcc, v45, v132
	v_max_f32_e32 v45, v38, v38
	v_max_f32_e32 v45, v44, v45
	s_and_b64 s[14:15], s[18:19], vcc
	v_cndmask_b32_e64 v44, v44, v45, s[14:15]
	v_add_u32_e32 v45, 3, v3
	v_cmp_le_i32_e32 vcc, v45, v132
	v_max_f32_e32 v45, v39, v39
	v_max_f32_e32 v45, v44, v45
	s_and_b64 s[10:11], s[18:19], vcc
	v_cndmask_b32_e64 v44, v44, v45, s[10:11]
	v_add_u32_e32 v45, 16, v3
	v_cmp_le_i32_e32 vcc, v45, v132
	v_max_f32_e32 v45, v40, v40
	v_max_f32_e32 v45, v44, v45
	s_and_b64 s[24:25], s[18:19], vcc
	v_cndmask_b32_e64 v44, v44, v45, s[24:25]
	v_add_u32_e32 v45, 17, v3
	v_cmp_le_i32_e32 vcc, v45, v132
	v_max_f32_e32 v45, v44, v44
	v_max_f32_e32 v46, v41, v41
	v_max_f32_e32 v45, v45, v46
	s_and_b64 s[20:21], s[18:19], vcc
	v_cndmask_b32_e64 v44, v44, v45, s[20:21]
	v_add_u32_e32 v45, 18, v3
	v_cmp_le_i32_e32 vcc, v45, v132
	v_max_f32_e32 v45, v44, v44
	v_max_f32_e32 v46, v42, v42
	v_max_f32_e32 v45, v45, v46
	s_and_b64 s[22:23], s[18:19], vcc
	v_cndmask_b32_e64 v44, v44, v45, s[22:23]
	v_add_u32_e32 v3, 19, v3
	v_cmp_le_i32_e32 vcc, v3, v132
	v_max_f32_e32 v3, v44, v44
	v_max_f32_e32 v45, v43, v43
	v_max_f32_e32 v3, v3, v45
	s_and_b64 s[18:19], s[18:19], vcc
	v_cndmask_b32_e64 v3, v44, v3, s[18:19]
	v_cmp_gt_f32_e32 vcc, v3, v2
	s_cbranch_vccz .LBB0_981
	ds_bpermute_b32 v2, v225, v3
	v_max_f32_e32 v3, v3, v3
	s_waitcnt lgkmcnt(0)
	v_max_f32_e32 v2, v2, v2
	v_max_f32_e32 v2, v3, v2
	ds_bpermute_b32 v3, v224, v2
	s_waitcnt lgkmcnt(0)
	v_max3_f32 v2, v0, v2, v3
	v_sub_f32_e32 v0, v0, v2
	v_exp_f32_e32 v0, v0
	s_nop 0
	v_mul_f32_e32 v133, v133, v0
	v_pk_mul_f32 v[10:11], v[10:11], v[0:1] op_sel_hi:[1,0]
	v_pk_mul_f32 v[8:9], v[8:9], v[0:1] op_sel_hi:[1,0]
	v_pk_mul_f32 v[14:15], v[14:15], v[0:1] op_sel_hi:[1,0]
	v_pk_mul_f32 v[12:13], v[12:13], v[0:1] op_sel_hi:[1,0]
	v_pk_mul_f32 v[18:19], v[18:19], v[0:1] op_sel_hi:[1,0]
	v_pk_mul_f32 v[16:17], v[16:17], v[0:1] op_sel_hi:[1,0]
	v_pk_mul_f32 v[22:23], v[22:23], v[0:1] op_sel_hi:[1,0]
	v_pk_mul_f32 v[20:21], v[20:21], v[0:1] op_sel_hi:[1,0]
	v_pk_mul_f32 v[26:27], v[26:27], v[0:1] op_sel_hi:[1,0]
	v_pk_mul_f32 v[24:25], v[24:25], v[0:1] op_sel_hi:[1,0]
	v_pk_mul_f32 v[34:35], v[34:35], v[0:1] op_sel_hi:[1,0]
	v_pk_mul_f32 v[32:33], v[32:33], v[0:1] op_sel_hi:[1,0]
	v_pk_mul_f32 v[30:31], v[30:31], v[0:1] op_sel_hi:[1,0]
	v_pk_mul_f32 v[28:29], v[28:29], v[0:1] op_sel_hi:[1,0]
	v_pk_mul_f32 v[6:7], v[6:7], v[0:1] op_sel_hi:[1,0]
	v_pk_mul_f32 v[4:5], v[4:5], v[0:1] op_sel_hi:[1,0]
	v_mov_b32_e32 v0, v2

; template <bool SLC, bool NOMASK> ...
;     ...
;     const int pos0 = SLC ? (dcur & 0xfffff) : dcur;
;     const int lo = SLC ? ((((dcur >> 20) == qi) | ((dcur >> 20) == 4)) ? 0 : (1 << 30)) : lo_in;
;     load_frag8(nxt, KF, VF, SLC ? (dnext & 0xfffff) : dnext, lane);
;     f32x4 sa[2] = {(f32x4){0.f, 0.f, 0.f, 0.f}, (f32x4){0.f, 0.f, 0.f, 0.f}};
; #pragma unroll
;     for (int T = 0; T < 2; ++T)
; #pragma unroll
;         for (int s2 = 0; s2 < 4; ++s2) sa[T] = __builtin_amdgcn_mfma_f32_16x16x32_fp8_fp8(cur.k[T][s2], qf[s2], sa[T], 0, 0, 0);
;     float sc[8]; bool vd[8]; float mx = -1e30f;
;     const bool act = lo == 0 || !SLC;
;     if (NOMASK) {
; #pragma unroll
;         for (int j = 0; j < 8; ++j) { sc[j] = sa[j >> 2][j & 3]; vd[j] = act; }
;         mx = fmaxf(fmaxf(fmaxf(sc[0], sc[1]), fmaxf(sc[2], sc[3])), fmaxf(fmaxf(sc[4], sc[5]), fmaxf(sc[6], sc[7])));
;         mx = act ? mx : -1e30f;
;     } else {
; #pragma unroll
;         for (int T = 0; T < 2; ++T)
; #pragma unroll
;             for (int r = 0; r < 4; ++r) { const int p = pos0 + 16 * T + 4 * kq + r; const bool v = (p >= lo) & (p <= hi); const float x = sa[T][r];
;                 sc[4 * T + r] = x; vd[4 * T + r] = v; mx = v ? fmaxf(mx, x) : mx; }
;     }
;     if (__builtin_amdgcn_ballot_w64(mx > st.m + 4.f) != 0ull) {
;         mx = fmaxf(mx, __shfl_xor(mx, 16)); mx = fmaxf(mx, __shfl_xor(mx, 32));
;         const float mn = fmaxf(st.m, mx), alpha = __builtin_amdgcn_exp2f(st.m - mn); st.m = mn; st.l *= alpha;
; #pragma unroll
;         for (int j = 0; j < 8; ++j) st.o[j] = st.o[j] * alpha;
;     }
; template <bool SLC, class Desc>
; __device__ __forceinline__ void attn_run_frag8(const i64_t (&qf)[4], const unsigned char* __restrict__ KF, const unsigned char* __restrict__ VF, const Desc& desc, int n,
;                                                int lo_in, int hi, int qi, AState& st, int lane) {
;     ...
;     for (int i = 0; i < n; i += 3) {
;         const int d2 = desc(i + 2 < n ? i + 2 : n - 1);
;         F8_STEP(fa, fc, d0, d2);
;         if (i + 1 >= n) break;
;         const int d3 = desc(i + 3 < n ? i + 3 : n - 1);
;         F8_STEP(fb, fa, d1, d3);
;         if (i + 2 >= n) break;
;         const int d4 = desc(i + 4 < n ? i + 4 : n - 1);
;         F8_STEP(fc, fb, d2, d4);
.LBB0_982:
	s_cmp_lt_u32 s56, s54
	s_cselect_b32 s10, s56, s55
	s_lshl_b32 s10, s10, 2
	s_add_i32 s10, s3, s10
	v_mov_b32_e32 v0, s10
	ds_read_b32 v0, v0 offset:13632
	s_and_b32 s13, s66, 2.0
	s_ashr_i32 s12, s66, 20
	s_mov_b64 s[10:11], -1
	s_cmp_eq_u32 s13, 0
	s_waitcnt lgkmcnt(0)
	v_readfirstlane_b32 s92, v0
	v_add_f32_e32 v0, 4.0, v203
	s_cbranch_scc1 .LBB0_986
	s_and_b32 s13, s12, 0xfffffbff
	s_cmp_eq_u32 s13, 4
	s_cselect_b64 s[10:11], -1, 0
	s_lshl_b32 s14, s92, 7
	s_and_b32 s50, s14, 0x7fff800
	v_lshl_add_u64 v[10:11], v[86:87], 0, s[50:51]
	s_and_b32 s50, s14, 0x7fff000
	v_lshl_add_u64 v[246:247], v[10:11], 0, v[120:121]
	global_load_dwordx4 v[154:157], v[246:247], off
	global_load_dwordx4 v[158:161], v[246:247], off offset:1024
	global_load_dwordx4 v[162:165], v[246:247], off offset:2048
	global_load_dwordx4 v[166:169], v[246:247], off offset:3072
	v_lshl_add_u64 v[10:11], v[88:89], 0, s[50:51]
	v_lshl_add_u64 v[244:245], v[10:11], 0, v[120:121]
	global_load_dwordx4 v[106:109], v[244:245], off
	global_load_dwordx4 v[110:113], v[244:245], off offset:1024
	global_load_dwordx4 v[114:117], v[244:245], off offset:2048
	global_load_dwordx4 v[134:137], v[244:245], off offset:3072
	s_waitcnt vmcnt(20)
	v_mfma_f32_16x16x128_f8f6f4 v[2:5], v[186:193], v[78:85], 0
	v_cmp_eq_u32_e32 vcc, s13, v209
	s_or_b64 s[10:11], s[10:11], vcc
	v_mfma_f32_16x16x128_f8f6f4 v[6:9], v[194:201], v[78:85], 0
	v_mov_b32_e32 v202, v203
	v_mov_b32_e32 v133, v204
	s_nop 6
	v_max_f32_e32 v10, v3, v3
	v_max_f32_e32 v11, v2, v2
	v_max_f32_e32 v10, v11, v10
	v_max_f32_e32 v11, v5, v5
	v_max_f32_e32 v12, v4, v4
	v_max_f32_e32 v11, v12, v11
	v_max_f32_e32 v12, v9, v9
	v_max_f32_e32 v13, v8, v8
	v_max_f32_e32 v12, v13, v12
	v_max3_f32 v12, v6, v7, v12
	v_max3_f32 v10, v10, v11, v12
	v_cndmask_b32_e64 v34, v220, v10, s[10:11]
	v_cmp_gt_f32_e32 vcc, v34, v0
	s_cbranch_vccz .LBB0_985
	ds_bpermute_b32 v10, v225, v34
	v_max_f32_e32 v11, v34, v34
	s_waitcnt lgkmcnt(0)
	v_max_f32_e32 v10, v10, v10
	v_max_f32_e32 v10, v11, v10
	ds_bpermute_b32 v11, v224, v10
	s_waitcnt lgkmcnt(0)
	v_max3_f32 v202, v203, v10, v11
	v_sub_f32_e32 v10, v203, v202
	v_exp_f32_e32 v34, v10
	s_nop 0
	v_mul_f32_e32 v133, v204, v34
	v_pk_mul_f32 v[38:39], v[38:39], v[34:35] op_sel_hi:[1,0]
	v_pk_mul_f32 v[36:37], v[36:37], v[34:35] op_sel_hi:[1,0]
	v_pk_mul_f32 v[42:43], v[42:43], v[34:35] op_sel_hi:[1,0]
	v_pk_mul_f32 v[40:41], v[40:41], v[34:35] op_sel_hi:[1,0]
	v_pk_mul_f32 v[46:47], v[46:47], v[34:35] op_sel_hi:[1,0]
	v_pk_mul_f32 v[44:45], v[44:45], v[34:35] op_sel_hi:[1,0]
	v_pk_mul_f32 v[50:51], v[50:51], v[34:35] op_sel_hi:[1,0]
	v_pk_mul_f32 v[48:49], v[48:49], v[34:35] op_sel_hi:[1,0]
	v_pk_mul_f32 v[54:55], v[54:55], v[34:35] op_sel_hi:[1,0]
	v_pk_mul_f32 v[52:53], v[52:53], v[34:35] op_sel_hi:[1,0]
	v_pk_mul_f32 v[58:59], v[58:59], v[34:35] op_sel_hi:[1,0]
	v_pk_mul_f32 v[56:57], v[56:57], v[34:35] op_sel_hi:[1,0]
	v_pk_mul_f32 v[62:63], v[62:63], v[34:35] op_sel_hi:[1,0]
	v_pk_mul_f32 v[60:61], v[60:61], v[34:35] op_sel_hi:[1,0]
	v_pk_mul_f32 v[66:67], v[66:67], v[34:35] op_sel_hi:[1,0]
	v_pk_mul_f32 v[64:65], v[64:65], v[34:35] op_sel_hi:[1,0]

; template <bool SLC, bool NOMASK> ...
;     ...
;     const int pos0 = SLC ? (dcur & 0xfffff) : dcur;
;     const int lo = SLC ? ((((dcur >> 20) == qi) | ((dcur >> 20) == 4)) ? 0 : (1 << 30)) : lo_in;
;     load_frag8(nxt, KF, VF, SLC ? (dnext & 0xfffff) : dnext, lane);
;     f32x4 sa[2] = {(f32x4){0.f, 0.f, 0.f, 0.f}, (f32x4){0.f, 0.f, 0.f, 0.f}};
; #pragma unroll
;     for (int T = 0; T < 2; ++T)
; #pragma unroll
;         for (int s2 = 0; s2 < 4; ++s2) sa[T] = __builtin_amdgcn_mfma_f32_16x16x32_fp8_fp8(cur.k[T][s2], qf[s2], sa[T], 0, 0, 0);
;     float sc[8]; bool vd[8]; float mx = -1e30f;
;     const bool act = lo == 0 || !SLC;
;     if (NOMASK) {
; #pragma unroll
;         for (int j = 0; j < 8; ++j) { sc[j] = sa[j >> 2][j & 3]; vd[j] = act; }
;         mx = fmaxf(fmaxf(fmaxf(sc[0], sc[1]), fmaxf(sc[2], sc[3])), fmaxf(fmaxf(sc[4], sc[5]), fmaxf(sc[6], sc[7])));
;         mx = act ? mx : -1e30f;
;     } else {
; #pragma unroll
;         for (int T = 0; T < 2; ++T)
; #pragma unroll
;             for (int r = 0; r < 4; ++r) { const int p = pos0 + 16 * T + 4 * kq + r; const bool v = (p >= lo) & (p <= hi); const float x = sa[T][r];
;                 sc[4 * T + r] = x; vd[4 * T + r] = v; mx = v ? fmaxf(mx, x) : mx; }
;     }
;     if (__builtin_amdgcn_ballot_w64(mx > st.m + 4.f) != 0ull) {
;         mx = fmaxf(mx, __shfl_xor(mx, 16)); mx = fmaxf(mx, __shfl_xor(mx, 32));
;         const float mn = fmaxf(st.m, mx), alpha = __builtin_amdgcn_exp2f(st.m - mn); st.m = mn; st.l *= alpha;
; #pragma unroll
;         for (int j = 0; j < 8; ++j) st.o[j] = st.o[j] * alpha;
;     }
.LBB0_986:
	s_and_b64 vcc, exec, s[10:11]
	s_cbranch_vccz .LBB0_990
	s_cmp_eq_u32 s12, 4
	s_cselect_b64 s[10:11], -1, 0
	s_lshl_b32 s13, s92, 7
	s_and_b32 s50, s13, 0x7fff800
	v_lshl_add_u64 v[10:11], v[86:87], 0, s[50:51]
	s_and_b32 s50, s13, 0x7fff000
	v_lshl_add_u64 v[246:247], v[10:11], 0, v[120:121]
	global_load_dwordx4 v[154:157], v[246:247], off
	global_load_dwordx4 v[158:161], v[246:247], off offset:1024
	global_load_dwordx4 v[162:165], v[246:247], off offset:2048
	global_load_dwordx4 v[166:169], v[246:247], off offset:3072
	v_lshl_add_u64 v[10:11], v[88:89], 0, s[50:51]
	v_lshl_add_u64 v[244:245], v[10:11], 0, v[120:121]
	global_load_dwordx4 v[106:109], v[244:245], off
	global_load_dwordx4 v[110:113], v[244:245], off offset:1024
	global_load_dwordx4 v[114:117], v[244:245], off offset:2048
	global_load_dwordx4 v[134:137], v[244:245], off offset:3072
	s_waitcnt vmcnt(20)
	v_mfma_f32_16x16x128_f8f6f4 v[2:5], v[186:193], v[78:85], 0
	s_and_b32 s13, s66, 0xfffff
	v_cmp_eq_u32_e32 vcc, s12, v209
	v_add_u32_e32 v10, s13, v210
	v_mfma_f32_16x16x128_f8f6f4 v[6:9], v[194:201], v[78:85], 0
	s_or_b64 s[18:19], s[10:11], vcc
	v_cmp_le_i32_e32 vcc, v10, v132
	s_and_b64 s[16:17], s[18:19], vcc
	v_cmp_lt_i32_e32 vcc, v10, v132
	s_and_b64 s[12:13], s[18:19], vcc
	s_nop 5
	v_max_f32_e32 v11, v2, v2
	v_max_f32_e32 v11, 0xf149f2ca, v11
	v_cndmask_b32_e64 v11, v220, v11, s[16:17]
	v_max_f32_e32 v12, v3, v3
	v_max_f32_e32 v12, v11, v12
	v_cndmask_b32_e64 v11, v11, v12, s[12:13]
	v_add_u32_e32 v12, 2, v10
	v_cmp_le_i32_e32 vcc, v12, v132
	v_max_f32_e32 v12, v4, v4
	v_max_f32_e32 v12, v11, v12
	s_and_b64 s[14:15], s[18:19], vcc
	v_cndmask_b32_e64 v11, v11, v12, s[14:15]
	v_add_u32_e32 v12, 3, v10
	v_cmp_le_i32_e32 vcc, v12, v132
	v_max_f32_e32 v12, v5, v5
	v_max_f32_e32 v12, v11, v12
	s_and_b64 s[10:11], s[18:19], vcc
	v_cndmask_b32_e64 v11, v11, v12, s[10:11]
	v_add_u32_e32 v12, 16, v10
	v_cmp_le_i32_e32 vcc, v12, v132
	v_max_f32_e32 v12, v6, v6
	v_max_f32_e32 v12, v11, v12
	s_and_b64 s[24:25], s[18:19], vcc
	v_cndmask_b32_e64 v11, v11, v12, s[24:25]
	v_add_u32_e32 v12, 17, v10
	v_cmp_le_i32_e32 vcc, v12, v132
	v_max_f32_e32 v12, v11, v11
	v_max_f32_e32 v13, v7, v7
	v_max_f32_e32 v12, v12, v13
	s_and_b64 s[20:21], s[18:19], vcc
	v_cndmask_b32_e64 v11, v11, v12, s[20:21]
	v_add_u32_e32 v12, 18, v10
	v_cmp_le_i32_e32 vcc, v12, v132
	v_max_f32_e32 v12, v11, v11
	v_max_f32_e32 v13, v8, v8
	v_max_f32_e32 v12, v12, v13
	s_and_b64 s[22:23], s[18:19], vcc
	v_cndmask_b32_e64 v11, v11, v12, s[22:23]
	v_add_u32_e32 v10, 19, v10
	v_cmp_le_i32_e32 vcc, v10, v132
	v_max_f32_e32 v10, v11, v11
	v_max_f32_e32 v12, v9, v9
	v_max_f32_e32 v10, v10, v12
	s_and_b64 s[18:19], s[18:19], vcc
	v_cndmask_b32_e64 v10, v11, v10, s[18:19]
	v_cmp_gt_f32_e32 vcc, v10, v0
	s_cbranch_vccz .LBB0_989
	ds_bpermute_b32 v0, v225, v10
	v_max_f32_e32 v10, v10, v10
	s_waitcnt lgkmcnt(0)
	v_max_f32_e32 v0, v0, v0
	v_max_f32_e32 v0, v10, v0
	ds_bpermute_b32 v10, v224, v0
	s_waitcnt lgkmcnt(0)
	v_max3_f32 v10, v203, v0, v10
	v_sub_f32_e32 v0, v203, v10
	v_exp_f32_e32 v0, v0
	v_mov_b32_e32 v203, v10
	v_mul_f32_e32 v204, v204, v0
	v_pk_mul_f32 v[38:39], v[38:39], v[0:1] op_sel_hi:[1,0]
	v_pk_mul_f32 v[36:37], v[36:37], v[0:1] op_sel_hi:[1,0]
	v_pk_mul_f32 v[42:43], v[42:43], v[0:1] op_sel_hi:[1,0]
	v_pk_mul_f32 v[40:41], v[40:41], v[0:1] op_sel_hi:[1,0]
	v_pk_mul_f32 v[46:47], v[46:47], v[0:1] op_sel_hi:[1,0]
	v_pk_mul_f32 v[44:45], v[44:45], v[0:1] op_sel_hi:[1,0]
	v_pk_mul_f32 v[50:51], v[50:51], v[0:1] op_sel_hi:[1,0]
	v_pk_mul_f32 v[48:49], v[48:49], v[0:1] op_sel_hi:[1,0]
	v_pk_mul_f32 v[54:55], v[54:55], v[0:1] op_sel_hi:[1,0]
	v_pk_mul_f32 v[52:53], v[52:53], v[0:1] op_sel_hi:[1,0]
	v_pk_mul_f32 v[58:59], v[58:59], v[0:1] op_sel_hi:[1,0]
	v_pk_mul_f32 v[56:57], v[56:57], v[0:1] op_sel_hi:[1,0]
	v_pk_mul_f32 v[62:63], v[62:63], v[0:1] op_sel_hi:[1,0]
	v_pk_mul_f32 v[60:61], v[60:61], v[0:1] op_sel_hi:[1,0]
	v_pk_mul_f32 v[66:67], v[66:67], v[0:1] op_sel_hi:[1,0]
	v_pk_mul_f32 v[64:65], v[64:65], v[0:1] op_sel_hi:[1,0]

; template <bool SLC, bool NOMASK> ...
;     ...
;     load_frag8(nxt, KF, VF, SLC ? (dnext & 0xfffff) : dnext, lane);
;     f32x4 sa[2] = {(f32x4){0.f, 0.f, 0.f, 0.f}, (f32x4){0.f, 0.f, 0.f, 0.f}};
; #pragma unroll
;     for (int T = 0; T < 2; ++T)
; #pragma unroll
;         for (int s2 = 0; s2 < 4; ++s2) sa[T] = __builtin_amdgcn_mfma_f32_16x16x32_fp8_fp8(cur.k[T][s2], qf[s2], sa[T], 0, 0, 0);
;     float sc[8]; bool vd[8]; float mx = -1e30f;
;     const bool act = lo == 0 || !SLC;
;     if (NOMASK) {
; #pragma unroll
;         for (int j = 0; j < 8; ++j) { sc[j] = sa[j >> 2][j & 3]; vd[j] = act; }
;         mx = fmaxf(fmaxf(fmaxf(sc[0], sc[1]), fmaxf(sc[2], sc[3])), fmaxf(fmaxf(sc[4], sc[5]), fmaxf(sc[6], sc[7])));
;         mx = act ? mx : -1e30f;
;     } else {
; #pragma unroll
;         for (int T = 0; T < 2; ++T)
; #pragma unroll
;             for (int r = 0; r < 4; ++r) { const int p = pos0 + 16 * T + 4 * kq + r; const bool v = (p >= lo) & (p <= hi); const float x = sa[T][r];
;                 sc[4 * T + r] = x; vd[4 * T + r] = v; mx = v ? fmaxf(mx, x) : mx; }
;     }
;     if (__builtin_amdgcn_ballot_w64(mx > st.m + 4.f) != 0ull) {
;         mx = fmaxf(mx, __shfl_xor(mx, 16)); mx = fmaxf(mx, __shfl_xor(mx, 32));
;         const float mn = fmaxf(st.m, mx), alpha = __builtin_amdgcn_exp2f(st.m - mn); st.m = mn; st.l *= alpha;
; #pragma unroll
;         for (int j = 0; j < 8; ++j) st.o[j] = st.o[j] * alpha;
;     }
.LBB0_1002:
	v_lshl_add_u64 v[246:247], v[204:205], 0, v[120:121]
	global_load_dwordx4 v[186:189], v[246:247], off
	global_load_dwordx4 v[190:193], v[246:247], off offset:1024
	global_load_dwordx4 v[194:197], v[246:247], off offset:2048
	global_load_dwordx4 v[198:201], v[246:247], off offset:3072
	v_lshl_add_u64 v[244:245], v[202:203], 0, v[120:121]
	global_load_dwordx4 v[170:173], v[244:245], off
	global_load_dwordx4 v[174:177], v[244:245], off offset:1024
	global_load_dwordx4 v[178:181], v[244:245], off offset:2048
	global_load_dwordx4 v[182:185], v[244:245], off offset:3072
	s_waitcnt vmcnt(20)
	v_mfma_f32_16x16x128_f8f6f4 v[2:5], v[138:145], v[78:85], 0
	v_mfma_f32_16x16x128_f8f6f4 v[6:9], v[146:153], v[78:85], 0
	v_mov_b32_e32 v228, v133
	v_mov_b32_e32 v34, v227
	s_nop 8
	v_max_f32_e32 v0, v3, v3
	v_max_f32_e32 v10, v2, v2
	v_max_f32_e32 v0, v10, v0
	v_max_f32_e32 v10, v5, v5
	v_max_f32_e32 v11, v4, v4
	v_max_f32_e32 v10, v11, v10
	v_max_f32_e32 v11, v9, v9
	v_max_f32_e32 v12, v8, v8
	v_max_f32_e32 v11, v12, v11
	v_max3_f32 v11, v6, v7, v11
	v_max3_f32 v0, v0, v10, v11
	v_add_f32_e32 v10, 4.0, v133
	v_cmp_gt_f32_e32 vcc, v0, v10
	s_cbranch_vccz .LBB0_1004
	ds_bpermute_b32 v10, v225, v0
	v_max_f32_e32 v0, v0, v0
	s_waitcnt lgkmcnt(0)
	v_max_f32_e32 v10, v10, v10
	v_max_f32_e32 v0, v0, v10
	ds_bpermute_b32 v10, v224, v0
	s_waitcnt lgkmcnt(0)
	v_max3_f32 v228, v133, v0, v10
	v_sub_f32_e32 v0, v133, v228
	v_exp_f32_e32 v0, v0
	s_nop 0
	v_mul_f32_e32 v34, v227, v0
	v_pk_mul_f32 v[66:67], v[66:67], v[0:1] op_sel_hi:[1,0]
	v_pk_mul_f32 v[64:65], v[64:65], v[0:1] op_sel_hi:[1,0]
	v_pk_mul_f32 v[62:63], v[62:63], v[0:1] op_sel_hi:[1,0]
	v_pk_mul_f32 v[60:61], v[60:61], v[0:1] op_sel_hi:[1,0]
	v_pk_mul_f32 v[58:59], v[58:59], v[0:1] op_sel_hi:[1,0]
	v_pk_mul_f32 v[56:57], v[56:57], v[0:1] op_sel_hi:[1,0]
	v_pk_mul_f32 v[54:55], v[54:55], v[0:1] op_sel_hi:[1,0]
	v_pk_mul_f32 v[52:53], v[52:53], v[0:1] op_sel_hi:[1,0]
	v_pk_mul_f32 v[50:51], v[50:51], v[0:1] op_sel_hi:[1,0]
	v_pk_mul_f32 v[48:49], v[48:49], v[0:1] op_sel_hi:[1,0]
	v_pk_mul_f32 v[46:47], v[46:47], v[0:1] op_sel_hi:[1,0]
	v_pk_mul_f32 v[44:45], v[44:45], v[0:1] op_sel_hi:[1,0]
	v_pk_mul_f32 v[42:43], v[42:43], v[0:1] op_sel_hi:[1,0]
	v_pk_mul_f32 v[40:41], v[40:41], v[0:1] op_sel_hi:[1,0]
	v_pk_mul_f32 v[38:39], v[38:39], v[0:1] op_sel_hi:[1,0]
	v_pk_mul_f32 v[36:37], v[36:37], v[0:1] op_sel_hi:[1,0]

; template <bool SLC, bool NOMASK> ...
;     ...
;     load_frag8(nxt, KF, VF, SLC ? (dnext & 0xfffff) : dnext, lane);
;     f32x4 sa[2] = {(f32x4){0.f, 0.f, 0.f, 0.f}, (f32x4){0.f, 0.f, 0.f, 0.f}};
; #pragma unroll
;     for (int T = 0; T < 2; ++T)
; #pragma unroll
;         for (int s2 = 0; s2 < 4; ++s2) sa[T] = __builtin_amdgcn_mfma_f32_16x16x32_fp8_fp8(cur.k[T][s2], qf[s2], sa[T], 0, 0, 0);
;     float sc[8]; bool vd[8]; float mx = -1e30f;
;     const bool act = lo == 0 || !SLC;
;     if (NOMASK) {
; #pragma unroll
;         for (int j = 0; j < 8; ++j) { sc[j] = sa[j >> 2][j & 3]; vd[j] = act; }
;         mx = fmaxf(fmaxf(fmaxf(sc[0], sc[1]), fmaxf(sc[2], sc[3])), fmaxf(fmaxf(sc[4], sc[5]), fmaxf(sc[6], sc[7])));
;         mx = act ? mx : -1e30f;
;     } else {
; #pragma unroll
;         for (int T = 0; T < 2; ++T)
; #pragma unroll
;             for (int r = 0; r < 4; ++r) { const int p = pos0 + 16 * T + 4 * kq + r; const bool v = (p >= lo) & (p <= hi); const float x = sa[T][r];
;                 sc[4 * T + r] = x; vd[4 * T + r] = v; mx = v ? fmaxf(mx, x) : mx; }
;     }
;     if (__builtin_amdgcn_ballot_w64(mx > st.m + 4.f) != 0ull) {
;         mx = fmaxf(mx, __shfl_xor(mx, 16)); mx = fmaxf(mx, __shfl_xor(mx, 32));
;         const float mn = fmaxf(st.m, mx), alpha = __builtin_amdgcn_exp2f(st.m - mn); st.m = mn; st.l *= alpha;
; #pragma unroll
;         for (int j = 0; j < 8; ++j) st.o[j] = st.o[j] * alpha;
;     }
.LBB0_1005:
	v_lshl_add_u64 v[246:247], v[204:205], 0, v[120:121]
	global_load_dwordx4 v[186:189], v[246:247], off
	global_load_dwordx4 v[190:193], v[246:247], off offset:1024
	global_load_dwordx4 v[194:197], v[246:247], off offset:2048
	global_load_dwordx4 v[198:201], v[246:247], off offset:3072
	v_lshl_add_u64 v[244:245], v[202:203], 0, v[120:121]
	global_load_dwordx4 v[170:173], v[244:245], off
	global_load_dwordx4 v[174:177], v[244:245], off offset:1024
	global_load_dwordx4 v[178:181], v[244:245], off offset:2048
	global_load_dwordx4 v[182:185], v[244:245], off offset:3072
	s_waitcnt vmcnt(20)
	v_mfma_f32_16x16x128_f8f6f4 v[2:5], v[138:145], v[78:85], 0
	v_add_u32_e32 v0, s14, v210
	v_cmp_ge_i32_e32 vcc, v0, v35
	v_cmp_le_i32_e64 s[10:11], v0, v132
	v_mfma_f32_16x16x128_f8f6f4 v[6:9], v[146:153], v[78:85], 0
	s_and_b64 s[16:17], vcc, s[10:11]
	v_add_u32_e32 v11, 1, v0
	v_cmp_ge_i32_e32 vcc, v11, v35
	v_cmp_lt_i32_e64 s[10:11], v0, v132
	s_and_b64 s[12:13], s[10:11], vcc
	s_nop 5
	v_max_f32_e32 v10, v2, v2
	v_max_f32_e32 v10, 0xf149f2ca, v10
	v_cndmask_b32_e64 v10, v220, v10, s[16:17]
	v_max_f32_e32 v11, v3, v3
	v_max_f32_e32 v11, v10, v11
	v_cndmask_b32_e64 v10, v10, v11, s[12:13]
	v_add_u32_e32 v11, 2, v0
	v_cmp_ge_i32_e32 vcc, v11, v35
	v_cmp_le_i32_e64 s[10:11], v11, v132
	v_max_f32_e32 v11, v4, v4
	v_max_f32_e32 v11, v10, v11
	s_and_b64 s[14:15], vcc, s[10:11]
	v_cndmask_b32_e64 v10, v10, v11, s[14:15]
	v_add_u32_e32 v11, 3, v0
	v_cmp_ge_i32_e32 vcc, v11, v35
	v_cmp_le_i32_e64 s[10:11], v11, v132
	v_max_f32_e32 v11, v5, v5
	v_max_f32_e32 v11, v10, v11
	s_and_b64 s[10:11], vcc, s[10:11]
	v_cndmask_b32_e64 v10, v10, v11, s[10:11]
	v_add_u32_e32 v11, 16, v0
	v_cmp_ge_i32_e32 vcc, v11, v35
	v_cmp_le_i32_e64 s[18:19], v11, v132
	v_max_f32_e32 v11, v6, v6
	v_max_f32_e32 v11, v10, v11
	s_and_b64 s[24:25], vcc, s[18:19]
	v_cndmask_b32_e64 v10, v10, v11, s[24:25]
	v_add_u32_e32 v11, 17, v0
	v_cmp_ge_i32_e32 vcc, v11, v35
	v_cmp_le_i32_e64 s[18:19], v11, v132
	v_max_f32_e32 v11, v10, v10
	v_max_f32_e32 v12, v7, v7
	v_max_f32_e32 v11, v11, v12
	s_and_b64 s[20:21], vcc, s[18:19]
	v_cndmask_b32_e64 v10, v10, v11, s[20:21]
	v_add_u32_e32 v11, 18, v0
	v_cmp_ge_i32_e32 vcc, v11, v35
	v_cmp_le_i32_e64 s[18:19], v11, v132
	v_max_f32_e32 v11, v10, v10
	v_max_f32_e32 v12, v8, v8
	v_max_f32_e32 v11, v11, v12
	s_and_b64 s[22:23], vcc, s[18:19]
	v_cndmask_b32_e64 v10, v10, v11, s[22:23]
	v_add_u32_e32 v0, 19, v0
	v_cmp_ge_i32_e32 vcc, v0, v35
	v_cmp_le_i32_e64 s[18:19], v0, v132
	v_max_f32_e32 v0, v10, v10
	v_max_f32_e32 v11, v9, v9
	v_max_f32_e32 v0, v0, v11
	s_and_b64 s[18:19], vcc, s[18:19]
	v_cndmask_b32_e64 v0, v10, v0, s[18:19]
	v_add_f32_e32 v10, 4.0, v133
	v_cmp_gt_f32_e32 vcc, v0, v10
	s_cbranch_vccz .LBB0_1007
	ds_bpermute_b32 v10, v225, v0
	v_max_f32_e32 v0, v0, v0
	s_waitcnt lgkmcnt(0)
	v_max_f32_e32 v10, v10, v10
	v_max_f32_e32 v0, v0, v10
	ds_bpermute_b32 v10, v224, v0
	s_waitcnt lgkmcnt(0)
	v_max3_f32 v10, v133, v0, v10
	v_sub_f32_e32 v0, v133, v10
	v_exp_f32_e32 v0, v0
	v_mov_b32_e32 v133, v10
	v_mul_f32_e32 v227, v227, v0
	v_pk_mul_f32 v[66:67], v[66:67], v[0:1] op_sel_hi:[1,0]
	v_pk_mul_f32 v[64:65], v[64:65], v[0:1] op_sel_hi:[1,0]
	v_pk_mul_f32 v[62:63], v[62:63], v[0:1] op_sel_hi:[1,0]
	v_pk_mul_f32 v[60:61], v[60:61], v[0:1] op_sel_hi:[1,0]
	v_pk_mul_f32 v[58:59], v[58:59], v[0:1] op_sel_hi:[1,0]
	v_pk_mul_f32 v[56:57], v[56:57], v[0:1] op_sel_hi:[1,0]
	v_pk_mul_f32 v[54:55], v[54:55], v[0:1] op_sel_hi:[1,0]
	v_pk_mul_f32 v[52:53], v[52:53], v[0:1] op_sel_hi:[1,0]
	v_pk_mul_f32 v[50:51], v[50:51], v[0:1] op_sel_hi:[1,0]
	v_pk_mul_f32 v[48:49], v[48:49], v[0:1] op_sel_hi:[1,0]
	v_pk_mul_f32 v[46:47], v[46:47], v[0:1] op_sel_hi:[1,0]
	v_pk_mul_f32 v[44:45], v[44:45], v[0:1] op_sel_hi:[1,0]
	v_pk_mul_f32 v[42:43], v[42:43], v[0:1] op_sel_hi:[1,0]
	v_pk_mul_f32 v[40:41], v[40:41], v[0:1] op_sel_hi:[1,0]
	v_pk_mul_f32 v[38:39], v[38:39], v[0:1] op_sel_hi:[1,0]
	v_pk_mul_f32 v[36:37], v[36:37], v[0:1] op_sel_hi:[1,0]

; template <bool SLC, bool NOMASK> ...
;     ...
;     load_frag8(nxt, KF, VF, SLC ? (dnext & 0xfffff) : dnext, lane);
;     f32x4 sa[2] = {(f32x4){0.f, 0.f, 0.f, 0.f}, (f32x4){0.f, 0.f, 0.f, 0.f}};
; #pragma unroll
;     for (int T = 0; T < 2; ++T)
; #pragma unroll
;         for (int s2 = 0; s2 < 4; ++s2) sa[T] = __builtin_amdgcn_mfma_f32_16x16x32_fp8_fp8(cur.k[T][s2], qf[s2], sa[T], 0, 0, 0);
;     float sc[8]; bool vd[8]; float mx = -1e30f;
;     const bool act = lo == 0 || !SLC;
;     if (NOMASK) {
; #pragma unroll
;         for (int j = 0; j < 8; ++j) { sc[j] = sa[j >> 2][j & 3]; vd[j] = act; }
;         mx = fmaxf(fmaxf(fmaxf(sc[0], sc[1]), fmaxf(sc[2], sc[3])), fmaxf(fmaxf(sc[4], sc[5]), fmaxf(sc[6], sc[7])));
;         mx = act ? mx : -1e30f;
;     } else {
; #pragma unroll
;         for (int T = 0; T < 2; ++T)
; #pragma unroll
;             for (int r = 0; r < 4; ++r) { const int p = pos0 + 16 * T + 4 * kq + r; const bool v = (p >= lo) & (p <= hi); const float x = sa[T][r];
;                 sc[4 * T + r] = x; vd[4 * T + r] = v; mx = v ? fmaxf(mx, x) : mx; }
;     }
;     if (__builtin_amdgcn_ballot_w64(mx > st.m + 4.f) != 0ull) {
;         mx = fmaxf(mx, __shfl_xor(mx, 16)); mx = fmaxf(mx, __shfl_xor(mx, 32));
;         const float mn = fmaxf(st.m, mx), alpha = __builtin_amdgcn_exp2f(st.m - mn); st.m = mn; st.l *= alpha;
; #pragma unroll
;         for (int j = 0; j < 8; ++j) st.o[j] = st.o[j] * alpha;
;     }
.LBB0_1009:
	v_lshl_add_u64 v[246:247], v[204:205], 0, v[120:121]
	global_load_dwordx4 v[138:141], v[246:247], off
	global_load_dwordx4 v[142:145], v[246:247], off offset:1024
	global_load_dwordx4 v[146:149], v[246:247], off offset:2048
	global_load_dwordx4 v[150:153], v[246:247], off offset:3072
	v_lshl_add_u64 v[244:245], v[202:203], 0, v[120:121]
	global_load_dwordx4 v[90:93], v[244:245], off
	global_load_dwordx4 v[94:97], v[244:245], off offset:1024
	global_load_dwordx4 v[98:101], v[244:245], off offset:2048
	global_load_dwordx4 v[102:105], v[244:245], off offset:3072
	s_waitcnt vmcnt(20)
	v_mfma_f32_16x16x128_f8f6f4 v[36:39], v[154:161], v[78:85], 0
	v_mfma_f32_16x16x128_f8f6f4 v[40:43], v[162:169], v[78:85], 0
	v_mov_b32_e32 v227, v228
	v_mov_b32_e32 v229, v34
	s_nop 8
	v_max_f32_e32 v0, v37, v37
	v_max_f32_e32 v44, v36, v36
	v_max_f32_e32 v0, v44, v0
	v_max_f32_e32 v44, v39, v39
	v_max_f32_e32 v45, v38, v38
	v_max_f32_e32 v44, v45, v44
	v_max_f32_e32 v45, v43, v43
	v_max_f32_e32 v46, v42, v42
	v_max_f32_e32 v45, v46, v45
	v_max3_f32 v45, v40, v41, v45
	v_max3_f32 v0, v0, v44, v45
	v_cmp_gt_f32_e32 vcc, v0, v133
	s_cbranch_vccz .LBB0_1011
	ds_bpermute_b32 v44, v225, v0
	v_max_f32_e32 v0, v0, v0
	s_waitcnt lgkmcnt(0)
	v_max_f32_e32 v44, v44, v44
	v_max_f32_e32 v0, v0, v44
	ds_bpermute_b32 v44, v224, v0
	s_waitcnt lgkmcnt(0)
	v_max3_f32 v227, v228, v0, v44
	v_sub_f32_e32 v0, v228, v227
	v_exp_f32_e32 v0, v0
	s_nop 0
	v_mul_f32_e32 v229, v34, v0
	v_pk_mul_f32 v[8:9], v[8:9], v[0:1] op_sel_hi:[1,0]
	v_pk_mul_f32 v[6:7], v[6:7], v[0:1] op_sel_hi:[1,0]
	v_pk_mul_f32 v[12:13], v[12:13], v[0:1] op_sel_hi:[1,0]
	v_pk_mul_f32 v[10:11], v[10:11], v[0:1] op_sel_hi:[1,0]
	v_pk_mul_f32 v[16:17], v[16:17], v[0:1] op_sel_hi:[1,0]
	v_pk_mul_f32 v[14:15], v[14:15], v[0:1] op_sel_hi:[1,0]
	v_pk_mul_f32 v[20:21], v[20:21], v[0:1] op_sel_hi:[1,0]
	v_pk_mul_f32 v[18:19], v[18:19], v[0:1] op_sel_hi:[1,0]
	v_pk_mul_f32 v[24:25], v[24:25], v[0:1] op_sel_hi:[1,0]
	v_pk_mul_f32 v[22:23], v[22:23], v[0:1] op_sel_hi:[1,0]
	v_pk_mul_f32 v[28:29], v[28:29], v[0:1] op_sel_hi:[1,0]
	v_pk_mul_f32 v[26:27], v[26:27], v[0:1] op_sel_hi:[1,0]
	v_pk_mul_f32 v[32:33], v[32:33], v[0:1] op_sel_hi:[1,0]
	v_pk_mul_f32 v[30:31], v[30:31], v[0:1] op_sel_hi:[1,0]
	v_pk_mul_f32 v[4:5], v[4:5], v[0:1] op_sel_hi:[1,0]
	v_pk_mul_f32 v[2:3], v[2:3], v[0:1] op_sel_hi:[1,0]

; template <bool SLC, bool NOMASK> ...
;     ...
;     load_frag8(nxt, KF, VF, SLC ? (dnext & 0xfffff) : dnext, lane);
;     f32x4 sa[2] = {(f32x4){0.f, 0.f, 0.f, 0.f}, (f32x4){0.f, 0.f, 0.f, 0.f}};
; #pragma unroll
;     for (int T = 0; T < 2; ++T)
; #pragma unroll
;         for (int s2 = 0; s2 < 4; ++s2) sa[T] = __builtin_amdgcn_mfma_f32_16x16x32_fp8_fp8(cur.k[T][s2], qf[s2], sa[T], 0, 0, 0);
;     float sc[8]; bool vd[8]; float mx = -1e30f;
;     const bool act = lo == 0 || !SLC;
;     if (NOMASK) {
; #pragma unroll
;         for (int j = 0; j < 8; ++j) { sc[j] = sa[j >> 2][j & 3]; vd[j] = act; }
;         mx = fmaxf(fmaxf(fmaxf(sc[0], sc[1]), fmaxf(sc[2], sc[3])), fmaxf(fmaxf(sc[4], sc[5]), fmaxf(sc[6], sc[7])));
;         mx = act ? mx : -1e30f;
;     } else {
; #pragma unroll
;         for (int T = 0; T < 2; ++T)
; #pragma unroll
;             for (int r = 0; r < 4; ++r) { const int p = pos0 + 16 * T + 4 * kq + r; const bool v = (p >= lo) & (p <= hi); const float x = sa[T][r];
;                 sc[4 * T + r] = x; vd[4 * T + r] = v; mx = v ? fmaxf(mx, x) : mx; }
;     }
;     if (__builtin_amdgcn_ballot_w64(mx > st.m + 4.f) != 0ull) {
;         mx = fmaxf(mx, __shfl_xor(mx, 16)); mx = fmaxf(mx, __shfl_xor(mx, 32));
;         const float mn = fmaxf(st.m, mx), alpha = __builtin_amdgcn_exp2f(st.m - mn); st.m = mn; st.l *= alpha;
; #pragma unroll
;         for (int j = 0; j < 8; ++j) st.o[j] = st.o[j] * alpha;
;     }
.LBB0_1012:
	v_lshl_add_u64 v[246:247], v[204:205], 0, v[120:121]
	global_load_dwordx4 v[138:141], v[246:247], off
	global_load_dwordx4 v[142:145], v[246:247], off offset:1024
	global_load_dwordx4 v[146:149], v[246:247], off offset:2048
	global_load_dwordx4 v[150:153], v[246:247], off offset:3072
	v_lshl_add_u64 v[244:245], v[202:203], 0, v[120:121]
	global_load_dwordx4 v[90:93], v[244:245], off
	global_load_dwordx4 v[94:97], v[244:245], off offset:1024
	global_load_dwordx4 v[98:101], v[244:245], off offset:2048
	global_load_dwordx4 v[102:105], v[244:245], off offset:3072
	s_waitcnt vmcnt(20)
	v_mfma_f32_16x16x128_f8f6f4 v[36:39], v[154:161], v[78:85], 0
	v_add_u32_e32 v0, s66, v210
	v_cmp_ge_i32_e32 vcc, v0, v35
	v_cmp_le_i32_e64 s[10:11], v0, v132
	v_mfma_f32_16x16x128_f8f6f4 v[40:43], v[162:169], v[78:85], 0
	s_and_b64 s[16:17], vcc, s[10:11]
	v_add_u32_e32 v45, 1, v0
	v_cmp_ge_i32_e32 vcc, v45, v35
	v_cmp_lt_i32_e64 s[10:11], v0, v132
	s_and_b64 s[12:13], s[10:11], vcc
	s_nop 5
	v_max_f32_e32 v44, v36, v36
	v_max_f32_e32 v44, 0xf149f2ca, v44
	v_cndmask_b32_e64 v44, v220, v44, s[16:17]
	v_max_f32_e32 v45, v37, v37
	v_max_f32_e32 v45, v44, v45
	v_cndmask_b32_e64 v44, v44, v45, s[12:13]
	v_add_u32_e32 v45, 2, v0
	v_cmp_ge_i32_e32 vcc, v45, v35
	v_cmp_le_i32_e64 s[10:11], v45, v132
	v_max_f32_e32 v45, v38, v38
	v_max_f32_e32 v45, v44, v45
	s_and_b64 s[14:15], vcc, s[10:11]
	v_cndmask_b32_e64 v44, v44, v45, s[14:15]
	v_add_u32_e32 v45, 3, v0
	v_cmp_ge_i32_e32 vcc, v45, v35
	v_cmp_le_i32_e64 s[10:11], v45, v132
	v_max_f32_e32 v45, v39, v39
	v_max_f32_e32 v45, v44, v45
	s_and_b64 s[10:11], vcc, s[10:11]
	v_cndmask_b32_e64 v44, v44, v45, s[10:11]
	v_add_u32_e32 v45, 16, v0
	v_cmp_ge_i32_e32 vcc, v45, v35
	v_cmp_le_i32_e64 s[18:19], v45, v132
	v_max_f32_e32 v45, v40, v40
	v_max_f32_e32 v45, v44, v45
	s_and_b64 s[24:25], vcc, s[18:19]
	v_cndmask_b32_e64 v44, v44, v45, s[24:25]
	v_add_u32_e32 v45, 17, v0
	v_cmp_ge_i32_e32 vcc, v45, v35
	v_cmp_le_i32_e64 s[18:19], v45, v132
	v_max_f32_e32 v45, v44, v44
	v_max_f32_e32 v46, v41, v41
	v_max_f32_e32 v45, v45, v46
	s_and_b64 s[20:21], vcc, s[18:19]
	v_cndmask_b32_e64 v44, v44, v45, s[20:21]
	v_add_u32_e32 v45, 18, v0
	v_cmp_ge_i32_e32 vcc, v45, v35
	v_cmp_le_i32_e64 s[18:19], v45, v132
	v_max_f32_e32 v45, v44, v44
	v_max_f32_e32 v46, v42, v42
	v_max_f32_e32 v45, v45, v46
	s_and_b64 s[22:23], vcc, s[18:19]
	v_cndmask_b32_e64 v44, v44, v45, s[22:23]
	v_add_u32_e32 v0, 19, v0
	v_cmp_ge_i32_e32 vcc, v0, v35
	v_cmp_le_i32_e64 s[18:19], v0, v132
	v_max_f32_e32 v0, v44, v44
	v_max_f32_e32 v45, v43, v43
	v_max_f32_e32 v0, v0, v45
	s_and_b64 s[18:19], vcc, s[18:19]
	v_cndmask_b32_e64 v0, v44, v0, s[18:19]
	v_cmp_gt_f32_e32 vcc, v0, v133
	s_cbranch_vccz .LBB0_1014
	ds_bpermute_b32 v44, v225, v0
	v_max_f32_e32 v0, v0, v0
	s_waitcnt lgkmcnt(0)
	v_max_f32_e32 v44, v44, v44
	v_max_f32_e32 v0, v0, v44
	ds_bpermute_b32 v44, v224, v0
	s_waitcnt lgkmcnt(0)
	v_max3_f32 v44, v228, v0, v44
	v_sub_f32_e32 v0, v228, v44
	v_exp_f32_e32 v0, v0
	v_mov_b32_e32 v228, v44
	v_mul_f32_e32 v34, v34, v0
	v_pk_mul_f32 v[8:9], v[8:9], v[0:1] op_sel_hi:[1,0]
	v_pk_mul_f32 v[6:7], v[6:7], v[0:1] op_sel_hi:[1,0]
	v_pk_mul_f32 v[12:13], v[12:13], v[0:1] op_sel_hi:[1,0]
	v_pk_mul_f32 v[10:11], v[10:11], v[0:1] op_sel_hi:[1,0]
	v_pk_mul_f32 v[16:17], v[16:17], v[0:1] op_sel_hi:[1,0]
	v_pk_mul_f32 v[14:15], v[14:15], v[0:1] op_sel_hi:[1,0]
	v_pk_mul_f32 v[20:21], v[20:21], v[0:1] op_sel_hi:[1,0]
	v_pk_mul_f32 v[18:19], v[18:19], v[0:1] op_sel_hi:[1,0]
	v_pk_mul_f32 v[24:25], v[24:25], v[0:1] op_sel_hi:[1,0]
	v_pk_mul_f32 v[22:23], v[22:23], v[0:1] op_sel_hi:[1,0]
	v_pk_mul_f32 v[28:29], v[28:29], v[0:1] op_sel_hi:[1,0]
	v_pk_mul_f32 v[26:27], v[26:27], v[0:1] op_sel_hi:[1,0]
	v_pk_mul_f32 v[32:33], v[32:33], v[0:1] op_sel_hi:[1,0]
	v_pk_mul_f32 v[30:31], v[30:31], v[0:1] op_sel_hi:[1,0]
	v_pk_mul_f32 v[4:5], v[4:5], v[0:1] op_sel_hi:[1,0]
	v_pk_mul_f32 v[2:3], v[2:3], v[0:1] op_sel_hi:[1,0]

; template <bool SLC, bool NOMASK> ...
;     ...
;     const int pos0 = SLC ? (dcur & 0xfffff) : dcur;
;     const int lo = SLC ? ((((dcur >> 20) == qi) | ((dcur >> 20) == 4)) ? 0 : (1 << 30)) : lo_in;
;     load_frag8(nxt, KF, VF, SLC ? (dnext & 0xfffff) : dnext, lane);
;     f32x4 sa[2] = {(f32x4){0.f, 0.f, 0.f, 0.f}, (f32x4){0.f, 0.f, 0.f, 0.f}};
; #pragma unroll
;     for (int T = 0; T < 2; ++T)
; #pragma unroll
;         for (int s2 = 0; s2 < 4; ++s2) sa[T] = __builtin_amdgcn_mfma_f32_16x16x32_fp8_fp8(cur.k[T][s2], qf[s2], sa[T], 0, 0, 0);
;     float sc[8]; bool vd[8]; float mx = -1e30f;
;     const bool act = lo == 0 || !SLC;
;     if (NOMASK) {
; #pragma unroll
;         for (int j = 0; j < 8; ++j) { sc[j] = sa[j >> 2][j & 3]; vd[j] = act; }
;         mx = fmaxf(fmaxf(fmaxf(sc[0], sc[1]), fmaxf(sc[2], sc[3])), fmaxf(fmaxf(sc[4], sc[5]), fmaxf(sc[6], sc[7])));
;         mx = act ? mx : -1e30f;
;     } else {
; #pragma unroll
;         for (int T = 0; T < 2; ++T)
; #pragma unroll
;             for (int r = 0; r < 4; ++r) { const int p = pos0 + 16 * T + 4 * kq + r; const bool v = (p >= lo) & (p <= hi); const float x = sa[T][r];
;                 sc[4 * T + r] = x; vd[4 * T + r] = v; mx = v ? fmaxf(mx, x) : mx; }
;     }
;     if (__builtin_amdgcn_ballot_w64(mx > st.m + 4.f) != 0ull) {
;         mx = fmaxf(mx, __shfl_xor(mx, 16)); mx = fmaxf(mx, __shfl_xor(mx, 32));
;         const float mn = fmaxf(st.m, mx), alpha = __builtin_amdgcn_exp2f(st.m - mn); st.m = mn; st.l *= alpha;
; #pragma unroll
;         for (int j = 0; j < 8; ++j) st.o[j] = st.o[j] * alpha;
;     }
; __device__ __forceinline__ void nsa_unit(int unit, const bf16_t* proj, const bf16_t* kc, const bf16_t* vc, const bf16_t* gn, const float* cs, const float* sn, ...
;     ...
;       auto desc = [&](int i) { const int p0 = 32 * (first + i); return p0 | ((p0 >= t0 + 3 - 511 && p0 + 31 <= t0) ? (1 << 30) : 0); };
;       unsigned long long goff = (unsigned long long)g * S * 128; asm volatile("" : "+s"(goff));
;       attn_run_frag8<false>(q8, (const unsigned char*)kslf + ((size_t)16 << 20) + goff, (const unsigned char*)kslf + ((size_t)24 << 20) + goff, desc, last - first + 1, lo, tc, 0, st, lane); }
.LBB0_1015:
	s_cmp_lt_i32 s57, s54
	s_cselect_b64 s[10:11], -1, 0
	s_or_b32 s12, s57, 31
	s_cmp_gt_i32 s12, s90
	s_cselect_b64 s[12:13], -1, 0
	s_or_b64 s[10:11], s[10:11], s[12:13]
	s_and_b64 s[10:11], s[10:11], exec
	s_cselect_b32 s10, 0, 2.0
	s_add_i32 s56, s56, 4
	s_or_b32 s14, s10, s57
	s_min_i32 s10, s56, s27
	s_add_i32 s12, s10, s26
	s_lshl_b32 s43, s12, 5
	s_and_b32 s10, s43, 0x3fffffe0
	s_lshr_b32 s50, s10, 4
	s_lshl_b64 s[10:11], s[50:51], 11
	s_and_b32 s50, s12, 0x1ffffff
	s_lshl_b64 s[12:13], s[50:51], 12
	s_cmp_lt_u32 s14, 2.0
	v_lshl_add_u64 v[204:205], v[86:87], 0, s[10:11]
	v_lshl_add_u64 v[202:203], v[88:89], 0, s[12:13]
	s_mov_b64 s[10:11], -1
	v_add_f32_e32 v228, 4.0, v227
	s_cbranch_scc1 .LBB0_1019
	v_lshl_add_u64 v[246:247], v[204:205], 0, v[120:121]
	global_load_dwordx4 v[154:157], v[246:247], off
	global_load_dwordx4 v[158:161], v[246:247], off offset:1024
	global_load_dwordx4 v[162:165], v[246:247], off offset:2048
	global_load_dwordx4 v[166:169], v[246:247], off offset:3072
	v_lshl_add_u64 v[244:245], v[202:203], 0, v[120:121]
	global_load_dwordx4 v[106:109], v[244:245], off
	global_load_dwordx4 v[110:113], v[244:245], off offset:1024
	global_load_dwordx4 v[114:117], v[244:245], off offset:2048
	global_load_dwordx4 v[134:137], v[244:245], off offset:3072
	s_waitcnt vmcnt(20)
	v_mfma_f32_16x16x128_f8f6f4 v[2:5], v[186:193], v[78:85], 0
	v_mfma_f32_16x16x128_f8f6f4 v[6:9], v[194:201], v[78:85], 0
	v_mov_b32_e32 v133, v227
	v_mov_b32_e32 v34, v229
	s_nop 8
	v_max_f32_e32 v0, v3, v3
	v_max_f32_e32 v10, v2, v2
	v_max_f32_e32 v0, v10, v0
	v_max_f32_e32 v10, v5, v5
	v_max_f32_e32 v11, v4, v4
	v_max_f32_e32 v10, v11, v10
	v_max_f32_e32 v11, v9, v9
	v_max_f32_e32 v12, v8, v8
	v_max_f32_e32 v11, v12, v11
	v_max3_f32 v11, v6, v7, v11
	v_max3_f32 v0, v0, v10, v11
	v_cmp_gt_f32_e32 vcc, v0, v228
	s_cbranch_vccz .LBB0_1018
	ds_bpermute_b32 v10, v225, v0
	v_max_f32_e32 v0, v0, v0
	s_waitcnt lgkmcnt(0)
	v_max_f32_e32 v10, v10, v10
	v_max_f32_e32 v0, v0, v10
	ds_bpermute_b32 v10, v224, v0
	s_waitcnt lgkmcnt(0)
	v_max3_f32 v133, v227, v0, v10
	v_sub_f32_e32 v0, v227, v133
	v_exp_f32_e32 v0, v0
	s_nop 0
	v_mul_f32_e32 v34, v229, v0
	v_pk_mul_f32 v[38:39], v[38:39], v[0:1] op_sel_hi:[1,0]
	v_pk_mul_f32 v[36:37], v[36:37], v[0:1] op_sel_hi:[1,0]
	v_pk_mul_f32 v[42:43], v[42:43], v[0:1] op_sel_hi:[1,0]
	v_pk_mul_f32 v[40:41], v[40:41], v[0:1] op_sel_hi:[1,0]
	v_pk_mul_f32 v[46:47], v[46:47], v[0:1] op_sel_hi:[1,0]
	v_pk_mul_f32 v[44:45], v[44:45], v[0:1] op_sel_hi:[1,0]
	v_pk_mul_f32 v[50:51], v[50:51], v[0:1] op_sel_hi:[1,0]
	v_pk_mul_f32 v[48:49], v[48:49], v[0:1] op_sel_hi:[1,0]
	v_pk_mul_f32 v[54:55], v[54:55], v[0:1] op_sel_hi:[1,0]
	v_pk_mul_f32 v[52:53], v[52:53], v[0:1] op_sel_hi:[1,0]
	v_pk_mul_f32 v[58:59], v[58:59], v[0:1] op_sel_hi:[1,0]
	v_pk_mul_f32 v[56:57], v[56:57], v[0:1] op_sel_hi:[1,0]
	v_pk_mul_f32 v[62:63], v[62:63], v[0:1] op_sel_hi:[1,0]
	v_pk_mul_f32 v[60:61], v[60:61], v[0:1] op_sel_hi:[1,0]
	v_pk_mul_f32 v[66:67], v[66:67], v[0:1] op_sel_hi:[1,0]
	v_pk_mul_f32 v[64:65], v[64:65], v[0:1] op_sel_hi:[1,0]

; template <bool SLC, bool NOMASK> ...
;     ...
;     load_frag8(nxt, KF, VF, SLC ? (dnext & 0xfffff) : dnext, lane);
;     f32x4 sa[2] = {(f32x4){0.f, 0.f, 0.f, 0.f}, (f32x4){0.f, 0.f, 0.f, 0.f}};
; #pragma unroll
;     for (int T = 0; T < 2; ++T)
; #pragma unroll
;         for (int s2 = 0; s2 < 4; ++s2) sa[T] = __builtin_amdgcn_mfma_f32_16x16x32_fp8_fp8(cur.k[T][s2], qf[s2], sa[T], 0, 0, 0);
;     float sc[8]; bool vd[8]; float mx = -1e30f;
;     const bool act = lo == 0 || !SLC;
;     if (NOMASK) {
; #pragma unroll
;         for (int j = 0; j < 8; ++j) { sc[j] = sa[j >> 2][j & 3]; vd[j] = act; }
;         mx = fmaxf(fmaxf(fmaxf(sc[0], sc[1]), fmaxf(sc[2], sc[3])), fmaxf(fmaxf(sc[4], sc[5]), fmaxf(sc[6], sc[7])));
;         mx = act ? mx : -1e30f;
;     } else {
; #pragma unroll
;         for (int T = 0; T < 2; ++T)
; #pragma unroll
;             for (int r = 0; r < 4; ++r) { const int p = pos0 + 16 * T + 4 * kq + r; const bool v = (p >= lo) & (p <= hi); const float x = sa[T][r];
;                 sc[4 * T + r] = x; vd[4 * T + r] = v; mx = v ? fmaxf(mx, x) : mx; }
;     }
;     if (__builtin_amdgcn_ballot_w64(mx > st.m + 4.f) != 0ull) {
;         mx = fmaxf(mx, __shfl_xor(mx, 16)); mx = fmaxf(mx, __shfl_xor(mx, 32));
;         const float mn = fmaxf(st.m, mx), alpha = __builtin_amdgcn_exp2f(st.m - mn); st.m = mn; st.l *= alpha;
; #pragma unroll
;         for (int j = 0; j < 8; ++j) st.o[j] = st.o[j] * alpha;
;     }
.LBB0_1019:
	s_and_b64 vcc, exec, s[10:11]
	s_cbranch_vccz .LBB0_1023
	v_lshl_add_u64 v[246:247], v[204:205], 0, v[120:121]
	global_load_dwordx4 v[154:157], v[246:247], off
	global_load_dwordx4 v[158:161], v[246:247], off offset:1024
	global_load_dwordx4 v[162:165], v[246:247], off offset:2048
	global_load_dwordx4 v[166:169], v[246:247], off offset:3072
	v_lshl_add_u64 v[244:245], v[202:203], 0, v[120:121]
	global_load_dwordx4 v[106:109], v[244:245], off
	global_load_dwordx4 v[110:113], v[244:245], off offset:1024
	global_load_dwordx4 v[114:117], v[244:245], off offset:2048
	global_load_dwordx4 v[134:137], v[244:245], off offset:3072
	s_waitcnt vmcnt(20)
	v_mfma_f32_16x16x128_f8f6f4 v[2:5], v[186:193], v[78:85], 0
	v_or_b32_e32 v0, s57, v210
	v_cmp_ge_i32_e32 vcc, v0, v35
	v_cmp_le_i32_e64 s[10:11], v0, v132
	v_mfma_f32_16x16x128_f8f6f4 v[6:9], v[194:201], v[78:85], 0
	s_and_b64 s[16:17], vcc, s[10:11]
	v_or_b32_e32 v11, 1, v0
	v_cmp_ge_i32_e32 vcc, v11, v35
	v_cmp_lt_i32_e64 s[10:11], v0, v132
	s_and_b64 s[12:13], s[10:11], vcc
	s_nop 5
	v_max_f32_e32 v10, v2, v2
	v_max_f32_e32 v10, 0xf149f2ca, v10
	v_cndmask_b32_e64 v10, v220, v10, s[16:17]
	v_max_f32_e32 v11, v3, v3
	v_max_f32_e32 v11, v10, v11
	v_cndmask_b32_e64 v10, v10, v11, s[12:13]
	v_or_b32_e32 v11, 2, v0
	v_cmp_ge_i32_e32 vcc, v11, v35
	v_cmp_le_i32_e64 s[10:11], v11, v132
	v_max_f32_e32 v11, v4, v4
	v_max_f32_e32 v11, v10, v11
	s_and_b64 s[14:15], vcc, s[10:11]
	v_cndmask_b32_e64 v10, v10, v11, s[14:15]
	v_or_b32_e32 v11, 3, v0
	v_cmp_ge_i32_e32 vcc, v11, v35
	v_cmp_le_i32_e64 s[10:11], v11, v132
	v_max_f32_e32 v11, v5, v5
	v_max_f32_e32 v11, v10, v11
	s_and_b64 s[10:11], vcc, s[10:11]
	v_cndmask_b32_e64 v10, v10, v11, s[10:11]
	v_or_b32_e32 v11, 16, v0
	v_cmp_ge_i32_e32 vcc, v11, v35
	v_cmp_le_i32_e64 s[18:19], v11, v132
	v_max_f32_e32 v11, v6, v6
	v_max_f32_e32 v11, v10, v11
	s_and_b64 s[24:25], vcc, s[18:19]
	v_cndmask_b32_e64 v10, v10, v11, s[24:25]
	v_or_b32_e32 v11, 17, v0
	v_cmp_ge_i32_e32 vcc, v11, v35
	v_cmp_le_i32_e64 s[18:19], v11, v132
	v_max_f32_e32 v11, v10, v10
	v_max_f32_e32 v12, v7, v7
	v_max_f32_e32 v11, v11, v12
	s_and_b64 s[20:21], vcc, s[18:19]
	v_cndmask_b32_e64 v10, v10, v11, s[20:21]
	v_or_b32_e32 v11, 18, v0
	v_cmp_ge_i32_e32 vcc, v11, v35
	v_cmp_le_i32_e64 s[18:19], v11, v132
	v_max_f32_e32 v11, v10, v10
	v_max_f32_e32 v12, v8, v8
	v_max_f32_e32 v11, v11, v12
	s_and_b64 s[22:23], vcc, s[18:19]
	v_cndmask_b32_e64 v10, v10, v11, s[22:23]
	v_or_b32_e32 v0, 19, v0
	v_cmp_ge_i32_e32 vcc, v0, v35
	v_cmp_le_i32_e64 s[18:19], v0, v132
	v_max_f32_e32 v0, v10, v10
	v_max_f32_e32 v11, v9, v9
	v_max_f32_e32 v0, v0, v11
	s_and_b64 s[18:19], vcc, s[18:19]
	v_cndmask_b32_e64 v0, v10, v0, s[18:19]
	v_cmp_gt_f32_e32 vcc, v0, v228
	s_cbranch_vccz .LBB0_1022
	ds_bpermute_b32 v10, v225, v0
	v_max_f32_e32 v0, v0, v0
	s_waitcnt lgkmcnt(0)
	v_max_f32_e32 v10, v10, v10
	v_max_f32_e32 v0, v0, v10
	ds_bpermute_b32 v10, v224, v0
	s_waitcnt lgkmcnt(0)
	v_max3_f32 v10, v227, v0, v10
	v_sub_f32_e32 v0, v227, v10
	v_exp_f32_e32 v0, v0
	v_mov_b32_e32 v227, v10
	v_mul_f32_e32 v229, v229, v0
	v_pk_mul_f32 v[38:39], v[38:39], v[0:1] op_sel_hi:[1,0]
	v_pk_mul_f32 v[36:37], v[36:37], v[0:1] op_sel_hi:[1,0]
	v_pk_mul_f32 v[42:43], v[42:43], v[0:1] op_sel_hi:[1,0]
	v_pk_mul_f32 v[40:41], v[40:41], v[0:1] op_sel_hi:[1,0]
	v_pk_mul_f32 v[46:47], v[46:47], v[0:1] op_sel_hi:[1,0]
	v_pk_mul_f32 v[44:45], v[44:45], v[0:1] op_sel_hi:[1,0]
	v_pk_mul_f32 v[50:51], v[50:51], v[0:1] op_sel_hi:[1,0]
	v_pk_mul_f32 v[48:49], v[48:49], v[0:1] op_sel_hi:[1,0]
	v_pk_mul_f32 v[54:55], v[54:55], v[0:1] op_sel_hi:[1,0]
	v_pk_mul_f32 v[52:53], v[52:53], v[0:1] op_sel_hi:[1,0]
	v_pk_mul_f32 v[58:59], v[58:59], v[0:1] op_sel_hi:[1,0]
	v_pk_mul_f32 v[56:57], v[56:57], v[0:1] op_sel_hi:[1,0]
	v_pk_mul_f32 v[62:63], v[62:63], v[0:1] op_sel_hi:[1,0]
	v_pk_mul_f32 v[60:61], v[60:61], v[0:1] op_sel_hi:[1,0]
	v_pk_mul_f32 v[66:67], v[66:67], v[0:1] op_sel_hi:[1,0]
	v_pk_mul_f32 v[64:65], v[64:65], v[0:1] op_sel_hi:[1,0]
